# s5a item also rewritten with f32 MFMA + DPP scan; s5b uses token-pair combine to halve the scan work
# speedup vs baseline: 1.0873x; 1.0284x over previous
.LBB0_524:
	s_and_b64 vcc, exec, s[0:1]
	s_cbranch_vccz .LBB0_408
	s_lshr_b32 s0, s23, 1
	s_and_b32 s1, s23, 1
	v_lshrrev_b32_e32 v0, 6, v135
	v_readlane_b32 s32, v249, 47
	v_readlane_b32 s10, v251, 1
	v_readlane_b32 s11, v251, 2
	v_readfirstlane_b32 s4, v0
	s_nop 3
	s_sub_u32 s10, s10, 0x168
	s_subb_u32 s11, s11, 0
	s_load_dwordx4 s[16:19], s[10:11], 0xd8
	s_load_dwordx2 s[20:21], s[10:11], 0xe8
	s_lshl_b32 s6, s1, 3
	s_add_i32 s6, s6, s4
	v_and_b32_e32 v2, 63, v135
	v_lshrrev_b32_e32 v3, 4, v2
	v_and_b32_e32 v4, 15, v2
	v_lshlrev_b32_e32 v5, 11, v4
	v_lshl_add_u32 v5, v3, 4, v5
	v_lshlrev_b32_e32 v6, 4, v4
	v_lshl_add_u32 v6, v3, 11, v6
	v_lshlrev_b32_e32 v7, 3, v2
	v_lshlrev_b32_e32 v11, 2, v4
	v_lshl_add_u32 v11, v3, 13, v11
	v_add_u32_e32 v12, 0x1000, v11
	v_lshlrev_b32_e32 v13, 1, v4
	v_lshl_add_u32 v13, v3, 12, v13
	v_lshlrev_b32_e32 v14, 8, v4
	v_lshl_add_u32 v14, v3, 4, v14
	v_lshlrev_b32_e32 v15, 5, v3
	v_lshlrev_b32_e32 v16, 2, v4
	v_lshlrev_b32_e32 v10, 4, v3
	s_mul_i32 s54, s4, 0xa00
	s_add_i32 s54, s54, 0x18400
	v_lshl_add_u32 v8, v2, 2, s54
	v_lshl_add_u32 v9, v3, 4, s54
	s_mov_b32 s52, 0x00010001
	s_mov_b32 s53, 0x00010001
	s_lshl_b32 s55, s0, 15
	s_lshl_b32 s56, s6, 6
	s_add_u32 s55, s55, s56
	s_add_u32 s8, s94, 0x8a40000
	s_addc_u32 s9, s95, 0
	s_add_u32 s8, s8, s55
	s_addc_u32 s9, s9, 0
	global_load_dwordx4 v[228:231], v5, s[8:9] offset:0
	global_load_dwordx4 v[232:235], v5, s[8:9] offset:1024
	s_waitcnt lgkmcnt(0)
	s_mov_b32 s10, 0x80008000
	s_mov_b32 s11, 0x80008000
	s_lshl_b32 s55, s0, 14
	s_lshl_b32 s56, s6, 5
	s_add_u32 s55, s55, s56
	s_add_u32 s44, s94, 0x11640000
	s_addc_u32 s45, s95, 0
	s_add_u32 s44, s44, s55
	s_addc_u32 s45, s45, 0
	s_lshl_b32 s55, s32, 10
	s_lshl_b32 s56, s6, 6
	s_add_u32 s55, s55, s56
	s_add_u32 s20, s20, s55
	s_addc_u32 s21, s21, 0
	s_add_i32 s55, s6, 0
	s_lshl_b32 s56, s55, 13
	s_add_u32 s12, s94, 0x12d96000
	s_addc_u32 s13, s95, 0
	s_add_u32 s12, s12, s56
	s_addc_u32 s13, s13, 0
	s_lshl_b32 s56, s55, 9
	s_add_u32 s38, s94, 0x12d92000
	s_addc_u32 s39, s95, 0
	s_add_u32 s38, s38, s56
	s_addc_u32 s39, s39, 0
	s_lshl_b32 s56, s0, 5
	s_lshl_b32 s55, s6, 1
	s_add_i32 s56, s56, s55
	s_add_i32 s56, s56, 0
	s_lshl_b32 s56, s56, 9
	s_add_u32 s36, s94, 0x133d6000
	s_addc_u32 s37, s95, 0
	s_add_u32 s36, s36, s56
	s_addc_u32 s37, s37, 0
	s_lshl_b32 s56, s32, 1
	s_add_i32 s56, s56, 0
	s_lshl_b32 s56, s56, 4
	s_add_i32 s56, s56, s6
	s_lshl_b32 s56, s56, 12
	s_add_u32 s14, s16, s56
	s_addc_u32 s15, s17, 0
	s_add_u32 s24, s18, s56
	s_addc_u32 s25, s19, 0
	global_load_dwordx2 v[2:3], v7, s[38:39]
	global_load_dwordx4 v[20:23], v6, s[12:13] offset:0
	global_load_dwordx4 v[24:27], v6, s[12:13] offset:1024
	global_load_dwordx4 v[28:31], v6, s[12:13] offset:256
	global_load_dwordx4 v[32:35], v6, s[12:13] offset:1280
	global_load_dwordx4 v[36:39], v6, s[12:13] offset:512
	global_load_dwordx4 v[40:43], v6, s[12:13] offset:1536
	global_load_dwordx4 v[44:47], v6, s[12:13] offset:768
	global_load_dwordx4 v[48:51], v6, s[12:13] offset:1792
	global_load_dwordx4 v[52:55], v15, s[36:37] offset:0
	global_load_dwordx4 v[56:59], v15, s[36:37] offset:16
	global_load_dwordx4 v[60:63], v15, s[36:37] offset:128
	global_load_dwordx4 v[64:67], v15, s[36:37] offset:144
	global_load_dwordx4 v[68:71], v15, s[36:37] offset:256
	global_load_dwordx4 v[72:75], v15, s[36:37] offset:272
	global_load_dwordx4 v[76:79], v15, s[36:37] offset:384
	global_load_dwordx4 v[80:83], v15, s[36:37] offset:400
	s_waitcnt vmcnt(16)
	ds_write_b32 v8, v2 offset:0
	ds_write_b32 v8, v3 offset:256
	v_mul_f32_e32 v180, v3, v3
	v_mul_f32_e32 v181, v2, v3
	v_fma_f32 v2, v2, v2, -v180
	v_add_f32_e32 v3, v181, v181
	ds_write_b32 v8, v2 offset:512
	ds_write_b32 v8, v3 offset:768
	v_mul_f32_e32 v180, v3, v3
	v_mul_f32_e32 v181, v2, v3
	v_fma_f32 v2, v2, v2, -v180
	v_add_f32_e32 v3, v181, v181
	ds_write_b32 v8, v2 offset:1024
	ds_write_b32 v8, v3 offset:1280
	v_mul_f32_e32 v180, v3, v3
	v_mul_f32_e32 v181, v2, v3
	v_fma_f32 v2, v2, v2, -v180
	v_add_f32_e32 v3, v181, v181
	ds_write_b32 v8, v2 offset:1536
	ds_write_b32 v8, v3 offset:1792
	v_mul_f32_e32 v180, v3, v3
	v_mul_f32_e32 v181, v2, v3
	v_fma_f32 v2, v2, v2, -v180
	v_add_f32_e32 v3, v181, v181
	ds_write_b32 v8, v2 offset:2048
	ds_write_b32 v8, v3 offset:2304
	s_waitcnt lgkmcnt(0)
	s_waitcnt vmcnt(15)
	v_mfma_f32_16x16x4_f32 v[84:87], v20, v228, 0
	v_mfma_f32_16x16x4_f32 v[88:91], v21, v228, 0
	v_mfma_f32_16x16x4_f32 v[116:119], v20, v232, 0
	v_mfma_f32_16x16x4_f32 v[120:123], v21, v232, 0
	s_waitcnt vmcnt(13)
	v_mfma_f32_16x16x4_f32 v[92:95], v28, v228, 0
	v_mfma_f32_16x16x4_f32 v[96:99], v29, v228, 0
	v_mfma_f32_16x16x4_f32 v[124:127], v28, v232, 0
	v_mfma_f32_16x16x4_f32 v[128:131], v29, v232, 0
	s_waitcnt vmcnt(11)
	v_mfma_f32_16x16x4_f32 v[100:103], v36, v228, 0
	v_mfma_f32_16x16x4_f32 v[104:107], v37, v228, 0
	v_mfma_f32_16x16x4_f32 v[140:143], v36, v232, 0
	v_mfma_f32_16x16x4_f32 v[144:147], v37, v232, 0
	s_waitcnt vmcnt(9)
	v_mfma_f32_16x16x4_f32 v[108:111], v44, v228, 0
	v_mfma_f32_16x16x4_f32 v[112:115], v45, v228, 0
	v_mfma_f32_16x16x4_f32 v[148:151], v44, v232, 0
	v_mfma_f32_16x16x4_f32 v[152:155], v45, v232, 0
	v_mfma_f32_16x16x4_f32 v[84:87], v22, v229, v[84:87]
	v_mfma_f32_16x16x4_f32 v[88:91], v23, v229, v[88:91]
	v_mfma_f32_16x16x4_f32 v[116:119], v22, v233, v[116:119]
	v_mfma_f32_16x16x4_f32 v[120:123], v23, v233, v[120:123]
	v_mfma_f32_16x16x4_f32 v[92:95], v30, v229, v[92:95]
	v_mfma_f32_16x16x4_f32 v[96:99], v31, v229, v[96:99]
	v_mfma_f32_16x16x4_f32 v[124:127], v30, v233, v[124:127]
	v_mfma_f32_16x16x4_f32 v[128:131], v31, v233, v[128:131]
	v_mfma_f32_16x16x4_f32 v[100:103], v38, v229, v[100:103]
	v_mfma_f32_16x16x4_f32 v[104:107], v39, v229, v[104:107]
	v_mfma_f32_16x16x4_f32 v[140:143], v38, v233, v[140:143]
	v_mfma_f32_16x16x4_f32 v[144:147], v39, v233, v[144:147]
	v_mfma_f32_16x16x4_f32 v[108:111], v46, v229, v[108:111]
	v_mfma_f32_16x16x4_f32 v[112:115], v47, v229, v[112:115]
	v_mfma_f32_16x16x4_f32 v[148:151], v46, v233, v[148:151]
	v_mfma_f32_16x16x4_f32 v[152:155], v47, v233, v[152:155]
	v_mfma_f32_16x16x4_f32 v[84:87], v24, v230, v[84:87]
	v_mfma_f32_16x16x4_f32 v[88:91], v25, v230, v[88:91]
	v_mfma_f32_16x16x4_f32 v[116:119], v24, v234, v[116:119]
	v_mfma_f32_16x16x4_f32 v[120:123], v25, v234, v[120:123]
	v_mfma_f32_16x16x4_f32 v[92:95], v32, v230, v[92:95]
	v_mfma_f32_16x16x4_f32 v[96:99], v33, v230, v[96:99]
	v_mfma_f32_16x16x4_f32 v[124:127], v32, v234, v[124:127]
	v_mfma_f32_16x16x4_f32 v[128:131], v33, v234, v[128:131]
	v_mfma_f32_16x16x4_f32 v[100:103], v40, v230, v[100:103]
	v_mfma_f32_16x16x4_f32 v[104:107], v41, v230, v[104:107]
	v_mfma_f32_16x16x4_f32 v[140:143], v40, v234, v[140:143]
	v_mfma_f32_16x16x4_f32 v[144:147], v41, v234, v[144:147]
	s_waitcnt vmcnt(8)
	v_mfma_f32_16x16x4_f32 v[108:111], v48, v230, v[108:111]
	v_mfma_f32_16x16x4_f32 v[112:115], v49, v230, v[112:115]
	v_mfma_f32_16x16x4_f32 v[148:151], v48, v234, v[148:151]
	v_mfma_f32_16x16x4_f32 v[152:155], v49, v234, v[152:155]
	v_mfma_f32_16x16x4_f32 v[84:87], v26, v231, v[84:87]
	v_mfma_f32_16x16x4_f32 v[88:91], v27, v231, v[88:91]
	v_mfma_f32_16x16x4_f32 v[116:119], v26, v235, v[116:119]
	v_mfma_f32_16x16x4_f32 v[120:123], v27, v235, v[120:123]
	v_mfma_f32_16x16x4_f32 v[92:95], v34, v231, v[92:95]
	v_mfma_f32_16x16x4_f32 v[96:99], v35, v231, v[96:99]
	v_mfma_f32_16x16x4_f32 v[124:127], v34, v235, v[124:127]
	v_mfma_f32_16x16x4_f32 v[128:131], v35, v235, v[128:131]
	v_mfma_f32_16x16x4_f32 v[100:103], v42, v231, v[100:103]
	v_mfma_f32_16x16x4_f32 v[104:107], v43, v231, v[104:107]
	v_mfma_f32_16x16x4_f32 v[140:143], v42, v235, v[140:143]
	v_mfma_f32_16x16x4_f32 v[144:147], v43, v235, v[144:147]
	v_mfma_f32_16x16x4_f32 v[108:111], v50, v231, v[108:111]
	v_mfma_f32_16x16x4_f32 v[112:115], v51, v231, v[112:115]
	v_mfma_f32_16x16x4_f32 v[148:151], v50, v235, v[148:151]
	v_mfma_f32_16x16x4_f32 v[152:155], v51, v235, v[152:155]
	global_load_dwordx4 v[20:23], v14, s[14:15] offset:0
	global_load_dwordx4 v[24:27], v14, s[24:25] offset:0
	global_load_dwordx4 v[28:31], v14, s[14:15] offset:64
	global_load_dwordx4 v[32:35], v14, s[24:25] offset:64
	global_load_dwordx4 v[36:39], v14, s[14:15] offset:128
	global_load_dwordx4 v[40:43], v14, s[24:25] offset:128
	global_load_dwordx4 v[44:47], v14, s[14:15] offset:192
	global_load_dwordx4 v[48:51], v14, s[24:25] offset:192
	s_waitcnt vmcnt(8)
	s_nop 9
	ds_read_b128 v[156:159], v9 offset:0
	ds_read_b128 v[168:171], v9 offset:256
	ds_read_b128 v[172:175], v9 offset:64
	ds_read_b128 v[176:179], v9 offset:320
	s_waitcnt lgkmcnt(2)
	s_mov_b64 exec, s[52:53]
	v_fmac_f32_e32 v84, v156, v52
	v_fmac_f32_e32 v85, v157, v54
	v_fmac_f32_e32 v86, v158, v56
	v_fmac_f32_e32 v87, v159, v58
	v_fma_f32 v84, -v168, v53, v84
	v_fma_f32 v85, -v169, v55, v85
	v_fma_f32 v86, -v170, v57, v86
	v_fma_f32 v87, -v171, v59, v87
	v_fmac_f32_e32 v88, v156, v53
	v_fmac_f32_e32 v89, v157, v55
	v_fmac_f32_e32 v90, v158, v57
	v_fmac_f32_e32 v91, v159, v59
	v_fmac_f32_e32 v88, v168, v52
	v_fmac_f32_e32 v89, v169, v54
	v_fmac_f32_e32 v90, v170, v56
	v_fmac_f32_e32 v91, v171, v58
	s_mov_b64 exec, -1
	v_fmac_f32_e32 v116, v156, v84
	v_fmac_f32_e32 v117, v157, v85
	v_fmac_f32_e32 v118, v158, v86
	v_fmac_f32_e32 v119, v159, v87
	v_fma_f32 v116, -v168, v88, v116
	v_fma_f32 v117, -v169, v89, v117
	v_fma_f32 v118, -v170, v90, v118
	v_fma_f32 v119, -v171, v91, v119
	v_fmac_f32_e32 v120, v156, v88
	v_fmac_f32_e32 v121, v157, v89
	v_fmac_f32_e32 v122, v158, v90
	v_fmac_f32_e32 v123, v159, v91
	v_fmac_f32_e32 v120, v168, v84
	v_fmac_f32_e32 v121, v169, v85
	v_fmac_f32_e32 v122, v170, v86
	v_fmac_f32_e32 v123, v171, v87
	ds_read_b128 v[156:159], v9 offset:128
	ds_read_b128 v[168:171], v9 offset:384
	s_waitcnt lgkmcnt(2)
	s_mov_b64 exec, s[52:53]
	v_fmac_f32_e32 v92, v172, v60
	v_fmac_f32_e32 v93, v173, v62
	v_fmac_f32_e32 v94, v174, v64
	v_fmac_f32_e32 v95, v175, v66
	v_fma_f32 v92, -v176, v61, v92
	v_fma_f32 v93, -v177, v63, v93
	v_fma_f32 v94, -v178, v65, v94
	v_fma_f32 v95, -v179, v67, v95
	v_fmac_f32_e32 v96, v172, v61
	v_fmac_f32_e32 v97, v173, v63
	v_fmac_f32_e32 v98, v174, v65
	v_fmac_f32_e32 v99, v175, v67
	v_fmac_f32_e32 v96, v176, v60
	v_fmac_f32_e32 v97, v177, v62
	v_fmac_f32_e32 v98, v178, v64
	v_fmac_f32_e32 v99, v179, v66
	s_mov_b64 exec, -1
	v_fmac_f32_e32 v124, v172, v92
	v_fmac_f32_e32 v125, v173, v93
	v_fmac_f32_e32 v126, v174, v94
	v_fmac_f32_e32 v127, v175, v95
	v_fma_f32 v124, -v176, v96, v124
	v_fma_f32 v125, -v177, v97, v125
	v_fma_f32 v126, -v178, v98, v126
	v_fma_f32 v127, -v179, v99, v127
	v_fmac_f32_e32 v128, v172, v96
	v_fmac_f32_e32 v129, v173, v97
	v_fmac_f32_e32 v130, v174, v98
	v_fmac_f32_e32 v131, v175, v99
	v_fmac_f32_e32 v128, v176, v92
	v_fmac_f32_e32 v129, v177, v93
	v_fmac_f32_e32 v130, v178, v94
	v_fmac_f32_e32 v131, v179, v95
	ds_read_b128 v[172:175], v9 offset:192
	ds_read_b128 v[176:179], v9 offset:448
	s_waitcnt lgkmcnt(2)
	s_mov_b64 exec, s[52:53]
	v_fmac_f32_e32 v100, v156, v68
	v_fmac_f32_e32 v101, v157, v70
	v_fmac_f32_e32 v102, v158, v72
	v_fmac_f32_e32 v103, v159, v74
	v_fma_f32 v100, -v168, v69, v100
	v_fma_f32 v101, -v169, v71, v101
	v_fma_f32 v102, -v170, v73, v102
	v_fma_f32 v103, -v171, v75, v103
	v_fmac_f32_e32 v104, v156, v69
	v_fmac_f32_e32 v105, v157, v71
	v_fmac_f32_e32 v106, v158, v73
	v_fmac_f32_e32 v107, v159, v75
	v_fmac_f32_e32 v104, v168, v68
	v_fmac_f32_e32 v105, v169, v70
	v_fmac_f32_e32 v106, v170, v72
	v_fmac_f32_e32 v107, v171, v74
	s_mov_b64 exec, -1
	v_fmac_f32_e32 v140, v156, v100
	v_fmac_f32_e32 v141, v157, v101
	v_fmac_f32_e32 v142, v158, v102
	v_fmac_f32_e32 v143, v159, v103
	v_fma_f32 v140, -v168, v104, v140
	v_fma_f32 v141, -v169, v105, v141
	v_fma_f32 v142, -v170, v106, v142
	v_fma_f32 v143, -v171, v107, v143
	v_fmac_f32_e32 v144, v156, v104
	v_fmac_f32_e32 v145, v157, v105
	v_fmac_f32_e32 v146, v158, v106
	v_fmac_f32_e32 v147, v159, v107
	v_fmac_f32_e32 v144, v168, v100
	v_fmac_f32_e32 v145, v169, v101
	v_fmac_f32_e32 v146, v170, v102
	v_fmac_f32_e32 v147, v171, v103
	s_waitcnt lgkmcnt(0)
	s_mov_b64 exec, s[52:53]
	v_fmac_f32_e32 v108, v172, v76
	v_fmac_f32_e32 v109, v173, v78
	v_fmac_f32_e32 v110, v174, v80
	v_fmac_f32_e32 v111, v175, v82
	v_fma_f32 v108, -v176, v77, v108
	v_fma_f32 v109, -v177, v79, v109
	v_fma_f32 v110, -v178, v81, v110
	v_fma_f32 v111, -v179, v83, v111
	v_fmac_f32_e32 v112, v172, v77
	v_fmac_f32_e32 v113, v173, v79
	v_fmac_f32_e32 v114, v174, v81
	v_fmac_f32_e32 v115, v175, v83
	v_fmac_f32_e32 v112, v176, v76
	v_fmac_f32_e32 v113, v177, v78
	v_fmac_f32_e32 v114, v178, v80
	v_fmac_f32_e32 v115, v179, v82
	s_mov_b64 exec, -1
	v_fmac_f32_e32 v148, v172, v108
	v_fmac_f32_e32 v149, v173, v109
	v_fmac_f32_e32 v150, v174, v110
	v_fmac_f32_e32 v151, v175, v111
	v_fma_f32 v148, -v176, v112, v148
	v_fma_f32 v149, -v177, v113, v149
	v_fma_f32 v150, -v178, v114, v150
	v_fma_f32 v151, -v179, v115, v151
	v_fmac_f32_e32 v152, v172, v112
	v_fmac_f32_e32 v153, v173, v113
	v_fmac_f32_e32 v154, v174, v114
	v_fmac_f32_e32 v155, v175, v115
	v_fmac_f32_e32 v152, v176, v108
	v_fmac_f32_e32 v153, v177, v109
	v_fmac_f32_e32 v154, v178, v110
	v_fmac_f32_e32 v155, v179, v111
	ds_read_b128 v[156:159], v9 offset:512
	ds_read_b128 v[168:171], v9 offset:768
	ds_read_b128 v[172:175], v9 offset:576
	ds_read_b128 v[176:179], v9 offset:832
	s_waitcnt lgkmcnt(2)
	v_mov_b32_e32 v180, v116
	v_mov_b32_e32 v181, v117
	v_mov_b32_e32 v182, v118
	v_mov_b32_e32 v183, v119
	s_nop 1
	v_fmac_f32_dpp v116, v116, v156 row_shr:1 row_mask:0xf bank_mask:0xf bound_ctrl:0
	v_fmac_f32_dpp v117, v117, v157 row_shr:1 row_mask:0xf bank_mask:0xf bound_ctrl:0
	v_fmac_f32_dpp v118, v118, v158 row_shr:1 row_mask:0xf bank_mask:0xf bound_ctrl:0
	v_fmac_f32_dpp v119, v119, v159 row_shr:1 row_mask:0xf bank_mask:0xf bound_ctrl:0
	v_fmac_f32_dpp v116, v120, -v168 row_shr:1 row_mask:0xf bank_mask:0xf bound_ctrl:0
	v_fmac_f32_dpp v117, v121, -v169 row_shr:1 row_mask:0xf bank_mask:0xf bound_ctrl:0
	v_fmac_f32_dpp v118, v122, -v170 row_shr:1 row_mask:0xf bank_mask:0xf bound_ctrl:0
	v_fmac_f32_dpp v119, v123, -v171 row_shr:1 row_mask:0xf bank_mask:0xf bound_ctrl:0
	v_fmac_f32_dpp v120, v120, v156 row_shr:1 row_mask:0xf bank_mask:0xf bound_ctrl:0
	v_fmac_f32_dpp v121, v121, v157 row_shr:1 row_mask:0xf bank_mask:0xf bound_ctrl:0
	v_fmac_f32_dpp v122, v122, v158 row_shr:1 row_mask:0xf bank_mask:0xf bound_ctrl:0
	v_fmac_f32_dpp v123, v123, v159 row_shr:1 row_mask:0xf bank_mask:0xf bound_ctrl:0
	v_fmac_f32_dpp v120, v180, v168 row_shr:1 row_mask:0xf bank_mask:0xf bound_ctrl:0
	v_fmac_f32_dpp v121, v181, v169 row_shr:1 row_mask:0xf bank_mask:0xf bound_ctrl:0
	v_fmac_f32_dpp v122, v182, v170 row_shr:1 row_mask:0xf bank_mask:0xf bound_ctrl:0
	v_fmac_f32_dpp v123, v183, v171 row_shr:1 row_mask:0xf bank_mask:0xf bound_ctrl:0
	ds_read_b128 v[156:159], v9 offset:640
	ds_read_b128 v[168:171], v9 offset:896
	s_waitcnt lgkmcnt(2)
	v_mov_b32_e32 v180, v124
	v_mov_b32_e32 v181, v125
	v_mov_b32_e32 v182, v126
	v_mov_b32_e32 v183, v127
	v_fmac_f32_dpp v124, v124, v172 row_shr:1 row_mask:0xf bank_mask:0xf bound_ctrl:0
	v_fmac_f32_dpp v125, v125, v173 row_shr:1 row_mask:0xf bank_mask:0xf bound_ctrl:0
	v_fmac_f32_dpp v126, v126, v174 row_shr:1 row_mask:0xf bank_mask:0xf bound_ctrl:0
	v_fmac_f32_dpp v127, v127, v175 row_shr:1 row_mask:0xf bank_mask:0xf bound_ctrl:0
	v_fmac_f32_dpp v124, v128, -v176 row_shr:1 row_mask:0xf bank_mask:0xf bound_ctrl:0
	v_fmac_f32_dpp v125, v129, -v177 row_shr:1 row_mask:0xf bank_mask:0xf bound_ctrl:0
	v_fmac_f32_dpp v126, v130, -v178 row_shr:1 row_mask:0xf bank_mask:0xf bound_ctrl:0
	v_fmac_f32_dpp v127, v131, -v179 row_shr:1 row_mask:0xf bank_mask:0xf bound_ctrl:0
	v_fmac_f32_dpp v128, v128, v172 row_shr:1 row_mask:0xf bank_mask:0xf bound_ctrl:0
	v_fmac_f32_dpp v129, v129, v173 row_shr:1 row_mask:0xf bank_mask:0xf bound_ctrl:0
	v_fmac_f32_dpp v130, v130, v174 row_shr:1 row_mask:0xf bank_mask:0xf bound_ctrl:0
	v_fmac_f32_dpp v131, v131, v175 row_shr:1 row_mask:0xf bank_mask:0xf bound_ctrl:0
	v_fmac_f32_dpp v128, v180, v176 row_shr:1 row_mask:0xf bank_mask:0xf bound_ctrl:0
	v_fmac_f32_dpp v129, v181, v177 row_shr:1 row_mask:0xf bank_mask:0xf bound_ctrl:0
	v_fmac_f32_dpp v130, v182, v178 row_shr:1 row_mask:0xf bank_mask:0xf bound_ctrl:0
	v_fmac_f32_dpp v131, v183, v179 row_shr:1 row_mask:0xf bank_mask:0xf bound_ctrl:0
	ds_read_b128 v[172:175], v9 offset:704
	ds_read_b128 v[176:179], v9 offset:960
	s_waitcnt lgkmcnt(2)
	v_mov_b32_e32 v180, v140
	v_mov_b32_e32 v181, v141
	v_mov_b32_e32 v182, v142
	v_mov_b32_e32 v183, v143
	v_fmac_f32_dpp v140, v140, v156 row_shr:1 row_mask:0xf bank_mask:0xf bound_ctrl:0
	v_fmac_f32_dpp v141, v141, v157 row_shr:1 row_mask:0xf bank_mask:0xf bound_ctrl:0
	v_fmac_f32_dpp v142, v142, v158 row_shr:1 row_mask:0xf bank_mask:0xf bound_ctrl:0
	v_fmac_f32_dpp v143, v143, v159 row_shr:1 row_mask:0xf bank_mask:0xf bound_ctrl:0
	v_fmac_f32_dpp v140, v144, -v168 row_shr:1 row_mask:0xf bank_mask:0xf bound_ctrl:0
	v_fmac_f32_dpp v141, v145, -v169 row_shr:1 row_mask:0xf bank_mask:0xf bound_ctrl:0
	v_fmac_f32_dpp v142, v146, -v170 row_shr:1 row_mask:0xf bank_mask:0xf bound_ctrl:0
	v_fmac_f32_dpp v143, v147, -v171 row_shr:1 row_mask:0xf bank_mask:0xf bound_ctrl:0
	v_fmac_f32_dpp v144, v144, v156 row_shr:1 row_mask:0xf bank_mask:0xf bound_ctrl:0
	v_fmac_f32_dpp v145, v145, v157 row_shr:1 row_mask:0xf bank_mask:0xf bound_ctrl:0
	v_fmac_f32_dpp v146, v146, v158 row_shr:1 row_mask:0xf bank_mask:0xf bound_ctrl:0
	v_fmac_f32_dpp v147, v147, v159 row_shr:1 row_mask:0xf bank_mask:0xf bound_ctrl:0
	v_fmac_f32_dpp v144, v180, v168 row_shr:1 row_mask:0xf bank_mask:0xf bound_ctrl:0
	v_fmac_f32_dpp v145, v181, v169 row_shr:1 row_mask:0xf bank_mask:0xf bound_ctrl:0
	v_fmac_f32_dpp v146, v182, v170 row_shr:1 row_mask:0xf bank_mask:0xf bound_ctrl:0
	v_fmac_f32_dpp v147, v183, v171 row_shr:1 row_mask:0xf bank_mask:0xf bound_ctrl:0
	ds_read_b128 v[156:159], v9 offset:1024
	ds_read_b128 v[168:171], v9 offset:1280
	s_waitcnt lgkmcnt(2)
	v_mov_b32_e32 v180, v148
	v_mov_b32_e32 v181, v149
	v_mov_b32_e32 v182, v150
	v_mov_b32_e32 v183, v151
	v_fmac_f32_dpp v148, v148, v172 row_shr:1 row_mask:0xf bank_mask:0xf bound_ctrl:0
	v_fmac_f32_dpp v149, v149, v173 row_shr:1 row_mask:0xf bank_mask:0xf bound_ctrl:0
	v_fmac_f32_dpp v150, v150, v174 row_shr:1 row_mask:0xf bank_mask:0xf bound_ctrl:0
	v_fmac_f32_dpp v151, v151, v175 row_shr:1 row_mask:0xf bank_mask:0xf bound_ctrl:0
	v_fmac_f32_dpp v148, v152, -v176 row_shr:1 row_mask:0xf bank_mask:0xf bound_ctrl:0
	v_fmac_f32_dpp v149, v153, -v177 row_shr:1 row_mask:0xf bank_mask:0xf bound_ctrl:0
	v_fmac_f32_dpp v150, v154, -v178 row_shr:1 row_mask:0xf bank_mask:0xf bound_ctrl:0
	v_fmac_f32_dpp v151, v155, -v179 row_shr:1 row_mask:0xf bank_mask:0xf bound_ctrl:0
	v_fmac_f32_dpp v152, v152, v172 row_shr:1 row_mask:0xf bank_mask:0xf bound_ctrl:0
	v_fmac_f32_dpp v153, v153, v173 row_shr:1 row_mask:0xf bank_mask:0xf bound_ctrl:0
	v_fmac_f32_dpp v154, v154, v174 row_shr:1 row_mask:0xf bank_mask:0xf bound_ctrl:0
	v_fmac_f32_dpp v155, v155, v175 row_shr:1 row_mask:0xf bank_mask:0xf bound_ctrl:0
	v_fmac_f32_dpp v152, v180, v176 row_shr:1 row_mask:0xf bank_mask:0xf bound_ctrl:0
	v_fmac_f32_dpp v153, v181, v177 row_shr:1 row_mask:0xf bank_mask:0xf bound_ctrl:0
	v_fmac_f32_dpp v154, v182, v178 row_shr:1 row_mask:0xf bank_mask:0xf bound_ctrl:0
	v_fmac_f32_dpp v155, v183, v179 row_shr:1 row_mask:0xf bank_mask:0xf bound_ctrl:0
	ds_read_b128 v[172:175], v9 offset:1088
	ds_read_b128 v[176:179], v9 offset:1344
	s_waitcnt lgkmcnt(2)
	v_mov_b32_e32 v180, v116
	v_mov_b32_e32 v181, v117
	v_mov_b32_e32 v182, v118
	v_mov_b32_e32 v183, v119
	v_fmac_f32_dpp v116, v116, v156 row_shr:2 row_mask:0xf bank_mask:0xf bound_ctrl:0
	v_fmac_f32_dpp v117, v117, v157 row_shr:2 row_mask:0xf bank_mask:0xf bound_ctrl:0
	v_fmac_f32_dpp v118, v118, v158 row_shr:2 row_mask:0xf bank_mask:0xf bound_ctrl:0
	v_fmac_f32_dpp v119, v119, v159 row_shr:2 row_mask:0xf bank_mask:0xf bound_ctrl:0
	v_fmac_f32_dpp v116, v120, -v168 row_shr:2 row_mask:0xf bank_mask:0xf bound_ctrl:0
	v_fmac_f32_dpp v117, v121, -v169 row_shr:2 row_mask:0xf bank_mask:0xf bound_ctrl:0
	v_fmac_f32_dpp v118, v122, -v170 row_shr:2 row_mask:0xf bank_mask:0xf bound_ctrl:0
	v_fmac_f32_dpp v119, v123, -v171 row_shr:2 row_mask:0xf bank_mask:0xf bound_ctrl:0
	v_fmac_f32_dpp v120, v120, v156 row_shr:2 row_mask:0xf bank_mask:0xf bound_ctrl:0
	v_fmac_f32_dpp v121, v121, v157 row_shr:2 row_mask:0xf bank_mask:0xf bound_ctrl:0
	v_fmac_f32_dpp v122, v122, v158 row_shr:2 row_mask:0xf bank_mask:0xf bound_ctrl:0
	v_fmac_f32_dpp v123, v123, v159 row_shr:2 row_mask:0xf bank_mask:0xf bound_ctrl:0
	v_fmac_f32_dpp v120, v180, v168 row_shr:2 row_mask:0xf bank_mask:0xf bound_ctrl:0
	v_fmac_f32_dpp v121, v181, v169 row_shr:2 row_mask:0xf bank_mask:0xf bound_ctrl:0
	v_fmac_f32_dpp v122, v182, v170 row_shr:2 row_mask:0xf bank_mask:0xf bound_ctrl:0
	v_fmac_f32_dpp v123, v183, v171 row_shr:2 row_mask:0xf bank_mask:0xf bound_ctrl:0
	ds_read_b128 v[156:159], v9 offset:1152
	ds_read_b128 v[168:171], v9 offset:1408
	s_waitcnt lgkmcnt(2)
	v_mov_b32_e32 v180, v124
	v_mov_b32_e32 v181, v125
	v_mov_b32_e32 v182, v126
	v_mov_b32_e32 v183, v127
	v_fmac_f32_dpp v124, v124, v172 row_shr:2 row_mask:0xf bank_mask:0xf bound_ctrl:0
	v_fmac_f32_dpp v125, v125, v173 row_shr:2 row_mask:0xf bank_mask:0xf bound_ctrl:0
	v_fmac_f32_dpp v126, v126, v174 row_shr:2 row_mask:0xf bank_mask:0xf bound_ctrl:0
	v_fmac_f32_dpp v127, v127, v175 row_shr:2 row_mask:0xf bank_mask:0xf bound_ctrl:0
	v_fmac_f32_dpp v124, v128, -v176 row_shr:2 row_mask:0xf bank_mask:0xf bound_ctrl:0
	v_fmac_f32_dpp v125, v129, -v177 row_shr:2 row_mask:0xf bank_mask:0xf bound_ctrl:0
	v_fmac_f32_dpp v126, v130, -v178 row_shr:2 row_mask:0xf bank_mask:0xf bound_ctrl:0
	v_fmac_f32_dpp v127, v131, -v179 row_shr:2 row_mask:0xf bank_mask:0xf bound_ctrl:0
	v_fmac_f32_dpp v128, v128, v172 row_shr:2 row_mask:0xf bank_mask:0xf bound_ctrl:0
	v_fmac_f32_dpp v129, v129, v173 row_shr:2 row_mask:0xf bank_mask:0xf bound_ctrl:0
	v_fmac_f32_dpp v130, v130, v174 row_shr:2 row_mask:0xf bank_mask:0xf bound_ctrl:0
	v_fmac_f32_dpp v131, v131, v175 row_shr:2 row_mask:0xf bank_mask:0xf bound_ctrl:0
	v_fmac_f32_dpp v128, v180, v176 row_shr:2 row_mask:0xf bank_mask:0xf bound_ctrl:0
	v_fmac_f32_dpp v129, v181, v177 row_shr:2 row_mask:0xf bank_mask:0xf bound_ctrl:0
	v_fmac_f32_dpp v130, v182, v178 row_shr:2 row_mask:0xf bank_mask:0xf bound_ctrl:0
	v_fmac_f32_dpp v131, v183, v179 row_shr:2 row_mask:0xf bank_mask:0xf bound_ctrl:0
	ds_read_b128 v[172:175], v9 offset:1216
	ds_read_b128 v[176:179], v9 offset:1472
	s_waitcnt lgkmcnt(2)
	v_mov_b32_e32 v180, v140
	v_mov_b32_e32 v181, v141
	v_mov_b32_e32 v182, v142
	v_mov_b32_e32 v183, v143
	v_fmac_f32_dpp v140, v140, v156 row_shr:2 row_mask:0xf bank_mask:0xf bound_ctrl:0
	v_fmac_f32_dpp v141, v141, v157 row_shr:2 row_mask:0xf bank_mask:0xf bound_ctrl:0
	v_fmac_f32_dpp v142, v142, v158 row_shr:2 row_mask:0xf bank_mask:0xf bound_ctrl:0
	v_fmac_f32_dpp v143, v143, v159 row_shr:2 row_mask:0xf bank_mask:0xf bound_ctrl:0
	v_fmac_f32_dpp v140, v144, -v168 row_shr:2 row_mask:0xf bank_mask:0xf bound_ctrl:0
	v_fmac_f32_dpp v141, v145, -v169 row_shr:2 row_mask:0xf bank_mask:0xf bound_ctrl:0
	v_fmac_f32_dpp v142, v146, -v170 row_shr:2 row_mask:0xf bank_mask:0xf bound_ctrl:0
	v_fmac_f32_dpp v143, v147, -v171 row_shr:2 row_mask:0xf bank_mask:0xf bound_ctrl:0
	v_fmac_f32_dpp v144, v144, v156 row_shr:2 row_mask:0xf bank_mask:0xf bound_ctrl:0
	v_fmac_f32_dpp v145, v145, v157 row_shr:2 row_mask:0xf bank_mask:0xf bound_ctrl:0
	v_fmac_f32_dpp v146, v146, v158 row_shr:2 row_mask:0xf bank_mask:0xf bound_ctrl:0
	v_fmac_f32_dpp v147, v147, v159 row_shr:2 row_mask:0xf bank_mask:0xf bound_ctrl:0
	v_fmac_f32_dpp v144, v180, v168 row_shr:2 row_mask:0xf bank_mask:0xf bound_ctrl:0
	v_fmac_f32_dpp v145, v181, v169 row_shr:2 row_mask:0xf bank_mask:0xf bound_ctrl:0
	v_fmac_f32_dpp v146, v182, v170 row_shr:2 row_mask:0xf bank_mask:0xf bound_ctrl:0
	v_fmac_f32_dpp v147, v183, v171 row_shr:2 row_mask:0xf bank_mask:0xf bound_ctrl:0
	ds_read_b128 v[156:159], v9 offset:1536
	ds_read_b128 v[168:171], v9 offset:1792
	s_waitcnt lgkmcnt(2)
	v_mov_b32_e32 v180, v148
	v_mov_b32_e32 v181, v149
	v_mov_b32_e32 v182, v150
	v_mov_b32_e32 v183, v151
	v_fmac_f32_dpp v148, v148, v172 row_shr:2 row_mask:0xf bank_mask:0xf bound_ctrl:0
	v_fmac_f32_dpp v149, v149, v173 row_shr:2 row_mask:0xf bank_mask:0xf bound_ctrl:0
	v_fmac_f32_dpp v150, v150, v174 row_shr:2 row_mask:0xf bank_mask:0xf bound_ctrl:0
	v_fmac_f32_dpp v151, v151, v175 row_shr:2 row_mask:0xf bank_mask:0xf bound_ctrl:0
	v_fmac_f32_dpp v148, v152, -v176 row_shr:2 row_mask:0xf bank_mask:0xf bound_ctrl:0
	v_fmac_f32_dpp v149, v153, -v177 row_shr:2 row_mask:0xf bank_mask:0xf bound_ctrl:0
	v_fmac_f32_dpp v150, v154, -v178 row_shr:2 row_mask:0xf bank_mask:0xf bound_ctrl:0
	v_fmac_f32_dpp v151, v155, -v179 row_shr:2 row_mask:0xf bank_mask:0xf bound_ctrl:0
	v_fmac_f32_dpp v152, v152, v172 row_shr:2 row_mask:0xf bank_mask:0xf bound_ctrl:0
	v_fmac_f32_dpp v153, v153, v173 row_shr:2 row_mask:0xf bank_mask:0xf bound_ctrl:0
	v_fmac_f32_dpp v154, v154, v174 row_shr:2 row_mask:0xf bank_mask:0xf bound_ctrl:0
	v_fmac_f32_dpp v155, v155, v175 row_shr:2 row_mask:0xf bank_mask:0xf bound_ctrl:0
	v_fmac_f32_dpp v152, v180, v176 row_shr:2 row_mask:0xf bank_mask:0xf bound_ctrl:0
	v_fmac_f32_dpp v153, v181, v177 row_shr:2 row_mask:0xf bank_mask:0xf bound_ctrl:0
	v_fmac_f32_dpp v154, v182, v178 row_shr:2 row_mask:0xf bank_mask:0xf bound_ctrl:0
	v_fmac_f32_dpp v155, v183, v179 row_shr:2 row_mask:0xf bank_mask:0xf bound_ctrl:0
	ds_read_b128 v[172:175], v9 offset:1600
	ds_read_b128 v[176:179], v9 offset:1856
	s_waitcnt lgkmcnt(2)
	v_mov_b32_e32 v180, v116
	v_mov_b32_e32 v181, v117
	v_mov_b32_e32 v182, v118
	v_mov_b32_e32 v183, v119
	v_fmac_f32_dpp v116, v116, v156 row_shr:4 row_mask:0xf bank_mask:0xf bound_ctrl:0
	v_fmac_f32_dpp v117, v117, v157 row_shr:4 row_mask:0xf bank_mask:0xf bound_ctrl:0
	v_fmac_f32_dpp v118, v118, v158 row_shr:4 row_mask:0xf bank_mask:0xf bound_ctrl:0
	v_fmac_f32_dpp v119, v119, v159 row_shr:4 row_mask:0xf bank_mask:0xf bound_ctrl:0
	v_fmac_f32_dpp v116, v120, -v168 row_shr:4 row_mask:0xf bank_mask:0xf bound_ctrl:0
	v_fmac_f32_dpp v117, v121, -v169 row_shr:4 row_mask:0xf bank_mask:0xf bound_ctrl:0
	v_fmac_f32_dpp v118, v122, -v170 row_shr:4 row_mask:0xf bank_mask:0xf bound_ctrl:0
	v_fmac_f32_dpp v119, v123, -v171 row_shr:4 row_mask:0xf bank_mask:0xf bound_ctrl:0
	v_fmac_f32_dpp v120, v120, v156 row_shr:4 row_mask:0xf bank_mask:0xf bound_ctrl:0
	v_fmac_f32_dpp v121, v121, v157 row_shr:4 row_mask:0xf bank_mask:0xf bound_ctrl:0
	v_fmac_f32_dpp v122, v122, v158 row_shr:4 row_mask:0xf bank_mask:0xf bound_ctrl:0
	v_fmac_f32_dpp v123, v123, v159 row_shr:4 row_mask:0xf bank_mask:0xf bound_ctrl:0
	v_fmac_f32_dpp v120, v180, v168 row_shr:4 row_mask:0xf bank_mask:0xf bound_ctrl:0
	v_fmac_f32_dpp v121, v181, v169 row_shr:4 row_mask:0xf bank_mask:0xf bound_ctrl:0
	v_fmac_f32_dpp v122, v182, v170 row_shr:4 row_mask:0xf bank_mask:0xf bound_ctrl:0
	v_fmac_f32_dpp v123, v183, v171 row_shr:4 row_mask:0xf bank_mask:0xf bound_ctrl:0
	ds_read_b128 v[156:159], v9 offset:1664
	ds_read_b128 v[168:171], v9 offset:1920
	s_waitcnt lgkmcnt(2)
	v_mov_b32_e32 v180, v124
	v_mov_b32_e32 v181, v125
	v_mov_b32_e32 v182, v126
	v_mov_b32_e32 v183, v127
	v_fmac_f32_dpp v124, v124, v172 row_shr:4 row_mask:0xf bank_mask:0xf bound_ctrl:0
	v_fmac_f32_dpp v125, v125, v173 row_shr:4 row_mask:0xf bank_mask:0xf bound_ctrl:0
	v_fmac_f32_dpp v126, v126, v174 row_shr:4 row_mask:0xf bank_mask:0xf bound_ctrl:0
	v_fmac_f32_dpp v127, v127, v175 row_shr:4 row_mask:0xf bank_mask:0xf bound_ctrl:0
	v_fmac_f32_dpp v124, v128, -v176 row_shr:4 row_mask:0xf bank_mask:0xf bound_ctrl:0
	v_fmac_f32_dpp v125, v129, -v177 row_shr:4 row_mask:0xf bank_mask:0xf bound_ctrl:0
	v_fmac_f32_dpp v126, v130, -v178 row_shr:4 row_mask:0xf bank_mask:0xf bound_ctrl:0
	v_fmac_f32_dpp v127, v131, -v179 row_shr:4 row_mask:0xf bank_mask:0xf bound_ctrl:0
	v_fmac_f32_dpp v128, v128, v172 row_shr:4 row_mask:0xf bank_mask:0xf bound_ctrl:0
	v_fmac_f32_dpp v129, v129, v173 row_shr:4 row_mask:0xf bank_mask:0xf bound_ctrl:0
	v_fmac_f32_dpp v130, v130, v174 row_shr:4 row_mask:0xf bank_mask:0xf bound_ctrl:0
	v_fmac_f32_dpp v131, v131, v175 row_shr:4 row_mask:0xf bank_mask:0xf bound_ctrl:0
	v_fmac_f32_dpp v128, v180, v176 row_shr:4 row_mask:0xf bank_mask:0xf bound_ctrl:0
	v_fmac_f32_dpp v129, v181, v177 row_shr:4 row_mask:0xf bank_mask:0xf bound_ctrl:0
	v_fmac_f32_dpp v130, v182, v178 row_shr:4 row_mask:0xf bank_mask:0xf bound_ctrl:0
	v_fmac_f32_dpp v131, v183, v179 row_shr:4 row_mask:0xf bank_mask:0xf bound_ctrl:0
	ds_read_b128 v[172:175], v9 offset:1728
	ds_read_b128 v[176:179], v9 offset:1984
	s_waitcnt lgkmcnt(2)
	v_mov_b32_e32 v180, v140
	v_mov_b32_e32 v181, v141
	v_mov_b32_e32 v182, v142
	v_mov_b32_e32 v183, v143
	v_fmac_f32_dpp v140, v140, v156 row_shr:4 row_mask:0xf bank_mask:0xf bound_ctrl:0
	v_fmac_f32_dpp v141, v141, v157 row_shr:4 row_mask:0xf bank_mask:0xf bound_ctrl:0
	v_fmac_f32_dpp v142, v142, v158 row_shr:4 row_mask:0xf bank_mask:0xf bound_ctrl:0
	v_fmac_f32_dpp v143, v143, v159 row_shr:4 row_mask:0xf bank_mask:0xf bound_ctrl:0
	v_fmac_f32_dpp v140, v144, -v168 row_shr:4 row_mask:0xf bank_mask:0xf bound_ctrl:0
	v_fmac_f32_dpp v141, v145, -v169 row_shr:4 row_mask:0xf bank_mask:0xf bound_ctrl:0
	v_fmac_f32_dpp v142, v146, -v170 row_shr:4 row_mask:0xf bank_mask:0xf bound_ctrl:0
	v_fmac_f32_dpp v143, v147, -v171 row_shr:4 row_mask:0xf bank_mask:0xf bound_ctrl:0
	v_fmac_f32_dpp v144, v144, v156 row_shr:4 row_mask:0xf bank_mask:0xf bound_ctrl:0
	v_fmac_f32_dpp v145, v145, v157 row_shr:4 row_mask:0xf bank_mask:0xf bound_ctrl:0
	v_fmac_f32_dpp v146, v146, v158 row_shr:4 row_mask:0xf bank_mask:0xf bound_ctrl:0
	v_fmac_f32_dpp v147, v147, v159 row_shr:4 row_mask:0xf bank_mask:0xf bound_ctrl:0
	v_fmac_f32_dpp v144, v180, v168 row_shr:4 row_mask:0xf bank_mask:0xf bound_ctrl:0
	v_fmac_f32_dpp v145, v181, v169 row_shr:4 row_mask:0xf bank_mask:0xf bound_ctrl:0
	v_fmac_f32_dpp v146, v182, v170 row_shr:4 row_mask:0xf bank_mask:0xf bound_ctrl:0
	v_fmac_f32_dpp v147, v183, v171 row_shr:4 row_mask:0xf bank_mask:0xf bound_ctrl:0
	ds_read_b128 v[156:159], v9 offset:2048
	ds_read_b128 v[168:171], v9 offset:2304
	s_waitcnt lgkmcnt(2)
	v_mov_b32_e32 v180, v148
	v_mov_b32_e32 v181, v149
	v_mov_b32_e32 v182, v150
	v_mov_b32_e32 v183, v151
	v_fmac_f32_dpp v148, v148, v172 row_shr:4 row_mask:0xf bank_mask:0xf bound_ctrl:0
	v_fmac_f32_dpp v149, v149, v173 row_shr:4 row_mask:0xf bank_mask:0xf bound_ctrl:0
	v_fmac_f32_dpp v150, v150, v174 row_shr:4 row_mask:0xf bank_mask:0xf bound_ctrl:0
	v_fmac_f32_dpp v151, v151, v175 row_shr:4 row_mask:0xf bank_mask:0xf bound_ctrl:0
	v_fmac_f32_dpp v148, v152, -v176 row_shr:4 row_mask:0xf bank_mask:0xf bound_ctrl:0
	v_fmac_f32_dpp v149, v153, -v177 row_shr:4 row_mask:0xf bank_mask:0xf bound_ctrl:0
	v_fmac_f32_dpp v150, v154, -v178 row_shr:4 row_mask:0xf bank_mask:0xf bound_ctrl:0
	v_fmac_f32_dpp v151, v155, -v179 row_shr:4 row_mask:0xf bank_mask:0xf bound_ctrl:0
	v_fmac_f32_dpp v152, v152, v172 row_shr:4 row_mask:0xf bank_mask:0xf bound_ctrl:0
	v_fmac_f32_dpp v153, v153, v173 row_shr:4 row_mask:0xf bank_mask:0xf bound_ctrl:0
	v_fmac_f32_dpp v154, v154, v174 row_shr:4 row_mask:0xf bank_mask:0xf bound_ctrl:0
	v_fmac_f32_dpp v155, v155, v175 row_shr:4 row_mask:0xf bank_mask:0xf bound_ctrl:0
	v_fmac_f32_dpp v152, v180, v176 row_shr:4 row_mask:0xf bank_mask:0xf bound_ctrl:0
	v_fmac_f32_dpp v153, v181, v177 row_shr:4 row_mask:0xf bank_mask:0xf bound_ctrl:0
	v_fmac_f32_dpp v154, v182, v178 row_shr:4 row_mask:0xf bank_mask:0xf bound_ctrl:0
	v_fmac_f32_dpp v155, v183, v179 row_shr:4 row_mask:0xf bank_mask:0xf bound_ctrl:0
	ds_read_b128 v[172:175], v9 offset:2112
	ds_read_b128 v[176:179], v9 offset:2368
	s_waitcnt lgkmcnt(2)
	v_mov_b32_e32 v180, v116
	v_mov_b32_e32 v181, v117
	v_mov_b32_e32 v182, v118
	v_mov_b32_e32 v183, v119
	v_fmac_f32_dpp v116, v116, v156 row_shr:8 row_mask:0xf bank_mask:0xf bound_ctrl:0
	v_fmac_f32_dpp v117, v117, v157 row_shr:8 row_mask:0xf bank_mask:0xf bound_ctrl:0
	v_fmac_f32_dpp v118, v118, v158 row_shr:8 row_mask:0xf bank_mask:0xf bound_ctrl:0
	v_fmac_f32_dpp v119, v119, v159 row_shr:8 row_mask:0xf bank_mask:0xf bound_ctrl:0
	v_fmac_f32_dpp v116, v120, -v168 row_shr:8 row_mask:0xf bank_mask:0xf bound_ctrl:0
	v_fmac_f32_dpp v117, v121, -v169 row_shr:8 row_mask:0xf bank_mask:0xf bound_ctrl:0
	v_fmac_f32_dpp v118, v122, -v170 row_shr:8 row_mask:0xf bank_mask:0xf bound_ctrl:0
	v_fmac_f32_dpp v119, v123, -v171 row_shr:8 row_mask:0xf bank_mask:0xf bound_ctrl:0
	v_fmac_f32_dpp v120, v120, v156 row_shr:8 row_mask:0xf bank_mask:0xf bound_ctrl:0
	v_fmac_f32_dpp v121, v121, v157 row_shr:8 row_mask:0xf bank_mask:0xf bound_ctrl:0
	v_fmac_f32_dpp v122, v122, v158 row_shr:8 row_mask:0xf bank_mask:0xf bound_ctrl:0
	v_fmac_f32_dpp v123, v123, v159 row_shr:8 row_mask:0xf bank_mask:0xf bound_ctrl:0
	v_fmac_f32_dpp v120, v180, v168 row_shr:8 row_mask:0xf bank_mask:0xf bound_ctrl:0
	v_fmac_f32_dpp v121, v181, v169 row_shr:8 row_mask:0xf bank_mask:0xf bound_ctrl:0
	v_fmac_f32_dpp v122, v182, v170 row_shr:8 row_mask:0xf bank_mask:0xf bound_ctrl:0
	v_fmac_f32_dpp v123, v183, v171 row_shr:8 row_mask:0xf bank_mask:0xf bound_ctrl:0
	ds_read_b128 v[156:159], v9 offset:2176
	ds_read_b128 v[168:171], v9 offset:2432
	s_waitcnt lgkmcnt(2)
	v_mov_b32_e32 v180, v124
	v_mov_b32_e32 v181, v125
	v_mov_b32_e32 v182, v126
	v_mov_b32_e32 v183, v127
	v_fmac_f32_dpp v124, v124, v172 row_shr:8 row_mask:0xf bank_mask:0xf bound_ctrl:0
	v_fmac_f32_dpp v125, v125, v173 row_shr:8 row_mask:0xf bank_mask:0xf bound_ctrl:0
	v_fmac_f32_dpp v126, v126, v174 row_shr:8 row_mask:0xf bank_mask:0xf bound_ctrl:0
	v_fmac_f32_dpp v127, v127, v175 row_shr:8 row_mask:0xf bank_mask:0xf bound_ctrl:0
	v_fmac_f32_dpp v124, v128, -v176 row_shr:8 row_mask:0xf bank_mask:0xf bound_ctrl:0
	v_fmac_f32_dpp v125, v129, -v177 row_shr:8 row_mask:0xf bank_mask:0xf bound_ctrl:0
	v_fmac_f32_dpp v126, v130, -v178 row_shr:8 row_mask:0xf bank_mask:0xf bound_ctrl:0
	v_fmac_f32_dpp v127, v131, -v179 row_shr:8 row_mask:0xf bank_mask:0xf bound_ctrl:0
	v_fmac_f32_dpp v128, v128, v172 row_shr:8 row_mask:0xf bank_mask:0xf bound_ctrl:0
	v_fmac_f32_dpp v129, v129, v173 row_shr:8 row_mask:0xf bank_mask:0xf bound_ctrl:0
	v_fmac_f32_dpp v130, v130, v174 row_shr:8 row_mask:0xf bank_mask:0xf bound_ctrl:0
	v_fmac_f32_dpp v131, v131, v175 row_shr:8 row_mask:0xf bank_mask:0xf bound_ctrl:0
	v_fmac_f32_dpp v128, v180, v176 row_shr:8 row_mask:0xf bank_mask:0xf bound_ctrl:0
	v_fmac_f32_dpp v129, v181, v177 row_shr:8 row_mask:0xf bank_mask:0xf bound_ctrl:0
	v_fmac_f32_dpp v130, v182, v178 row_shr:8 row_mask:0xf bank_mask:0xf bound_ctrl:0
	v_fmac_f32_dpp v131, v183, v179 row_shr:8 row_mask:0xf bank_mask:0xf bound_ctrl:0
	ds_read_b128 v[172:175], v9 offset:2240
	ds_read_b128 v[176:179], v9 offset:2496
	s_waitcnt lgkmcnt(2)
	v_mov_b32_e32 v180, v140
	v_mov_b32_e32 v181, v141
	v_mov_b32_e32 v182, v142
	v_mov_b32_e32 v183, v143
	v_fmac_f32_dpp v140, v140, v156 row_shr:8 row_mask:0xf bank_mask:0xf bound_ctrl:0
	v_fmac_f32_dpp v141, v141, v157 row_shr:8 row_mask:0xf bank_mask:0xf bound_ctrl:0
	v_fmac_f32_dpp v142, v142, v158 row_shr:8 row_mask:0xf bank_mask:0xf bound_ctrl:0
	v_fmac_f32_dpp v143, v143, v159 row_shr:8 row_mask:0xf bank_mask:0xf bound_ctrl:0
	v_fmac_f32_dpp v140, v144, -v168 row_shr:8 row_mask:0xf bank_mask:0xf bound_ctrl:0
	v_fmac_f32_dpp v141, v145, -v169 row_shr:8 row_mask:0xf bank_mask:0xf bound_ctrl:0
	v_fmac_f32_dpp v142, v146, -v170 row_shr:8 row_mask:0xf bank_mask:0xf bound_ctrl:0
	v_fmac_f32_dpp v143, v147, -v171 row_shr:8 row_mask:0xf bank_mask:0xf bound_ctrl:0
	v_fmac_f32_dpp v144, v144, v156 row_shr:8 row_mask:0xf bank_mask:0xf bound_ctrl:0
	v_fmac_f32_dpp v145, v145, v157 row_shr:8 row_mask:0xf bank_mask:0xf bound_ctrl:0
	v_fmac_f32_dpp v146, v146, v158 row_shr:8 row_mask:0xf bank_mask:0xf bound_ctrl:0
	v_fmac_f32_dpp v147, v147, v159 row_shr:8 row_mask:0xf bank_mask:0xf bound_ctrl:0
	v_fmac_f32_dpp v144, v180, v168 row_shr:8 row_mask:0xf bank_mask:0xf bound_ctrl:0
	v_fmac_f32_dpp v145, v181, v169 row_shr:8 row_mask:0xf bank_mask:0xf bound_ctrl:0
	v_fmac_f32_dpp v146, v182, v170 row_shr:8 row_mask:0xf bank_mask:0xf bound_ctrl:0
	v_fmac_f32_dpp v147, v183, v171 row_shr:8 row_mask:0xf bank_mask:0xf bound_ctrl:0
	s_waitcnt lgkmcnt(0)
	v_mov_b32_e32 v180, v148
	v_mov_b32_e32 v181, v149
	v_mov_b32_e32 v182, v150
	v_mov_b32_e32 v183, v151
	v_fmac_f32_dpp v148, v148, v172 row_shr:8 row_mask:0xf bank_mask:0xf bound_ctrl:0
	v_fmac_f32_dpp v149, v149, v173 row_shr:8 row_mask:0xf bank_mask:0xf bound_ctrl:0
	v_fmac_f32_dpp v150, v150, v174 row_shr:8 row_mask:0xf bank_mask:0xf bound_ctrl:0
	v_fmac_f32_dpp v151, v151, v175 row_shr:8 row_mask:0xf bank_mask:0xf bound_ctrl:0
	v_fmac_f32_dpp v148, v152, -v176 row_shr:8 row_mask:0xf bank_mask:0xf bound_ctrl:0
	v_fmac_f32_dpp v149, v153, -v177 row_shr:8 row_mask:0xf bank_mask:0xf bound_ctrl:0
	v_fmac_f32_dpp v150, v154, -v178 row_shr:8 row_mask:0xf bank_mask:0xf bound_ctrl:0
	v_fmac_f32_dpp v151, v155, -v179 row_shr:8 row_mask:0xf bank_mask:0xf bound_ctrl:0
	v_fmac_f32_dpp v152, v152, v172 row_shr:8 row_mask:0xf bank_mask:0xf bound_ctrl:0
	v_fmac_f32_dpp v153, v153, v173 row_shr:8 row_mask:0xf bank_mask:0xf bound_ctrl:0
	v_fmac_f32_dpp v154, v154, v174 row_shr:8 row_mask:0xf bank_mask:0xf bound_ctrl:0
	v_fmac_f32_dpp v155, v155, v175 row_shr:8 row_mask:0xf bank_mask:0xf bound_ctrl:0
	v_fmac_f32_dpp v152, v180, v176 row_shr:8 row_mask:0xf bank_mask:0xf bound_ctrl:0
	v_fmac_f32_dpp v153, v181, v177 row_shr:8 row_mask:0xf bank_mask:0xf bound_ctrl:0
	v_fmac_f32_dpp v154, v182, v178 row_shr:8 row_mask:0xf bank_mask:0xf bound_ctrl:0
	v_fmac_f32_dpp v155, v183, v179 row_shr:8 row_mask:0xf bank_mask:0xf bound_ctrl:0
	ds_read_b128 v[156:159], v9 offset:0
	ds_read_b128 v[168:171], v9 offset:256
	ds_read_b128 v[172:175], v9 offset:64
	ds_read_b128 v[176:179], v9 offset:320
	s_waitcnt lgkmcnt(2)
	s_nop 1
	v_fmac_f32_dpp v84, v116, v156 row_shr:1 row_mask:0xf bank_mask:0xf bound_ctrl:0
	v_fmac_f32_dpp v85, v117, v157 row_shr:1 row_mask:0xf bank_mask:0xf bound_ctrl:0
	v_fmac_f32_dpp v86, v118, v158 row_shr:1 row_mask:0xf bank_mask:0xf bound_ctrl:0
	v_fmac_f32_dpp v87, v119, v159 row_shr:1 row_mask:0xf bank_mask:0xf bound_ctrl:0
	v_fmac_f32_dpp v84, v120, -v168 row_shr:1 row_mask:0xf bank_mask:0xf bound_ctrl:0
	v_fmac_f32_dpp v85, v121, -v169 row_shr:1 row_mask:0xf bank_mask:0xf bound_ctrl:0
	v_fmac_f32_dpp v86, v122, -v170 row_shr:1 row_mask:0xf bank_mask:0xf bound_ctrl:0
	v_fmac_f32_dpp v87, v123, -v171 row_shr:1 row_mask:0xf bank_mask:0xf bound_ctrl:0
	v_fmac_f32_dpp v88, v120, v156 row_shr:1 row_mask:0xf bank_mask:0xf bound_ctrl:0
	v_fmac_f32_dpp v89, v121, v157 row_shr:1 row_mask:0xf bank_mask:0xf bound_ctrl:0
	v_fmac_f32_dpp v90, v122, v158 row_shr:1 row_mask:0xf bank_mask:0xf bound_ctrl:0
	v_fmac_f32_dpp v91, v123, v159 row_shr:1 row_mask:0xf bank_mask:0xf bound_ctrl:0
	v_fmac_f32_dpp v88, v116, v168 row_shr:1 row_mask:0xf bank_mask:0xf bound_ctrl:0
	v_fmac_f32_dpp v89, v117, v169 row_shr:1 row_mask:0xf bank_mask:0xf bound_ctrl:0
	v_fmac_f32_dpp v90, v118, v170 row_shr:1 row_mask:0xf bank_mask:0xf bound_ctrl:0
	v_fmac_f32_dpp v91, v119, v171 row_shr:1 row_mask:0xf bank_mask:0xf bound_ctrl:0
	ds_read_b128 v[156:159], v9 offset:128
	ds_read_b128 v[168:171], v9 offset:384
	s_waitcnt lgkmcnt(2)
	v_fmac_f32_dpp v92, v124, v172 row_shr:1 row_mask:0xf bank_mask:0xf bound_ctrl:0
	v_fmac_f32_dpp v93, v125, v173 row_shr:1 row_mask:0xf bank_mask:0xf bound_ctrl:0
	v_fmac_f32_dpp v94, v126, v174 row_shr:1 row_mask:0xf bank_mask:0xf bound_ctrl:0
	v_fmac_f32_dpp v95, v127, v175 row_shr:1 row_mask:0xf bank_mask:0xf bound_ctrl:0
	v_fmac_f32_dpp v92, v128, -v176 row_shr:1 row_mask:0xf bank_mask:0xf bound_ctrl:0
	v_fmac_f32_dpp v93, v129, -v177 row_shr:1 row_mask:0xf bank_mask:0xf bound_ctrl:0
	v_fmac_f32_dpp v94, v130, -v178 row_shr:1 row_mask:0xf bank_mask:0xf bound_ctrl:0
	v_fmac_f32_dpp v95, v131, -v179 row_shr:1 row_mask:0xf bank_mask:0xf bound_ctrl:0
	v_fmac_f32_dpp v96, v128, v172 row_shr:1 row_mask:0xf bank_mask:0xf bound_ctrl:0
	v_fmac_f32_dpp v97, v129, v173 row_shr:1 row_mask:0xf bank_mask:0xf bound_ctrl:0
	v_fmac_f32_dpp v98, v130, v174 row_shr:1 row_mask:0xf bank_mask:0xf bound_ctrl:0
	v_fmac_f32_dpp v99, v131, v175 row_shr:1 row_mask:0xf bank_mask:0xf bound_ctrl:0
	v_fmac_f32_dpp v96, v124, v176 row_shr:1 row_mask:0xf bank_mask:0xf bound_ctrl:0
	v_fmac_f32_dpp v97, v125, v177 row_shr:1 row_mask:0xf bank_mask:0xf bound_ctrl:0
	v_fmac_f32_dpp v98, v126, v178 row_shr:1 row_mask:0xf bank_mask:0xf bound_ctrl:0
	v_fmac_f32_dpp v99, v127, v179 row_shr:1 row_mask:0xf bank_mask:0xf bound_ctrl:0
	ds_read_b128 v[172:175], v9 offset:192
	ds_read_b128 v[176:179], v9 offset:448
	s_waitcnt lgkmcnt(2)
	v_fmac_f32_dpp v100, v140, v156 row_shr:1 row_mask:0xf bank_mask:0xf bound_ctrl:0
	v_fmac_f32_dpp v101, v141, v157 row_shr:1 row_mask:0xf bank_mask:0xf bound_ctrl:0
	v_fmac_f32_dpp v102, v142, v158 row_shr:1 row_mask:0xf bank_mask:0xf bound_ctrl:0
	v_fmac_f32_dpp v103, v143, v159 row_shr:1 row_mask:0xf bank_mask:0xf bound_ctrl:0
	v_fmac_f32_dpp v100, v144, -v168 row_shr:1 row_mask:0xf bank_mask:0xf bound_ctrl:0
	v_fmac_f32_dpp v101, v145, -v169 row_shr:1 row_mask:0xf bank_mask:0xf bound_ctrl:0
	v_fmac_f32_dpp v102, v146, -v170 row_shr:1 row_mask:0xf bank_mask:0xf bound_ctrl:0
	v_fmac_f32_dpp v103, v147, -v171 row_shr:1 row_mask:0xf bank_mask:0xf bound_ctrl:0
	v_fmac_f32_dpp v104, v144, v156 row_shr:1 row_mask:0xf bank_mask:0xf bound_ctrl:0
	v_fmac_f32_dpp v105, v145, v157 row_shr:1 row_mask:0xf bank_mask:0xf bound_ctrl:0
	v_fmac_f32_dpp v106, v146, v158 row_shr:1 row_mask:0xf bank_mask:0xf bound_ctrl:0
	v_fmac_f32_dpp v107, v147, v159 row_shr:1 row_mask:0xf bank_mask:0xf bound_ctrl:0
	v_fmac_f32_dpp v104, v140, v168 row_shr:1 row_mask:0xf bank_mask:0xf bound_ctrl:0
	v_fmac_f32_dpp v105, v141, v169 row_shr:1 row_mask:0xf bank_mask:0xf bound_ctrl:0
	v_fmac_f32_dpp v106, v142, v170 row_shr:1 row_mask:0xf bank_mask:0xf bound_ctrl:0
	v_fmac_f32_dpp v107, v143, v171 row_shr:1 row_mask:0xf bank_mask:0xf bound_ctrl:0
	s_waitcnt lgkmcnt(0)
	v_fmac_f32_dpp v108, v148, v172 row_shr:1 row_mask:0xf bank_mask:0xf bound_ctrl:0
	v_fmac_f32_dpp v109, v149, v173 row_shr:1 row_mask:0xf bank_mask:0xf bound_ctrl:0
	v_fmac_f32_dpp v110, v150, v174 row_shr:1 row_mask:0xf bank_mask:0xf bound_ctrl:0
	v_fmac_f32_dpp v111, v151, v175 row_shr:1 row_mask:0xf bank_mask:0xf bound_ctrl:0
	v_fmac_f32_dpp v108, v152, -v176 row_shr:1 row_mask:0xf bank_mask:0xf bound_ctrl:0
	v_fmac_f32_dpp v109, v153, -v177 row_shr:1 row_mask:0xf bank_mask:0xf bound_ctrl:0
	v_fmac_f32_dpp v110, v154, -v178 row_shr:1 row_mask:0xf bank_mask:0xf bound_ctrl:0
	v_fmac_f32_dpp v111, v155, -v179 row_shr:1 row_mask:0xf bank_mask:0xf bound_ctrl:0
	v_fmac_f32_dpp v112, v152, v172 row_shr:1 row_mask:0xf bank_mask:0xf bound_ctrl:0
	v_fmac_f32_dpp v113, v153, v173 row_shr:1 row_mask:0xf bank_mask:0xf bound_ctrl:0
	v_fmac_f32_dpp v114, v154, v174 row_shr:1 row_mask:0xf bank_mask:0xf bound_ctrl:0
	v_fmac_f32_dpp v115, v155, v175 row_shr:1 row_mask:0xf bank_mask:0xf bound_ctrl:0
	v_fmac_f32_dpp v112, v148, v176 row_shr:1 row_mask:0xf bank_mask:0xf bound_ctrl:0
	v_fmac_f32_dpp v113, v149, v177 row_shr:1 row_mask:0xf bank_mask:0xf bound_ctrl:0
	v_fmac_f32_dpp v114, v150, v178 row_shr:1 row_mask:0xf bank_mask:0xf bound_ctrl:0
	v_fmac_f32_dpp v115, v151, v179 row_shr:1 row_mask:0xf bank_mask:0xf bound_ctrl:0
	s_waitcnt vmcnt(0)
	v_xor_b32_e32 v24, 0x80000000, v24
	v_xor_b32_e32 v25, 0x80000000, v25
	v_xor_b32_e32 v26, 0x80000000, v26
	v_xor_b32_e32 v27, 0x80000000, v27
	v_xor_b32_e32 v32, 0x80000000, v32
	v_xor_b32_e32 v33, 0x80000000, v33
	v_xor_b32_e32 v34, 0x80000000, v34
	v_xor_b32_e32 v35, 0x80000000, v35
	v_xor_b32_e32 v40, 0x80000000, v40
	v_xor_b32_e32 v41, 0x80000000, v41
	v_xor_b32_e32 v42, 0x80000000, v42
	v_xor_b32_e32 v43, 0x80000000, v43
	v_xor_b32_e32 v48, 0x80000000, v48
	v_xor_b32_e32 v49, 0x80000000, v49
	v_xor_b32_e32 v50, 0x80000000, v50
	v_xor_b32_e32 v51, 0x80000000, v51
	s_nop 1
	v_mfma_f32_16x16x4_f32 v[184:187], v84, v20, 0
	v_mfma_f32_16x16x4_f32 v[192:195], v88, v24, 0
	v_mfma_f32_16x16x4_f32 v[188:191], v116, v20, 0
	v_mfma_f32_16x16x4_f32 v[224:227], v120, v24, 0
	v_mfma_f32_16x16x4_f32 v[184:187], v85, v21, v[184:187]
	v_mfma_f32_16x16x4_f32 v[192:195], v89, v25, v[192:195]
	v_mfma_f32_16x16x4_f32 v[188:191], v117, v21, v[188:191]
	v_mfma_f32_16x16x4_f32 v[224:227], v121, v25, v[224:227]
	v_mfma_f32_16x16x4_f32 v[184:187], v86, v22, v[184:187]
	v_mfma_f32_16x16x4_f32 v[192:195], v90, v26, v[192:195]
	v_mfma_f32_16x16x4_f32 v[188:191], v118, v22, v[188:191]
	v_mfma_f32_16x16x4_f32 v[224:227], v122, v26, v[224:227]
	v_mfma_f32_16x16x4_f32 v[184:187], v87, v23, v[184:187]
	v_mfma_f32_16x16x4_f32 v[192:195], v91, v27, v[192:195]
	v_mfma_f32_16x16x4_f32 v[188:191], v119, v23, v[188:191]
	v_mfma_f32_16x16x4_f32 v[224:227], v123, v27, v[224:227]
	v_mfma_f32_16x16x4_f32 v[184:187], v92, v28, v[184:187]
	v_mfma_f32_16x16x4_f32 v[192:195], v96, v32, v[192:195]
	v_mfma_f32_16x16x4_f32 v[188:191], v124, v28, v[188:191]
	v_mfma_f32_16x16x4_f32 v[224:227], v128, v32, v[224:227]
	v_mfma_f32_16x16x4_f32 v[184:187], v93, v29, v[184:187]
	v_mfma_f32_16x16x4_f32 v[192:195], v97, v33, v[192:195]
	v_mfma_f32_16x16x4_f32 v[188:191], v125, v29, v[188:191]
	v_mfma_f32_16x16x4_f32 v[224:227], v129, v33, v[224:227]
	v_mfma_f32_16x16x4_f32 v[184:187], v94, v30, v[184:187]
	v_mfma_f32_16x16x4_f32 v[192:195], v98, v34, v[192:195]
	v_mfma_f32_16x16x4_f32 v[188:191], v126, v30, v[188:191]
	v_mfma_f32_16x16x4_f32 v[224:227], v130, v34, v[224:227]
	v_mfma_f32_16x16x4_f32 v[184:187], v95, v31, v[184:187]
	v_mfma_f32_16x16x4_f32 v[192:195], v99, v35, v[192:195]
	v_mfma_f32_16x16x4_f32 v[188:191], v127, v31, v[188:191]
	v_mfma_f32_16x16x4_f32 v[224:227], v131, v35, v[224:227]
	v_mfma_f32_16x16x4_f32 v[184:187], v100, v36, v[184:187]
	v_mfma_f32_16x16x4_f32 v[192:195], v104, v40, v[192:195]
	v_mfma_f32_16x16x4_f32 v[188:191], v140, v36, v[188:191]
	v_mfma_f32_16x16x4_f32 v[224:227], v144, v40, v[224:227]
	v_mfma_f32_16x16x4_f32 v[184:187], v101, v37, v[184:187]
	v_mfma_f32_16x16x4_f32 v[192:195], v105, v41, v[192:195]
	v_mfma_f32_16x16x4_f32 v[188:191], v141, v37, v[188:191]
	v_mfma_f32_16x16x4_f32 v[224:227], v145, v41, v[224:227]
	v_mfma_f32_16x16x4_f32 v[184:187], v102, v38, v[184:187]
	v_mfma_f32_16x16x4_f32 v[192:195], v106, v42, v[192:195]
	v_mfma_f32_16x16x4_f32 v[188:191], v142, v38, v[188:191]
	v_mfma_f32_16x16x4_f32 v[224:227], v146, v42, v[224:227]
	v_mfma_f32_16x16x4_f32 v[184:187], v103, v39, v[184:187]
	v_mfma_f32_16x16x4_f32 v[192:195], v107, v43, v[192:195]
	v_mfma_f32_16x16x4_f32 v[188:191], v143, v39, v[188:191]
	v_mfma_f32_16x16x4_f32 v[224:227], v147, v43, v[224:227]
	v_mfma_f32_16x16x4_f32 v[184:187], v108, v44, v[184:187]
	v_mfma_f32_16x16x4_f32 v[192:195], v112, v48, v[192:195]
	v_mfma_f32_16x16x4_f32 v[188:191], v148, v44, v[188:191]
	v_mfma_f32_16x16x4_f32 v[224:227], v152, v48, v[224:227]
	v_mfma_f32_16x16x4_f32 v[184:187], v109, v45, v[184:187]
	v_mfma_f32_16x16x4_f32 v[192:195], v113, v49, v[192:195]
	v_mfma_f32_16x16x4_f32 v[188:191], v149, v45, v[188:191]
	v_mfma_f32_16x16x4_f32 v[224:227], v153, v49, v[224:227]
	v_mfma_f32_16x16x4_f32 v[184:187], v110, v46, v[184:187]
	v_mfma_f32_16x16x4_f32 v[192:195], v114, v50, v[192:195]
	v_mfma_f32_16x16x4_f32 v[188:191], v150, v46, v[188:191]
	v_mfma_f32_16x16x4_f32 v[224:227], v154, v50, v[224:227]
	v_mfma_f32_16x16x4_f32 v[184:187], v111, v47, v[184:187]
	v_mfma_f32_16x16x4_f32 v[192:195], v115, v51, v[192:195]
	v_mfma_f32_16x16x4_f32 v[188:191], v151, v47, v[188:191]
	v_mfma_f32_16x16x4_f32 v[224:227], v155, v51, v[224:227]
	s_cmp_ge_u32 s0, 128
	s_cbranch_scc1 .Ls5b_nofin1
	s_and_b32 s55, s0, 7
	s_cmp_lg_u32 s55, 7
	s_cbranch_scc1 .Ls5b_nofin1
	s_lshr_b32 s55, s0, 3
	s_lshl_b32 s55, s55, 2
	s_add_i32 s55, s55, s32
	s_lshl_b32 s55, s55, 1
	s_add_i32 s55, s55, 0
	s_lshl_b32 s55, s55, 4
	s_add_i32 s55, s55, s6
	s_lshl_b32 s55, s55, 8
	s_add_u32 s48, s92, 0x4000000
	s_addc_u32 s49, s93, 0
	s_add_u32 s48, s48, s55
	s_addc_u32 s49, s49, 0
	s_add_u32 s50, s48, 0x80000
	s_addc_u32 s51, s49, 0
	s_mov_b64 exec, s[10:11]
	global_store_dwordx4 v10, v[116:119], s[48:49] offset:0
	global_store_dwordx4 v10, v[120:123], s[50:51] offset:0
	global_store_dwordx4 v10, v[124:127], s[48:49] offset:64
	global_store_dwordx4 v10, v[128:131], s[50:51] offset:64
	global_store_dwordx4 v10, v[140:143], s[48:49] offset:128
	global_store_dwordx4 v10, v[144:147], s[50:51] offset:128
	global_store_dwordx4 v10, v[148:151], s[48:49] offset:192
	global_store_dwordx4 v10, v[152:155], s[50:51] offset:192
	s_mov_b64 exec, -1
	s_waitcnt vmcnt(0)
.Ls5b_nofin1:
	s_add_i32 s55, s6, 16
	s_lshl_b32 s56, s55, 13
	s_add_u32 s12, s94, 0x12d96000
	s_addc_u32 s13, s95, 0
	s_add_u32 s12, s12, s56
	s_addc_u32 s13, s13, 0
	s_lshl_b32 s56, s55, 9
	s_add_u32 s38, s94, 0x12d92000
	s_addc_u32 s39, s95, 0
	s_add_u32 s38, s38, s56
	s_addc_u32 s39, s39, 0
	s_lshl_b32 s56, s0, 5
	s_lshl_b32 s55, s6, 1
	s_add_i32 s56, s56, s55
	s_add_i32 s56, s56, 1
	s_lshl_b32 s56, s56, 9
	s_add_u32 s36, s94, 0x133d6000
	s_addc_u32 s37, s95, 0
	s_add_u32 s36, s36, s56
	s_addc_u32 s37, s37, 0
	s_lshl_b32 s56, s32, 1
	s_add_i32 s56, s56, 1
	s_lshl_b32 s56, s56, 4
	s_add_i32 s56, s56, s6
	s_lshl_b32 s56, s56, 12
	s_add_u32 s14, s16, s56
	s_addc_u32 s15, s17, 0
	s_add_u32 s24, s18, s56
	s_addc_u32 s25, s19, 0
	global_load_dwordx2 v[2:3], v7, s[38:39]
	global_load_dwordx4 v[52:55], v6, s[12:13] offset:0
	global_load_dwordx4 v[56:59], v6, s[12:13] offset:1024
	global_load_dwordx4 v[60:63], v6, s[12:13] offset:256
	global_load_dwordx4 v[64:67], v6, s[12:13] offset:1280
	global_load_dwordx4 v[68:71], v6, s[12:13] offset:512
	global_load_dwordx4 v[72:75], v6, s[12:13] offset:1536
	global_load_dwordx4 v[76:79], v6, s[12:13] offset:768
	global_load_dwordx4 v[80:83], v6, s[12:13] offset:1792
	global_load_dwordx4 v[20:23], v15, s[36:37] offset:0
	global_load_dwordx4 v[24:27], v15, s[36:37] offset:16
	global_load_dwordx4 v[28:31], v15, s[36:37] offset:128
	global_load_dwordx4 v[32:35], v15, s[36:37] offset:144
	global_load_dwordx4 v[36:39], v15, s[36:37] offset:256
	global_load_dwordx4 v[40:43], v15, s[36:37] offset:272
	global_load_dwordx4 v[44:47], v15, s[36:37] offset:384
	global_load_dwordx4 v[48:51], v15, s[36:37] offset:400
	s_waitcnt vmcnt(16)
	ds_write_b32 v8, v2 offset:0
	ds_write_b32 v8, v3 offset:256
	v_mul_f32_e32 v180, v3, v3
	v_mul_f32_e32 v181, v2, v3
	v_fma_f32 v2, v2, v2, -v180
	v_add_f32_e32 v3, v181, v181
	ds_write_b32 v8, v2 offset:512
	ds_write_b32 v8, v3 offset:768
	v_mul_f32_e32 v180, v3, v3
	v_mul_f32_e32 v181, v2, v3
	v_fma_f32 v2, v2, v2, -v180
	v_add_f32_e32 v3, v181, v181
	ds_write_b32 v8, v2 offset:1024
	ds_write_b32 v8, v3 offset:1280
	v_mul_f32_e32 v180, v3, v3
	v_mul_f32_e32 v181, v2, v3
	v_fma_f32 v2, v2, v2, -v180
	v_add_f32_e32 v3, v181, v181
	ds_write_b32 v8, v2 offset:1536
	ds_write_b32 v8, v3 offset:1792
	v_mul_f32_e32 v180, v3, v3
	v_mul_f32_e32 v181, v2, v3
	v_fma_f32 v2, v2, v2, -v180
	v_add_f32_e32 v3, v181, v181
	ds_write_b32 v8, v2 offset:2048
	ds_write_b32 v8, v3 offset:2304
	s_waitcnt lgkmcnt(0)
	s_waitcnt vmcnt(15)
	v_mfma_f32_16x16x4_f32 v[84:87], v52, v228, 0
	v_mfma_f32_16x16x4_f32 v[88:91], v53, v228, 0
	v_mfma_f32_16x16x4_f32 v[116:119], v52, v232, 0
	v_mfma_f32_16x16x4_f32 v[120:123], v53, v232, 0
	s_waitcnt vmcnt(13)
	v_mfma_f32_16x16x4_f32 v[92:95], v60, v228, 0
	v_mfma_f32_16x16x4_f32 v[96:99], v61, v228, 0
	v_mfma_f32_16x16x4_f32 v[124:127], v60, v232, 0
	v_mfma_f32_16x16x4_f32 v[128:131], v61, v232, 0
	s_waitcnt vmcnt(11)
	v_mfma_f32_16x16x4_f32 v[100:103], v68, v228, 0
	v_mfma_f32_16x16x4_f32 v[104:107], v69, v228, 0
	v_mfma_f32_16x16x4_f32 v[140:143], v68, v232, 0
	v_mfma_f32_16x16x4_f32 v[144:147], v69, v232, 0
	s_waitcnt vmcnt(9)
	v_mfma_f32_16x16x4_f32 v[108:111], v76, v228, 0
	v_mfma_f32_16x16x4_f32 v[112:115], v77, v228, 0
	v_mfma_f32_16x16x4_f32 v[148:151], v76, v232, 0
	v_mfma_f32_16x16x4_f32 v[152:155], v77, v232, 0
	v_mfma_f32_16x16x4_f32 v[84:87], v54, v229, v[84:87]
	v_mfma_f32_16x16x4_f32 v[88:91], v55, v229, v[88:91]
	v_mfma_f32_16x16x4_f32 v[116:119], v54, v233, v[116:119]
	v_mfma_f32_16x16x4_f32 v[120:123], v55, v233, v[120:123]
	v_mfma_f32_16x16x4_f32 v[92:95], v62, v229, v[92:95]
	v_mfma_f32_16x16x4_f32 v[96:99], v63, v229, v[96:99]
	v_mfma_f32_16x16x4_f32 v[124:127], v62, v233, v[124:127]
	v_mfma_f32_16x16x4_f32 v[128:131], v63, v233, v[128:131]
	v_mfma_f32_16x16x4_f32 v[100:103], v70, v229, v[100:103]
	v_mfma_f32_16x16x4_f32 v[104:107], v71, v229, v[104:107]
	v_mfma_f32_16x16x4_f32 v[140:143], v70, v233, v[140:143]
	v_mfma_f32_16x16x4_f32 v[144:147], v71, v233, v[144:147]
	v_mfma_f32_16x16x4_f32 v[108:111], v78, v229, v[108:111]
	v_mfma_f32_16x16x4_f32 v[112:115], v79, v229, v[112:115]
	v_mfma_f32_16x16x4_f32 v[148:151], v78, v233, v[148:151]
	v_mfma_f32_16x16x4_f32 v[152:155], v79, v233, v[152:155]
	v_mfma_f32_16x16x4_f32 v[84:87], v56, v230, v[84:87]
	v_mfma_f32_16x16x4_f32 v[88:91], v57, v230, v[88:91]
	v_mfma_f32_16x16x4_f32 v[116:119], v56, v234, v[116:119]
	v_mfma_f32_16x16x4_f32 v[120:123], v57, v234, v[120:123]
	v_mfma_f32_16x16x4_f32 v[92:95], v64, v230, v[92:95]
	v_mfma_f32_16x16x4_f32 v[96:99], v65, v230, v[96:99]
	v_mfma_f32_16x16x4_f32 v[124:127], v64, v234, v[124:127]
	v_mfma_f32_16x16x4_f32 v[128:131], v65, v234, v[128:131]
	v_mfma_f32_16x16x4_f32 v[100:103], v72, v230, v[100:103]
	v_mfma_f32_16x16x4_f32 v[104:107], v73, v230, v[104:107]
	v_mfma_f32_16x16x4_f32 v[140:143], v72, v234, v[140:143]
	v_mfma_f32_16x16x4_f32 v[144:147], v73, v234, v[144:147]
	s_waitcnt vmcnt(8)
	v_mfma_f32_16x16x4_f32 v[108:111], v80, v230, v[108:111]
	v_mfma_f32_16x16x4_f32 v[112:115], v81, v230, v[112:115]
	v_mfma_f32_16x16x4_f32 v[148:151], v80, v234, v[148:151]
	v_mfma_f32_16x16x4_f32 v[152:155], v81, v234, v[152:155]
	v_mfma_f32_16x16x4_f32 v[84:87], v58, v231, v[84:87]
	v_mfma_f32_16x16x4_f32 v[88:91], v59, v231, v[88:91]
	v_mfma_f32_16x16x4_f32 v[116:119], v58, v235, v[116:119]
	v_mfma_f32_16x16x4_f32 v[120:123], v59, v235, v[120:123]
	v_mfma_f32_16x16x4_f32 v[92:95], v66, v231, v[92:95]
	v_mfma_f32_16x16x4_f32 v[96:99], v67, v231, v[96:99]
	v_mfma_f32_16x16x4_f32 v[124:127], v66, v235, v[124:127]
	v_mfma_f32_16x16x4_f32 v[128:131], v67, v235, v[128:131]
	v_mfma_f32_16x16x4_f32 v[100:103], v74, v231, v[100:103]
	v_mfma_f32_16x16x4_f32 v[104:107], v75, v231, v[104:107]
	v_mfma_f32_16x16x4_f32 v[140:143], v74, v235, v[140:143]
	v_mfma_f32_16x16x4_f32 v[144:147], v75, v235, v[144:147]
	v_mfma_f32_16x16x4_f32 v[108:111], v82, v231, v[108:111]
	v_mfma_f32_16x16x4_f32 v[112:115], v83, v231, v[112:115]
	v_mfma_f32_16x16x4_f32 v[148:151], v82, v235, v[148:151]
	v_mfma_f32_16x16x4_f32 v[152:155], v83, v235, v[152:155]
	global_load_dwordx4 v[52:55], v14, s[14:15] offset:0
	global_load_dwordx4 v[56:59], v14, s[24:25] offset:0
	global_load_dwordx4 v[60:63], v14, s[14:15] offset:64
	global_load_dwordx4 v[64:67], v14, s[24:25] offset:64
	global_load_dwordx4 v[68:71], v14, s[14:15] offset:128
	global_load_dwordx4 v[72:75], v14, s[24:25] offset:128
	global_load_dwordx4 v[76:79], v14, s[14:15] offset:192
	global_load_dwordx4 v[80:83], v14, s[24:25] offset:192
	s_waitcnt vmcnt(8)
	s_nop 9
	ds_read_b128 v[156:159], v9 offset:0
	ds_read_b128 v[168:171], v9 offset:256
	ds_read_b128 v[172:175], v9 offset:64
	ds_read_b128 v[176:179], v9 offset:320
	s_waitcnt lgkmcnt(2)
	s_mov_b64 exec, s[10:11]
	v_fmac_f32_e32 v116, v156, v20
	v_fmac_f32_e32 v117, v157, v22
	v_fmac_f32_e32 v118, v158, v24
	v_fmac_f32_e32 v119, v159, v26
	v_fma_f32 v116, -v168, v21, v116
	v_fma_f32 v117, -v169, v23, v117
	v_fma_f32 v118, -v170, v25, v118
	v_fma_f32 v119, -v171, v27, v119
	v_fmac_f32_e32 v120, v156, v21
	v_fmac_f32_e32 v121, v157, v23
	v_fmac_f32_e32 v122, v158, v25
	v_fmac_f32_e32 v123, v159, v27
	v_fmac_f32_e32 v120, v168, v20
	v_fmac_f32_e32 v121, v169, v22
	v_fmac_f32_e32 v122, v170, v24
	v_fmac_f32_e32 v123, v171, v26
	s_mov_b64 exec, -1
	v_fmac_f32_e32 v84, v156, v116
	v_fmac_f32_e32 v85, v157, v117
	v_fmac_f32_e32 v86, v158, v118
	v_fmac_f32_e32 v87, v159, v119
	v_fma_f32 v84, -v168, v120, v84
	v_fma_f32 v85, -v169, v121, v85
	v_fma_f32 v86, -v170, v122, v86
	v_fma_f32 v87, -v171, v123, v87
	v_fmac_f32_e32 v88, v156, v120
	v_fmac_f32_e32 v89, v157, v121
	v_fmac_f32_e32 v90, v158, v122
	v_fmac_f32_e32 v91, v159, v123
	v_fmac_f32_e32 v88, v168, v116
	v_fmac_f32_e32 v89, v169, v117
	v_fmac_f32_e32 v90, v170, v118
	v_fmac_f32_e32 v91, v171, v119
	ds_read_b128 v[156:159], v9 offset:128
	ds_read_b128 v[168:171], v9 offset:384
	s_waitcnt lgkmcnt(2)
	s_mov_b64 exec, s[10:11]
	v_fmac_f32_e32 v124, v172, v28
	v_fmac_f32_e32 v125, v173, v30
	v_fmac_f32_e32 v126, v174, v32
	v_fmac_f32_e32 v127, v175, v34
	v_fma_f32 v124, -v176, v29, v124
	v_fma_f32 v125, -v177, v31, v125
	v_fma_f32 v126, -v178, v33, v126
	v_fma_f32 v127, -v179, v35, v127
	v_fmac_f32_e32 v128, v172, v29
	v_fmac_f32_e32 v129, v173, v31
	v_fmac_f32_e32 v130, v174, v33
	v_fmac_f32_e32 v131, v175, v35
	v_fmac_f32_e32 v128, v176, v28
	v_fmac_f32_e32 v129, v177, v30
	v_fmac_f32_e32 v130, v178, v32
	v_fmac_f32_e32 v131, v179, v34
	s_mov_b64 exec, -1
	v_fmac_f32_e32 v92, v172, v124
	v_fmac_f32_e32 v93, v173, v125
	v_fmac_f32_e32 v94, v174, v126
	v_fmac_f32_e32 v95, v175, v127
	v_fma_f32 v92, -v176, v128, v92
	v_fma_f32 v93, -v177, v129, v93
	v_fma_f32 v94, -v178, v130, v94
	v_fma_f32 v95, -v179, v131, v95
	v_fmac_f32_e32 v96, v172, v128
	v_fmac_f32_e32 v97, v173, v129
	v_fmac_f32_e32 v98, v174, v130
	v_fmac_f32_e32 v99, v175, v131
	v_fmac_f32_e32 v96, v176, v124
	v_fmac_f32_e32 v97, v177, v125
	v_fmac_f32_e32 v98, v178, v126
	v_fmac_f32_e32 v99, v179, v127
	ds_read_b128 v[172:175], v9 offset:192
	ds_read_b128 v[176:179], v9 offset:448
	s_waitcnt lgkmcnt(2)
	s_mov_b64 exec, s[10:11]
	v_fmac_f32_e32 v140, v156, v36
	v_fmac_f32_e32 v141, v157, v38
	v_fmac_f32_e32 v142, v158, v40
	v_fmac_f32_e32 v143, v159, v42
	v_fma_f32 v140, -v168, v37, v140
	v_fma_f32 v141, -v169, v39, v141
	v_fma_f32 v142, -v170, v41, v142
	v_fma_f32 v143, -v171, v43, v143
	v_fmac_f32_e32 v144, v156, v37
	v_fmac_f32_e32 v145, v157, v39
	v_fmac_f32_e32 v146, v158, v41
	v_fmac_f32_e32 v147, v159, v43
	v_fmac_f32_e32 v144, v168, v36
	v_fmac_f32_e32 v145, v169, v38
	v_fmac_f32_e32 v146, v170, v40
	v_fmac_f32_e32 v147, v171, v42
	s_mov_b64 exec, -1
	v_fmac_f32_e32 v100, v156, v140
	v_fmac_f32_e32 v101, v157, v141
	v_fmac_f32_e32 v102, v158, v142
	v_fmac_f32_e32 v103, v159, v143
	v_fma_f32 v100, -v168, v144, v100
	v_fma_f32 v101, -v169, v145, v101
	v_fma_f32 v102, -v170, v146, v102
	v_fma_f32 v103, -v171, v147, v103
	v_fmac_f32_e32 v104, v156, v144
	v_fmac_f32_e32 v105, v157, v145
	v_fmac_f32_e32 v106, v158, v146
	v_fmac_f32_e32 v107, v159, v147
	v_fmac_f32_e32 v104, v168, v140
	v_fmac_f32_e32 v105, v169, v141
	v_fmac_f32_e32 v106, v170, v142
	v_fmac_f32_e32 v107, v171, v143
	s_waitcnt lgkmcnt(0)
	s_mov_b64 exec, s[10:11]
	v_fmac_f32_e32 v148, v172, v44
	v_fmac_f32_e32 v149, v173, v46
	v_fmac_f32_e32 v150, v174, v48
	v_fmac_f32_e32 v151, v175, v50
	v_fma_f32 v148, -v176, v45, v148
	v_fma_f32 v149, -v177, v47, v149
	v_fma_f32 v150, -v178, v49, v150
	v_fma_f32 v151, -v179, v51, v151
	v_fmac_f32_e32 v152, v172, v45
	v_fmac_f32_e32 v153, v173, v47
	v_fmac_f32_e32 v154, v174, v49
	v_fmac_f32_e32 v155, v175, v51
	v_fmac_f32_e32 v152, v176, v44
	v_fmac_f32_e32 v153, v177, v46
	v_fmac_f32_e32 v154, v178, v48
	v_fmac_f32_e32 v155, v179, v50
	s_mov_b64 exec, -1
	v_fmac_f32_e32 v108, v172, v148
	v_fmac_f32_e32 v109, v173, v149
	v_fmac_f32_e32 v110, v174, v150
	v_fmac_f32_e32 v111, v175, v151
	v_fma_f32 v108, -v176, v152, v108
	v_fma_f32 v109, -v177, v153, v109
	v_fma_f32 v110, -v178, v154, v110
	v_fma_f32 v111, -v179, v155, v111
	v_fmac_f32_e32 v112, v172, v152
	v_fmac_f32_e32 v113, v173, v153
	v_fmac_f32_e32 v114, v174, v154
	v_fmac_f32_e32 v115, v175, v155
	v_fmac_f32_e32 v112, v176, v148
	v_fmac_f32_e32 v113, v177, v149
	v_fmac_f32_e32 v114, v178, v150
	v_fmac_f32_e32 v115, v179, v151
	ds_read_b128 v[156:159], v9 offset:512
	ds_read_b128 v[168:171], v9 offset:768
	ds_read_b128 v[172:175], v9 offset:576
	ds_read_b128 v[176:179], v9 offset:832
	s_waitcnt lgkmcnt(2)
	v_mov_b32_e32 v180, v84
	v_mov_b32_e32 v181, v85
	v_mov_b32_e32 v182, v86
	v_mov_b32_e32 v183, v87
	s_nop 1
	v_fmac_f32_dpp v84, v84, v156 row_shl:1 row_mask:0xf bank_mask:0xf bound_ctrl:0
	v_fmac_f32_dpp v85, v85, v157 row_shl:1 row_mask:0xf bank_mask:0xf bound_ctrl:0
	v_fmac_f32_dpp v86, v86, v158 row_shl:1 row_mask:0xf bank_mask:0xf bound_ctrl:0
	v_fmac_f32_dpp v87, v87, v159 row_shl:1 row_mask:0xf bank_mask:0xf bound_ctrl:0
	v_fmac_f32_dpp v84, v88, -v168 row_shl:1 row_mask:0xf bank_mask:0xf bound_ctrl:0
	v_fmac_f32_dpp v85, v89, -v169 row_shl:1 row_mask:0xf bank_mask:0xf bound_ctrl:0
	v_fmac_f32_dpp v86, v90, -v170 row_shl:1 row_mask:0xf bank_mask:0xf bound_ctrl:0
	v_fmac_f32_dpp v87, v91, -v171 row_shl:1 row_mask:0xf bank_mask:0xf bound_ctrl:0
	v_fmac_f32_dpp v88, v88, v156 row_shl:1 row_mask:0xf bank_mask:0xf bound_ctrl:0
	v_fmac_f32_dpp v89, v89, v157 row_shl:1 row_mask:0xf bank_mask:0xf bound_ctrl:0
	v_fmac_f32_dpp v90, v90, v158 row_shl:1 row_mask:0xf bank_mask:0xf bound_ctrl:0
	v_fmac_f32_dpp v91, v91, v159 row_shl:1 row_mask:0xf bank_mask:0xf bound_ctrl:0
	v_fmac_f32_dpp v88, v180, v168 row_shl:1 row_mask:0xf bank_mask:0xf bound_ctrl:0
	v_fmac_f32_dpp v89, v181, v169 row_shl:1 row_mask:0xf bank_mask:0xf bound_ctrl:0
	v_fmac_f32_dpp v90, v182, v170 row_shl:1 row_mask:0xf bank_mask:0xf bound_ctrl:0
	v_fmac_f32_dpp v91, v183, v171 row_shl:1 row_mask:0xf bank_mask:0xf bound_ctrl:0
	ds_read_b128 v[156:159], v9 offset:640
	ds_read_b128 v[168:171], v9 offset:896
	s_waitcnt lgkmcnt(2)
	v_mov_b32_e32 v180, v92
	v_mov_b32_e32 v181, v93
	v_mov_b32_e32 v182, v94
	v_mov_b32_e32 v183, v95
	v_fmac_f32_dpp v92, v92, v172 row_shl:1 row_mask:0xf bank_mask:0xf bound_ctrl:0
	v_fmac_f32_dpp v93, v93, v173 row_shl:1 row_mask:0xf bank_mask:0xf bound_ctrl:0
	v_fmac_f32_dpp v94, v94, v174 row_shl:1 row_mask:0xf bank_mask:0xf bound_ctrl:0
	v_fmac_f32_dpp v95, v95, v175 row_shl:1 row_mask:0xf bank_mask:0xf bound_ctrl:0
	v_fmac_f32_dpp v92, v96, -v176 row_shl:1 row_mask:0xf bank_mask:0xf bound_ctrl:0
	v_fmac_f32_dpp v93, v97, -v177 row_shl:1 row_mask:0xf bank_mask:0xf bound_ctrl:0
	v_fmac_f32_dpp v94, v98, -v178 row_shl:1 row_mask:0xf bank_mask:0xf bound_ctrl:0
	v_fmac_f32_dpp v95, v99, -v179 row_shl:1 row_mask:0xf bank_mask:0xf bound_ctrl:0
	v_fmac_f32_dpp v96, v96, v172 row_shl:1 row_mask:0xf bank_mask:0xf bound_ctrl:0
	v_fmac_f32_dpp v97, v97, v173 row_shl:1 row_mask:0xf bank_mask:0xf bound_ctrl:0
	v_fmac_f32_dpp v98, v98, v174 row_shl:1 row_mask:0xf bank_mask:0xf bound_ctrl:0
	v_fmac_f32_dpp v99, v99, v175 row_shl:1 row_mask:0xf bank_mask:0xf bound_ctrl:0
	v_fmac_f32_dpp v96, v180, v176 row_shl:1 row_mask:0xf bank_mask:0xf bound_ctrl:0
	v_fmac_f32_dpp v97, v181, v177 row_shl:1 row_mask:0xf bank_mask:0xf bound_ctrl:0
	v_fmac_f32_dpp v98, v182, v178 row_shl:1 row_mask:0xf bank_mask:0xf bound_ctrl:0
	v_fmac_f32_dpp v99, v183, v179 row_shl:1 row_mask:0xf bank_mask:0xf bound_ctrl:0
	ds_read_b128 v[172:175], v9 offset:704
	ds_read_b128 v[176:179], v9 offset:960
	s_waitcnt lgkmcnt(2)
	v_mov_b32_e32 v180, v100
	v_mov_b32_e32 v181, v101
	v_mov_b32_e32 v182, v102
	v_mov_b32_e32 v183, v103
	v_fmac_f32_dpp v100, v100, v156 row_shl:1 row_mask:0xf bank_mask:0xf bound_ctrl:0
	v_fmac_f32_dpp v101, v101, v157 row_shl:1 row_mask:0xf bank_mask:0xf bound_ctrl:0
	v_fmac_f32_dpp v102, v102, v158 row_shl:1 row_mask:0xf bank_mask:0xf bound_ctrl:0
	v_fmac_f32_dpp v103, v103, v159 row_shl:1 row_mask:0xf bank_mask:0xf bound_ctrl:0
	v_fmac_f32_dpp v100, v104, -v168 row_shl:1 row_mask:0xf bank_mask:0xf bound_ctrl:0
	v_fmac_f32_dpp v101, v105, -v169 row_shl:1 row_mask:0xf bank_mask:0xf bound_ctrl:0
	v_fmac_f32_dpp v102, v106, -v170 row_shl:1 row_mask:0xf bank_mask:0xf bound_ctrl:0
	v_fmac_f32_dpp v103, v107, -v171 row_shl:1 row_mask:0xf bank_mask:0xf bound_ctrl:0
	v_fmac_f32_dpp v104, v104, v156 row_shl:1 row_mask:0xf bank_mask:0xf bound_ctrl:0
	v_fmac_f32_dpp v105, v105, v157 row_shl:1 row_mask:0xf bank_mask:0xf bound_ctrl:0
	v_fmac_f32_dpp v106, v106, v158 row_shl:1 row_mask:0xf bank_mask:0xf bound_ctrl:0
	v_fmac_f32_dpp v107, v107, v159 row_shl:1 row_mask:0xf bank_mask:0xf bound_ctrl:0
	v_fmac_f32_dpp v104, v180, v168 row_shl:1 row_mask:0xf bank_mask:0xf bound_ctrl:0
	v_fmac_f32_dpp v105, v181, v169 row_shl:1 row_mask:0xf bank_mask:0xf bound_ctrl:0
	v_fmac_f32_dpp v106, v182, v170 row_shl:1 row_mask:0xf bank_mask:0xf bound_ctrl:0
	v_fmac_f32_dpp v107, v183, v171 row_shl:1 row_mask:0xf bank_mask:0xf bound_ctrl:0
	ds_read_b128 v[156:159], v9 offset:1024
	ds_read_b128 v[168:171], v9 offset:1280
	s_waitcnt lgkmcnt(2)
	v_mov_b32_e32 v180, v108
	v_mov_b32_e32 v181, v109
	v_mov_b32_e32 v182, v110
	v_mov_b32_e32 v183, v111
	v_fmac_f32_dpp v108, v108, v172 row_shl:1 row_mask:0xf bank_mask:0xf bound_ctrl:0
	v_fmac_f32_dpp v109, v109, v173 row_shl:1 row_mask:0xf bank_mask:0xf bound_ctrl:0
	v_fmac_f32_dpp v110, v110, v174 row_shl:1 row_mask:0xf bank_mask:0xf bound_ctrl:0
	v_fmac_f32_dpp v111, v111, v175 row_shl:1 row_mask:0xf bank_mask:0xf bound_ctrl:0
	v_fmac_f32_dpp v108, v112, -v176 row_shl:1 row_mask:0xf bank_mask:0xf bound_ctrl:0
	v_fmac_f32_dpp v109, v113, -v177 row_shl:1 row_mask:0xf bank_mask:0xf bound_ctrl:0
	v_fmac_f32_dpp v110, v114, -v178 row_shl:1 row_mask:0xf bank_mask:0xf bound_ctrl:0
	v_fmac_f32_dpp v111, v115, -v179 row_shl:1 row_mask:0xf bank_mask:0xf bound_ctrl:0
	v_fmac_f32_dpp v112, v112, v172 row_shl:1 row_mask:0xf bank_mask:0xf bound_ctrl:0
	v_fmac_f32_dpp v113, v113, v173 row_shl:1 row_mask:0xf bank_mask:0xf bound_ctrl:0
	v_fmac_f32_dpp v114, v114, v174 row_shl:1 row_mask:0xf bank_mask:0xf bound_ctrl:0
	v_fmac_f32_dpp v115, v115, v175 row_shl:1 row_mask:0xf bank_mask:0xf bound_ctrl:0
	v_fmac_f32_dpp v112, v180, v176 row_shl:1 row_mask:0xf bank_mask:0xf bound_ctrl:0
	v_fmac_f32_dpp v113, v181, v177 row_shl:1 row_mask:0xf bank_mask:0xf bound_ctrl:0
	v_fmac_f32_dpp v114, v182, v178 row_shl:1 row_mask:0xf bank_mask:0xf bound_ctrl:0
	v_fmac_f32_dpp v115, v183, v179 row_shl:1 row_mask:0xf bank_mask:0xf bound_ctrl:0
	ds_read_b128 v[172:175], v9 offset:1088
	ds_read_b128 v[176:179], v9 offset:1344
	s_waitcnt lgkmcnt(2)
	v_mov_b32_e32 v180, v84
	v_mov_b32_e32 v181, v85
	v_mov_b32_e32 v182, v86
	v_mov_b32_e32 v183, v87
	v_fmac_f32_dpp v84, v84, v156 row_shl:2 row_mask:0xf bank_mask:0xf bound_ctrl:0
	v_fmac_f32_dpp v85, v85, v157 row_shl:2 row_mask:0xf bank_mask:0xf bound_ctrl:0
	v_fmac_f32_dpp v86, v86, v158 row_shl:2 row_mask:0xf bank_mask:0xf bound_ctrl:0
	v_fmac_f32_dpp v87, v87, v159 row_shl:2 row_mask:0xf bank_mask:0xf bound_ctrl:0
	v_fmac_f32_dpp v84, v88, -v168 row_shl:2 row_mask:0xf bank_mask:0xf bound_ctrl:0
	v_fmac_f32_dpp v85, v89, -v169 row_shl:2 row_mask:0xf bank_mask:0xf bound_ctrl:0
	v_fmac_f32_dpp v86, v90, -v170 row_shl:2 row_mask:0xf bank_mask:0xf bound_ctrl:0
	v_fmac_f32_dpp v87, v91, -v171 row_shl:2 row_mask:0xf bank_mask:0xf bound_ctrl:0
	v_fmac_f32_dpp v88, v88, v156 row_shl:2 row_mask:0xf bank_mask:0xf bound_ctrl:0
	v_fmac_f32_dpp v89, v89, v157 row_shl:2 row_mask:0xf bank_mask:0xf bound_ctrl:0
	v_fmac_f32_dpp v90, v90, v158 row_shl:2 row_mask:0xf bank_mask:0xf bound_ctrl:0
	v_fmac_f32_dpp v91, v91, v159 row_shl:2 row_mask:0xf bank_mask:0xf bound_ctrl:0
	v_fmac_f32_dpp v88, v180, v168 row_shl:2 row_mask:0xf bank_mask:0xf bound_ctrl:0
	v_fmac_f32_dpp v89, v181, v169 row_shl:2 row_mask:0xf bank_mask:0xf bound_ctrl:0
	v_fmac_f32_dpp v90, v182, v170 row_shl:2 row_mask:0xf bank_mask:0xf bound_ctrl:0
	v_fmac_f32_dpp v91, v183, v171 row_shl:2 row_mask:0xf bank_mask:0xf bound_ctrl:0
	ds_read_b128 v[156:159], v9 offset:1152
	ds_read_b128 v[168:171], v9 offset:1408
	s_waitcnt lgkmcnt(2)
	v_mov_b32_e32 v180, v92
	v_mov_b32_e32 v181, v93
	v_mov_b32_e32 v182, v94
	v_mov_b32_e32 v183, v95
	v_fmac_f32_dpp v92, v92, v172 row_shl:2 row_mask:0xf bank_mask:0xf bound_ctrl:0
	v_fmac_f32_dpp v93, v93, v173 row_shl:2 row_mask:0xf bank_mask:0xf bound_ctrl:0
	v_fmac_f32_dpp v94, v94, v174 row_shl:2 row_mask:0xf bank_mask:0xf bound_ctrl:0
	v_fmac_f32_dpp v95, v95, v175 row_shl:2 row_mask:0xf bank_mask:0xf bound_ctrl:0
	v_fmac_f32_dpp v92, v96, -v176 row_shl:2 row_mask:0xf bank_mask:0xf bound_ctrl:0
	v_fmac_f32_dpp v93, v97, -v177 row_shl:2 row_mask:0xf bank_mask:0xf bound_ctrl:0
	v_fmac_f32_dpp v94, v98, -v178 row_shl:2 row_mask:0xf bank_mask:0xf bound_ctrl:0
	v_fmac_f32_dpp v95, v99, -v179 row_shl:2 row_mask:0xf bank_mask:0xf bound_ctrl:0
	v_fmac_f32_dpp v96, v96, v172 row_shl:2 row_mask:0xf bank_mask:0xf bound_ctrl:0
	v_fmac_f32_dpp v97, v97, v173 row_shl:2 row_mask:0xf bank_mask:0xf bound_ctrl:0
	v_fmac_f32_dpp v98, v98, v174 row_shl:2 row_mask:0xf bank_mask:0xf bound_ctrl:0
	v_fmac_f32_dpp v99, v99, v175 row_shl:2 row_mask:0xf bank_mask:0xf bound_ctrl:0
	v_fmac_f32_dpp v96, v180, v176 row_shl:2 row_mask:0xf bank_mask:0xf bound_ctrl:0
	v_fmac_f32_dpp v97, v181, v177 row_shl:2 row_mask:0xf bank_mask:0xf bound_ctrl:0
	v_fmac_f32_dpp v98, v182, v178 row_shl:2 row_mask:0xf bank_mask:0xf bound_ctrl:0
	v_fmac_f32_dpp v99, v183, v179 row_shl:2 row_mask:0xf bank_mask:0xf bound_ctrl:0
	ds_read_b128 v[172:175], v9 offset:1216
	ds_read_b128 v[176:179], v9 offset:1472
	s_waitcnt lgkmcnt(2)
	v_mov_b32_e32 v180, v100
	v_mov_b32_e32 v181, v101
	v_mov_b32_e32 v182, v102
	v_mov_b32_e32 v183, v103
	v_fmac_f32_dpp v100, v100, v156 row_shl:2 row_mask:0xf bank_mask:0xf bound_ctrl:0
	v_fmac_f32_dpp v101, v101, v157 row_shl:2 row_mask:0xf bank_mask:0xf bound_ctrl:0
	v_fmac_f32_dpp v102, v102, v158 row_shl:2 row_mask:0xf bank_mask:0xf bound_ctrl:0
	v_fmac_f32_dpp v103, v103, v159 row_shl:2 row_mask:0xf bank_mask:0xf bound_ctrl:0
	v_fmac_f32_dpp v100, v104, -v168 row_shl:2 row_mask:0xf bank_mask:0xf bound_ctrl:0
	v_fmac_f32_dpp v101, v105, -v169 row_shl:2 row_mask:0xf bank_mask:0xf bound_ctrl:0
	v_fmac_f32_dpp v102, v106, -v170 row_shl:2 row_mask:0xf bank_mask:0xf bound_ctrl:0
	v_fmac_f32_dpp v103, v107, -v171 row_shl:2 row_mask:0xf bank_mask:0xf bound_ctrl:0
	v_fmac_f32_dpp v104, v104, v156 row_shl:2 row_mask:0xf bank_mask:0xf bound_ctrl:0
	v_fmac_f32_dpp v105, v105, v157 row_shl:2 row_mask:0xf bank_mask:0xf bound_ctrl:0
	v_fmac_f32_dpp v106, v106, v158 row_shl:2 row_mask:0xf bank_mask:0xf bound_ctrl:0
	v_fmac_f32_dpp v107, v107, v159 row_shl:2 row_mask:0xf bank_mask:0xf bound_ctrl:0
	v_fmac_f32_dpp v104, v180, v168 row_shl:2 row_mask:0xf bank_mask:0xf bound_ctrl:0
	v_fmac_f32_dpp v105, v181, v169 row_shl:2 row_mask:0xf bank_mask:0xf bound_ctrl:0
	v_fmac_f32_dpp v106, v182, v170 row_shl:2 row_mask:0xf bank_mask:0xf bound_ctrl:0
	v_fmac_f32_dpp v107, v183, v171 row_shl:2 row_mask:0xf bank_mask:0xf bound_ctrl:0
	ds_read_b128 v[156:159], v9 offset:1536
	ds_read_b128 v[168:171], v9 offset:1792
	s_waitcnt lgkmcnt(2)
	v_mov_b32_e32 v180, v108
	v_mov_b32_e32 v181, v109
	v_mov_b32_e32 v182, v110
	v_mov_b32_e32 v183, v111
	v_fmac_f32_dpp v108, v108, v172 row_shl:2 row_mask:0xf bank_mask:0xf bound_ctrl:0
	v_fmac_f32_dpp v109, v109, v173 row_shl:2 row_mask:0xf bank_mask:0xf bound_ctrl:0
	v_fmac_f32_dpp v110, v110, v174 row_shl:2 row_mask:0xf bank_mask:0xf bound_ctrl:0
	v_fmac_f32_dpp v111, v111, v175 row_shl:2 row_mask:0xf bank_mask:0xf bound_ctrl:0
	v_fmac_f32_dpp v108, v112, -v176 row_shl:2 row_mask:0xf bank_mask:0xf bound_ctrl:0
	v_fmac_f32_dpp v109, v113, -v177 row_shl:2 row_mask:0xf bank_mask:0xf bound_ctrl:0
	v_fmac_f32_dpp v110, v114, -v178 row_shl:2 row_mask:0xf bank_mask:0xf bound_ctrl:0
	v_fmac_f32_dpp v111, v115, -v179 row_shl:2 row_mask:0xf bank_mask:0xf bound_ctrl:0
	v_fmac_f32_dpp v112, v112, v172 row_shl:2 row_mask:0xf bank_mask:0xf bound_ctrl:0
	v_fmac_f32_dpp v113, v113, v173 row_shl:2 row_mask:0xf bank_mask:0xf bound_ctrl:0
	v_fmac_f32_dpp v114, v114, v174 row_shl:2 row_mask:0xf bank_mask:0xf bound_ctrl:0
	v_fmac_f32_dpp v115, v115, v175 row_shl:2 row_mask:0xf bank_mask:0xf bound_ctrl:0
	v_fmac_f32_dpp v112, v180, v176 row_shl:2 row_mask:0xf bank_mask:0xf bound_ctrl:0
	v_fmac_f32_dpp v113, v181, v177 row_shl:2 row_mask:0xf bank_mask:0xf bound_ctrl:0
	v_fmac_f32_dpp v114, v182, v178 row_shl:2 row_mask:0xf bank_mask:0xf bound_ctrl:0
	v_fmac_f32_dpp v115, v183, v179 row_shl:2 row_mask:0xf bank_mask:0xf bound_ctrl:0
	ds_read_b128 v[172:175], v9 offset:1600
	ds_read_b128 v[176:179], v9 offset:1856
	s_waitcnt lgkmcnt(2)
	v_mov_b32_e32 v180, v84
	v_mov_b32_e32 v181, v85
	v_mov_b32_e32 v182, v86
	v_mov_b32_e32 v183, v87
	v_fmac_f32_dpp v84, v84, v156 row_shl:4 row_mask:0xf bank_mask:0xf bound_ctrl:0
	v_fmac_f32_dpp v85, v85, v157 row_shl:4 row_mask:0xf bank_mask:0xf bound_ctrl:0
	v_fmac_f32_dpp v86, v86, v158 row_shl:4 row_mask:0xf bank_mask:0xf bound_ctrl:0
	v_fmac_f32_dpp v87, v87, v159 row_shl:4 row_mask:0xf bank_mask:0xf bound_ctrl:0
	v_fmac_f32_dpp v84, v88, -v168 row_shl:4 row_mask:0xf bank_mask:0xf bound_ctrl:0
	v_fmac_f32_dpp v85, v89, -v169 row_shl:4 row_mask:0xf bank_mask:0xf bound_ctrl:0
	v_fmac_f32_dpp v86, v90, -v170 row_shl:4 row_mask:0xf bank_mask:0xf bound_ctrl:0
	v_fmac_f32_dpp v87, v91, -v171 row_shl:4 row_mask:0xf bank_mask:0xf bound_ctrl:0
	v_fmac_f32_dpp v88, v88, v156 row_shl:4 row_mask:0xf bank_mask:0xf bound_ctrl:0
	v_fmac_f32_dpp v89, v89, v157 row_shl:4 row_mask:0xf bank_mask:0xf bound_ctrl:0
	v_fmac_f32_dpp v90, v90, v158 row_shl:4 row_mask:0xf bank_mask:0xf bound_ctrl:0
	v_fmac_f32_dpp v91, v91, v159 row_shl:4 row_mask:0xf bank_mask:0xf bound_ctrl:0
	v_fmac_f32_dpp v88, v180, v168 row_shl:4 row_mask:0xf bank_mask:0xf bound_ctrl:0
	v_fmac_f32_dpp v89, v181, v169 row_shl:4 row_mask:0xf bank_mask:0xf bound_ctrl:0
	v_fmac_f32_dpp v90, v182, v170 row_shl:4 row_mask:0xf bank_mask:0xf bound_ctrl:0
	v_fmac_f32_dpp v91, v183, v171 row_shl:4 row_mask:0xf bank_mask:0xf bound_ctrl:0
	ds_read_b128 v[156:159], v9 offset:1664
	ds_read_b128 v[168:171], v9 offset:1920
	s_waitcnt lgkmcnt(2)
	v_mov_b32_e32 v180, v92
	v_mov_b32_e32 v181, v93
	v_mov_b32_e32 v182, v94
	v_mov_b32_e32 v183, v95
	v_fmac_f32_dpp v92, v92, v172 row_shl:4 row_mask:0xf bank_mask:0xf bound_ctrl:0
	v_fmac_f32_dpp v93, v93, v173 row_shl:4 row_mask:0xf bank_mask:0xf bound_ctrl:0
	v_fmac_f32_dpp v94, v94, v174 row_shl:4 row_mask:0xf bank_mask:0xf bound_ctrl:0
	v_fmac_f32_dpp v95, v95, v175 row_shl:4 row_mask:0xf bank_mask:0xf bound_ctrl:0
	v_fmac_f32_dpp v92, v96, -v176 row_shl:4 row_mask:0xf bank_mask:0xf bound_ctrl:0
	v_fmac_f32_dpp v93, v97, -v177 row_shl:4 row_mask:0xf bank_mask:0xf bound_ctrl:0
	v_fmac_f32_dpp v94, v98, -v178 row_shl:4 row_mask:0xf bank_mask:0xf bound_ctrl:0
	v_fmac_f32_dpp v95, v99, -v179 row_shl:4 row_mask:0xf bank_mask:0xf bound_ctrl:0
	v_fmac_f32_dpp v96, v96, v172 row_shl:4 row_mask:0xf bank_mask:0xf bound_ctrl:0
	v_fmac_f32_dpp v97, v97, v173 row_shl:4 row_mask:0xf bank_mask:0xf bound_ctrl:0
	v_fmac_f32_dpp v98, v98, v174 row_shl:4 row_mask:0xf bank_mask:0xf bound_ctrl:0
	v_fmac_f32_dpp v99, v99, v175 row_shl:4 row_mask:0xf bank_mask:0xf bound_ctrl:0
	v_fmac_f32_dpp v96, v180, v176 row_shl:4 row_mask:0xf bank_mask:0xf bound_ctrl:0
	v_fmac_f32_dpp v97, v181, v177 row_shl:4 row_mask:0xf bank_mask:0xf bound_ctrl:0
	v_fmac_f32_dpp v98, v182, v178 row_shl:4 row_mask:0xf bank_mask:0xf bound_ctrl:0
	v_fmac_f32_dpp v99, v183, v179 row_shl:4 row_mask:0xf bank_mask:0xf bound_ctrl:0
	ds_read_b128 v[172:175], v9 offset:1728
	ds_read_b128 v[176:179], v9 offset:1984
	s_waitcnt lgkmcnt(2)
	v_mov_b32_e32 v180, v100
	v_mov_b32_e32 v181, v101
	v_mov_b32_e32 v182, v102
	v_mov_b32_e32 v183, v103
	v_fmac_f32_dpp v100, v100, v156 row_shl:4 row_mask:0xf bank_mask:0xf bound_ctrl:0
	v_fmac_f32_dpp v101, v101, v157 row_shl:4 row_mask:0xf bank_mask:0xf bound_ctrl:0
	v_fmac_f32_dpp v102, v102, v158 row_shl:4 row_mask:0xf bank_mask:0xf bound_ctrl:0
	v_fmac_f32_dpp v103, v103, v159 row_shl:4 row_mask:0xf bank_mask:0xf bound_ctrl:0
	v_fmac_f32_dpp v100, v104, -v168 row_shl:4 row_mask:0xf bank_mask:0xf bound_ctrl:0
	v_fmac_f32_dpp v101, v105, -v169 row_shl:4 row_mask:0xf bank_mask:0xf bound_ctrl:0
	v_fmac_f32_dpp v102, v106, -v170 row_shl:4 row_mask:0xf bank_mask:0xf bound_ctrl:0
	v_fmac_f32_dpp v103, v107, -v171 row_shl:4 row_mask:0xf bank_mask:0xf bound_ctrl:0
	v_fmac_f32_dpp v104, v104, v156 row_shl:4 row_mask:0xf bank_mask:0xf bound_ctrl:0
	v_fmac_f32_dpp v105, v105, v157 row_shl:4 row_mask:0xf bank_mask:0xf bound_ctrl:0
	v_fmac_f32_dpp v106, v106, v158 row_shl:4 row_mask:0xf bank_mask:0xf bound_ctrl:0
	v_fmac_f32_dpp v107, v107, v159 row_shl:4 row_mask:0xf bank_mask:0xf bound_ctrl:0
	v_fmac_f32_dpp v104, v180, v168 row_shl:4 row_mask:0xf bank_mask:0xf bound_ctrl:0
	v_fmac_f32_dpp v105, v181, v169 row_shl:4 row_mask:0xf bank_mask:0xf bound_ctrl:0
	v_fmac_f32_dpp v106, v182, v170 row_shl:4 row_mask:0xf bank_mask:0xf bound_ctrl:0
	v_fmac_f32_dpp v107, v183, v171 row_shl:4 row_mask:0xf bank_mask:0xf bound_ctrl:0
	ds_read_b128 v[156:159], v9 offset:2048
	ds_read_b128 v[168:171], v9 offset:2304
	s_waitcnt lgkmcnt(2)
	v_mov_b32_e32 v180, v108
	v_mov_b32_e32 v181, v109
	v_mov_b32_e32 v182, v110
	v_mov_b32_e32 v183, v111
	v_fmac_f32_dpp v108, v108, v172 row_shl:4 row_mask:0xf bank_mask:0xf bound_ctrl:0
	v_fmac_f32_dpp v109, v109, v173 row_shl:4 row_mask:0xf bank_mask:0xf bound_ctrl:0
	v_fmac_f32_dpp v110, v110, v174 row_shl:4 row_mask:0xf bank_mask:0xf bound_ctrl:0
	v_fmac_f32_dpp v111, v111, v175 row_shl:4 row_mask:0xf bank_mask:0xf bound_ctrl:0
	v_fmac_f32_dpp v108, v112, -v176 row_shl:4 row_mask:0xf bank_mask:0xf bound_ctrl:0
	v_fmac_f32_dpp v109, v113, -v177 row_shl:4 row_mask:0xf bank_mask:0xf bound_ctrl:0
	v_fmac_f32_dpp v110, v114, -v178 row_shl:4 row_mask:0xf bank_mask:0xf bound_ctrl:0
	v_fmac_f32_dpp v111, v115, -v179 row_shl:4 row_mask:0xf bank_mask:0xf bound_ctrl:0
	v_fmac_f32_dpp v112, v112, v172 row_shl:4 row_mask:0xf bank_mask:0xf bound_ctrl:0
	v_fmac_f32_dpp v113, v113, v173 row_shl:4 row_mask:0xf bank_mask:0xf bound_ctrl:0
	v_fmac_f32_dpp v114, v114, v174 row_shl:4 row_mask:0xf bank_mask:0xf bound_ctrl:0
	v_fmac_f32_dpp v115, v115, v175 row_shl:4 row_mask:0xf bank_mask:0xf bound_ctrl:0
	v_fmac_f32_dpp v112, v180, v176 row_shl:4 row_mask:0xf bank_mask:0xf bound_ctrl:0
	v_fmac_f32_dpp v113, v181, v177 row_shl:4 row_mask:0xf bank_mask:0xf bound_ctrl:0
	v_fmac_f32_dpp v114, v182, v178 row_shl:4 row_mask:0xf bank_mask:0xf bound_ctrl:0
	v_fmac_f32_dpp v115, v183, v179 row_shl:4 row_mask:0xf bank_mask:0xf bound_ctrl:0
	ds_read_b128 v[172:175], v9 offset:2112
	ds_read_b128 v[176:179], v9 offset:2368
	s_waitcnt lgkmcnt(2)
	v_mov_b32_e32 v180, v84
	v_mov_b32_e32 v181, v85
	v_mov_b32_e32 v182, v86
	v_mov_b32_e32 v183, v87
	v_fmac_f32_dpp v84, v84, v156 row_shl:8 row_mask:0xf bank_mask:0xf bound_ctrl:0
	v_fmac_f32_dpp v85, v85, v157 row_shl:8 row_mask:0xf bank_mask:0xf bound_ctrl:0
	v_fmac_f32_dpp v86, v86, v158 row_shl:8 row_mask:0xf bank_mask:0xf bound_ctrl:0
	v_fmac_f32_dpp v87, v87, v159 row_shl:8 row_mask:0xf bank_mask:0xf bound_ctrl:0
	v_fmac_f32_dpp v84, v88, -v168 row_shl:8 row_mask:0xf bank_mask:0xf bound_ctrl:0
	v_fmac_f32_dpp v85, v89, -v169 row_shl:8 row_mask:0xf bank_mask:0xf bound_ctrl:0
	v_fmac_f32_dpp v86, v90, -v170 row_shl:8 row_mask:0xf bank_mask:0xf bound_ctrl:0
	v_fmac_f32_dpp v87, v91, -v171 row_shl:8 row_mask:0xf bank_mask:0xf bound_ctrl:0
	v_fmac_f32_dpp v88, v88, v156 row_shl:8 row_mask:0xf bank_mask:0xf bound_ctrl:0
	v_fmac_f32_dpp v89, v89, v157 row_shl:8 row_mask:0xf bank_mask:0xf bound_ctrl:0
	v_fmac_f32_dpp v90, v90, v158 row_shl:8 row_mask:0xf bank_mask:0xf bound_ctrl:0
	v_fmac_f32_dpp v91, v91, v159 row_shl:8 row_mask:0xf bank_mask:0xf bound_ctrl:0
	v_fmac_f32_dpp v88, v180, v168 row_shl:8 row_mask:0xf bank_mask:0xf bound_ctrl:0
	v_fmac_f32_dpp v89, v181, v169 row_shl:8 row_mask:0xf bank_mask:0xf bound_ctrl:0
	v_fmac_f32_dpp v90, v182, v170 row_shl:8 row_mask:0xf bank_mask:0xf bound_ctrl:0
	v_fmac_f32_dpp v91, v183, v171 row_shl:8 row_mask:0xf bank_mask:0xf bound_ctrl:0
	ds_read_b128 v[156:159], v9 offset:2176
	ds_read_b128 v[168:171], v9 offset:2432
	s_waitcnt lgkmcnt(2)
	v_mov_b32_e32 v180, v92
	v_mov_b32_e32 v181, v93
	v_mov_b32_e32 v182, v94
	v_mov_b32_e32 v183, v95
	v_fmac_f32_dpp v92, v92, v172 row_shl:8 row_mask:0xf bank_mask:0xf bound_ctrl:0
	v_fmac_f32_dpp v93, v93, v173 row_shl:8 row_mask:0xf bank_mask:0xf bound_ctrl:0
	v_fmac_f32_dpp v94, v94, v174 row_shl:8 row_mask:0xf bank_mask:0xf bound_ctrl:0
	v_fmac_f32_dpp v95, v95, v175 row_shl:8 row_mask:0xf bank_mask:0xf bound_ctrl:0
	v_fmac_f32_dpp v92, v96, -v176 row_shl:8 row_mask:0xf bank_mask:0xf bound_ctrl:0
	v_fmac_f32_dpp v93, v97, -v177 row_shl:8 row_mask:0xf bank_mask:0xf bound_ctrl:0
	v_fmac_f32_dpp v94, v98, -v178 row_shl:8 row_mask:0xf bank_mask:0xf bound_ctrl:0
	v_fmac_f32_dpp v95, v99, -v179 row_shl:8 row_mask:0xf bank_mask:0xf bound_ctrl:0
	v_fmac_f32_dpp v96, v96, v172 row_shl:8 row_mask:0xf bank_mask:0xf bound_ctrl:0
	v_fmac_f32_dpp v97, v97, v173 row_shl:8 row_mask:0xf bank_mask:0xf bound_ctrl:0
	v_fmac_f32_dpp v98, v98, v174 row_shl:8 row_mask:0xf bank_mask:0xf bound_ctrl:0
	v_fmac_f32_dpp v99, v99, v175 row_shl:8 row_mask:0xf bank_mask:0xf bound_ctrl:0
	v_fmac_f32_dpp v96, v180, v176 row_shl:8 row_mask:0xf bank_mask:0xf bound_ctrl:0
	v_fmac_f32_dpp v97, v181, v177 row_shl:8 row_mask:0xf bank_mask:0xf bound_ctrl:0
	v_fmac_f32_dpp v98, v182, v178 row_shl:8 row_mask:0xf bank_mask:0xf bound_ctrl:0
	v_fmac_f32_dpp v99, v183, v179 row_shl:8 row_mask:0xf bank_mask:0xf bound_ctrl:0
	ds_read_b128 v[172:175], v9 offset:2240
	ds_read_b128 v[176:179], v9 offset:2496
	s_waitcnt lgkmcnt(2)
	v_mov_b32_e32 v180, v100
	v_mov_b32_e32 v181, v101
	v_mov_b32_e32 v182, v102
	v_mov_b32_e32 v183, v103
	v_fmac_f32_dpp v100, v100, v156 row_shl:8 row_mask:0xf bank_mask:0xf bound_ctrl:0
	v_fmac_f32_dpp v101, v101, v157 row_shl:8 row_mask:0xf bank_mask:0xf bound_ctrl:0
	v_fmac_f32_dpp v102, v102, v158 row_shl:8 row_mask:0xf bank_mask:0xf bound_ctrl:0
	v_fmac_f32_dpp v103, v103, v159 row_shl:8 row_mask:0xf bank_mask:0xf bound_ctrl:0
	v_fmac_f32_dpp v100, v104, -v168 row_shl:8 row_mask:0xf bank_mask:0xf bound_ctrl:0
	v_fmac_f32_dpp v101, v105, -v169 row_shl:8 row_mask:0xf bank_mask:0xf bound_ctrl:0
	v_fmac_f32_dpp v102, v106, -v170 row_shl:8 row_mask:0xf bank_mask:0xf bound_ctrl:0
	v_fmac_f32_dpp v103, v107, -v171 row_shl:8 row_mask:0xf bank_mask:0xf bound_ctrl:0
	v_fmac_f32_dpp v104, v104, v156 row_shl:8 row_mask:0xf bank_mask:0xf bound_ctrl:0
	v_fmac_f32_dpp v105, v105, v157 row_shl:8 row_mask:0xf bank_mask:0xf bound_ctrl:0
	v_fmac_f32_dpp v106, v106, v158 row_shl:8 row_mask:0xf bank_mask:0xf bound_ctrl:0
	v_fmac_f32_dpp v107, v107, v159 row_shl:8 row_mask:0xf bank_mask:0xf bound_ctrl:0
	v_fmac_f32_dpp v104, v180, v168 row_shl:8 row_mask:0xf bank_mask:0xf bound_ctrl:0
	v_fmac_f32_dpp v105, v181, v169 row_shl:8 row_mask:0xf bank_mask:0xf bound_ctrl:0
	v_fmac_f32_dpp v106, v182, v170 row_shl:8 row_mask:0xf bank_mask:0xf bound_ctrl:0
	v_fmac_f32_dpp v107, v183, v171 row_shl:8 row_mask:0xf bank_mask:0xf bound_ctrl:0
	s_waitcnt lgkmcnt(0)
	v_mov_b32_e32 v180, v108
	v_mov_b32_e32 v181, v109
	v_mov_b32_e32 v182, v110
	v_mov_b32_e32 v183, v111
	v_fmac_f32_dpp v108, v108, v172 row_shl:8 row_mask:0xf bank_mask:0xf bound_ctrl:0
	v_fmac_f32_dpp v109, v109, v173 row_shl:8 row_mask:0xf bank_mask:0xf bound_ctrl:0
	v_fmac_f32_dpp v110, v110, v174 row_shl:8 row_mask:0xf bank_mask:0xf bound_ctrl:0
	v_fmac_f32_dpp v111, v111, v175 row_shl:8 row_mask:0xf bank_mask:0xf bound_ctrl:0
	v_fmac_f32_dpp v108, v112, -v176 row_shl:8 row_mask:0xf bank_mask:0xf bound_ctrl:0
	v_fmac_f32_dpp v109, v113, -v177 row_shl:8 row_mask:0xf bank_mask:0xf bound_ctrl:0
	v_fmac_f32_dpp v110, v114, -v178 row_shl:8 row_mask:0xf bank_mask:0xf bound_ctrl:0
	v_fmac_f32_dpp v111, v115, -v179 row_shl:8 row_mask:0xf bank_mask:0xf bound_ctrl:0
	v_fmac_f32_dpp v112, v112, v172 row_shl:8 row_mask:0xf bank_mask:0xf bound_ctrl:0
	v_fmac_f32_dpp v113, v113, v173 row_shl:8 row_mask:0xf bank_mask:0xf bound_ctrl:0
	v_fmac_f32_dpp v114, v114, v174 row_shl:8 row_mask:0xf bank_mask:0xf bound_ctrl:0
	v_fmac_f32_dpp v115, v115, v175 row_shl:8 row_mask:0xf bank_mask:0xf bound_ctrl:0
	v_fmac_f32_dpp v112, v180, v176 row_shl:8 row_mask:0xf bank_mask:0xf bound_ctrl:0
	v_fmac_f32_dpp v113, v181, v177 row_shl:8 row_mask:0xf bank_mask:0xf bound_ctrl:0
	v_fmac_f32_dpp v114, v182, v178 row_shl:8 row_mask:0xf bank_mask:0xf bound_ctrl:0
	v_fmac_f32_dpp v115, v183, v179 row_shl:8 row_mask:0xf bank_mask:0xf bound_ctrl:0
	ds_read_b128 v[156:159], v9 offset:0
	ds_read_b128 v[168:171], v9 offset:256
	ds_read_b128 v[172:175], v9 offset:64
	ds_read_b128 v[176:179], v9 offset:320
	s_waitcnt lgkmcnt(2)
	s_nop 1
	v_fmac_f32_dpp v116, v84, v156 row_shl:1 row_mask:0xf bank_mask:0xf bound_ctrl:0
	v_fmac_f32_dpp v117, v85, v157 row_shl:1 row_mask:0xf bank_mask:0xf bound_ctrl:0
	v_fmac_f32_dpp v118, v86, v158 row_shl:1 row_mask:0xf bank_mask:0xf bound_ctrl:0
	v_fmac_f32_dpp v119, v87, v159 row_shl:1 row_mask:0xf bank_mask:0xf bound_ctrl:0
	v_fmac_f32_dpp v116, v88, -v168 row_shl:1 row_mask:0xf bank_mask:0xf bound_ctrl:0
	v_fmac_f32_dpp v117, v89, -v169 row_shl:1 row_mask:0xf bank_mask:0xf bound_ctrl:0
	v_fmac_f32_dpp v118, v90, -v170 row_shl:1 row_mask:0xf bank_mask:0xf bound_ctrl:0
	v_fmac_f32_dpp v119, v91, -v171 row_shl:1 row_mask:0xf bank_mask:0xf bound_ctrl:0
	v_fmac_f32_dpp v120, v88, v156 row_shl:1 row_mask:0xf bank_mask:0xf bound_ctrl:0
	v_fmac_f32_dpp v121, v89, v157 row_shl:1 row_mask:0xf bank_mask:0xf bound_ctrl:0
	v_fmac_f32_dpp v122, v90, v158 row_shl:1 row_mask:0xf bank_mask:0xf bound_ctrl:0
	v_fmac_f32_dpp v123, v91, v159 row_shl:1 row_mask:0xf bank_mask:0xf bound_ctrl:0
	v_fmac_f32_dpp v120, v84, v168 row_shl:1 row_mask:0xf bank_mask:0xf bound_ctrl:0
	v_fmac_f32_dpp v121, v85, v169 row_shl:1 row_mask:0xf bank_mask:0xf bound_ctrl:0
	v_fmac_f32_dpp v122, v86, v170 row_shl:1 row_mask:0xf bank_mask:0xf bound_ctrl:0
	v_fmac_f32_dpp v123, v87, v171 row_shl:1 row_mask:0xf bank_mask:0xf bound_ctrl:0
	ds_read_b128 v[156:159], v9 offset:128
	ds_read_b128 v[168:171], v9 offset:384
	s_waitcnt lgkmcnt(2)
	v_fmac_f32_dpp v124, v92, v172 row_shl:1 row_mask:0xf bank_mask:0xf bound_ctrl:0
	v_fmac_f32_dpp v125, v93, v173 row_shl:1 row_mask:0xf bank_mask:0xf bound_ctrl:0
	v_fmac_f32_dpp v126, v94, v174 row_shl:1 row_mask:0xf bank_mask:0xf bound_ctrl:0
	v_fmac_f32_dpp v127, v95, v175 row_shl:1 row_mask:0xf bank_mask:0xf bound_ctrl:0
	v_fmac_f32_dpp v124, v96, -v176 row_shl:1 row_mask:0xf bank_mask:0xf bound_ctrl:0
	v_fmac_f32_dpp v125, v97, -v177 row_shl:1 row_mask:0xf bank_mask:0xf bound_ctrl:0
	v_fmac_f32_dpp v126, v98, -v178 row_shl:1 row_mask:0xf bank_mask:0xf bound_ctrl:0
	v_fmac_f32_dpp v127, v99, -v179 row_shl:1 row_mask:0xf bank_mask:0xf bound_ctrl:0
	v_fmac_f32_dpp v128, v96, v172 row_shl:1 row_mask:0xf bank_mask:0xf bound_ctrl:0
	v_fmac_f32_dpp v129, v97, v173 row_shl:1 row_mask:0xf bank_mask:0xf bound_ctrl:0
	v_fmac_f32_dpp v130, v98, v174 row_shl:1 row_mask:0xf bank_mask:0xf bound_ctrl:0
	v_fmac_f32_dpp v131, v99, v175 row_shl:1 row_mask:0xf bank_mask:0xf bound_ctrl:0
	v_fmac_f32_dpp v128, v92, v176 row_shl:1 row_mask:0xf bank_mask:0xf bound_ctrl:0
	v_fmac_f32_dpp v129, v93, v177 row_shl:1 row_mask:0xf bank_mask:0xf bound_ctrl:0
	v_fmac_f32_dpp v130, v94, v178 row_shl:1 row_mask:0xf bank_mask:0xf bound_ctrl:0
	v_fmac_f32_dpp v131, v95, v179 row_shl:1 row_mask:0xf bank_mask:0xf bound_ctrl:0
	ds_read_b128 v[172:175], v9 offset:192
	ds_read_b128 v[176:179], v9 offset:448
	s_waitcnt lgkmcnt(2)
	v_fmac_f32_dpp v140, v100, v156 row_shl:1 row_mask:0xf bank_mask:0xf bound_ctrl:0
	v_fmac_f32_dpp v141, v101, v157 row_shl:1 row_mask:0xf bank_mask:0xf bound_ctrl:0
	v_fmac_f32_dpp v142, v102, v158 row_shl:1 row_mask:0xf bank_mask:0xf bound_ctrl:0
	v_fmac_f32_dpp v143, v103, v159 row_shl:1 row_mask:0xf bank_mask:0xf bound_ctrl:0
	v_fmac_f32_dpp v140, v104, -v168 row_shl:1 row_mask:0xf bank_mask:0xf bound_ctrl:0
	v_fmac_f32_dpp v141, v105, -v169 row_shl:1 row_mask:0xf bank_mask:0xf bound_ctrl:0
	v_fmac_f32_dpp v142, v106, -v170 row_shl:1 row_mask:0xf bank_mask:0xf bound_ctrl:0
	v_fmac_f32_dpp v143, v107, -v171 row_shl:1 row_mask:0xf bank_mask:0xf bound_ctrl:0
	v_fmac_f32_dpp v144, v104, v156 row_shl:1 row_mask:0xf bank_mask:0xf bound_ctrl:0
	v_fmac_f32_dpp v145, v105, v157 row_shl:1 row_mask:0xf bank_mask:0xf bound_ctrl:0
	v_fmac_f32_dpp v146, v106, v158 row_shl:1 row_mask:0xf bank_mask:0xf bound_ctrl:0
	v_fmac_f32_dpp v147, v107, v159 row_shl:1 row_mask:0xf bank_mask:0xf bound_ctrl:0
	v_fmac_f32_dpp v144, v100, v168 row_shl:1 row_mask:0xf bank_mask:0xf bound_ctrl:0
	v_fmac_f32_dpp v145, v101, v169 row_shl:1 row_mask:0xf bank_mask:0xf bound_ctrl:0
	v_fmac_f32_dpp v146, v102, v170 row_shl:1 row_mask:0xf bank_mask:0xf bound_ctrl:0
	v_fmac_f32_dpp v147, v103, v171 row_shl:1 row_mask:0xf bank_mask:0xf bound_ctrl:0
	s_waitcnt lgkmcnt(0)
	v_fmac_f32_dpp v148, v108, v172 row_shl:1 row_mask:0xf bank_mask:0xf bound_ctrl:0
	v_fmac_f32_dpp v149, v109, v173 row_shl:1 row_mask:0xf bank_mask:0xf bound_ctrl:0
	v_fmac_f32_dpp v150, v110, v174 row_shl:1 row_mask:0xf bank_mask:0xf bound_ctrl:0
	v_fmac_f32_dpp v151, v111, v175 row_shl:1 row_mask:0xf bank_mask:0xf bound_ctrl:0
	v_fmac_f32_dpp v148, v112, -v176 row_shl:1 row_mask:0xf bank_mask:0xf bound_ctrl:0
	v_fmac_f32_dpp v149, v113, -v177 row_shl:1 row_mask:0xf bank_mask:0xf bound_ctrl:0
	v_fmac_f32_dpp v150, v114, -v178 row_shl:1 row_mask:0xf bank_mask:0xf bound_ctrl:0
	v_fmac_f32_dpp v151, v115, -v179 row_shl:1 row_mask:0xf bank_mask:0xf bound_ctrl:0
	v_fmac_f32_dpp v152, v112, v172 row_shl:1 row_mask:0xf bank_mask:0xf bound_ctrl:0
	v_fmac_f32_dpp v153, v113, v173 row_shl:1 row_mask:0xf bank_mask:0xf bound_ctrl:0
	v_fmac_f32_dpp v154, v114, v174 row_shl:1 row_mask:0xf bank_mask:0xf bound_ctrl:0
	v_fmac_f32_dpp v155, v115, v175 row_shl:1 row_mask:0xf bank_mask:0xf bound_ctrl:0
	v_fmac_f32_dpp v152, v108, v176 row_shl:1 row_mask:0xf bank_mask:0xf bound_ctrl:0
	v_fmac_f32_dpp v153, v109, v177 row_shl:1 row_mask:0xf bank_mask:0xf bound_ctrl:0
	v_fmac_f32_dpp v154, v110, v178 row_shl:1 row_mask:0xf bank_mask:0xf bound_ctrl:0
	v_fmac_f32_dpp v155, v111, v179 row_shl:1 row_mask:0xf bank_mask:0xf bound_ctrl:0
	s_waitcnt vmcnt(0)
	v_xor_b32_e32 v56, 0x80000000, v56
	v_xor_b32_e32 v57, 0x80000000, v57
	v_xor_b32_e32 v58, 0x80000000, v58
	v_xor_b32_e32 v59, 0x80000000, v59
	v_xor_b32_e32 v64, 0x80000000, v64
	v_xor_b32_e32 v65, 0x80000000, v65
	v_xor_b32_e32 v66, 0x80000000, v66
	v_xor_b32_e32 v67, 0x80000000, v67
	v_xor_b32_e32 v72, 0x80000000, v72
	v_xor_b32_e32 v73, 0x80000000, v73
	v_xor_b32_e32 v74, 0x80000000, v74
	v_xor_b32_e32 v75, 0x80000000, v75
	v_xor_b32_e32 v80, 0x80000000, v80
	v_xor_b32_e32 v81, 0x80000000, v81
	v_xor_b32_e32 v82, 0x80000000, v82
	v_xor_b32_e32 v83, 0x80000000, v83
	s_nop 1
	v_mfma_f32_16x16x4_f32 v[184:187], v84, v52, v[184:187]
	v_mfma_f32_16x16x4_f32 v[192:195], v88, v56, v[192:195]
	v_mfma_f32_16x16x4_f32 v[188:191], v116, v52, v[188:191]
	v_mfma_f32_16x16x4_f32 v[224:227], v120, v56, v[224:227]
	v_mfma_f32_16x16x4_f32 v[184:187], v85, v53, v[184:187]
	v_mfma_f32_16x16x4_f32 v[192:195], v89, v57, v[192:195]
	v_mfma_f32_16x16x4_f32 v[188:191], v117, v53, v[188:191]
	v_mfma_f32_16x16x4_f32 v[224:227], v121, v57, v[224:227]
	v_mfma_f32_16x16x4_f32 v[184:187], v86, v54, v[184:187]
	v_mfma_f32_16x16x4_f32 v[192:195], v90, v58, v[192:195]
	v_mfma_f32_16x16x4_f32 v[188:191], v118, v54, v[188:191]
	v_mfma_f32_16x16x4_f32 v[224:227], v122, v58, v[224:227]
	v_mfma_f32_16x16x4_f32 v[184:187], v87, v55, v[184:187]
	v_mfma_f32_16x16x4_f32 v[192:195], v91, v59, v[192:195]
	v_mfma_f32_16x16x4_f32 v[188:191], v119, v55, v[188:191]
	v_mfma_f32_16x16x4_f32 v[224:227], v123, v59, v[224:227]
	v_mfma_f32_16x16x4_f32 v[184:187], v92, v60, v[184:187]
	v_mfma_f32_16x16x4_f32 v[192:195], v96, v64, v[192:195]
	v_mfma_f32_16x16x4_f32 v[188:191], v124, v60, v[188:191]
	v_mfma_f32_16x16x4_f32 v[224:227], v128, v64, v[224:227]
	v_mfma_f32_16x16x4_f32 v[184:187], v93, v61, v[184:187]
	v_mfma_f32_16x16x4_f32 v[192:195], v97, v65, v[192:195]
	v_mfma_f32_16x16x4_f32 v[188:191], v125, v61, v[188:191]
	v_mfma_f32_16x16x4_f32 v[224:227], v129, v65, v[224:227]
	v_mfma_f32_16x16x4_f32 v[184:187], v94, v62, v[184:187]
	v_mfma_f32_16x16x4_f32 v[192:195], v98, v66, v[192:195]
	v_mfma_f32_16x16x4_f32 v[188:191], v126, v62, v[188:191]
	v_mfma_f32_16x16x4_f32 v[224:227], v130, v66, v[224:227]
	v_mfma_f32_16x16x4_f32 v[184:187], v95, v63, v[184:187]
	v_mfma_f32_16x16x4_f32 v[192:195], v99, v67, v[192:195]
	v_mfma_f32_16x16x4_f32 v[188:191], v127, v63, v[188:191]
	v_mfma_f32_16x16x4_f32 v[224:227], v131, v67, v[224:227]
	v_mfma_f32_16x16x4_f32 v[184:187], v100, v68, v[184:187]
	v_mfma_f32_16x16x4_f32 v[192:195], v104, v72, v[192:195]
	v_mfma_f32_16x16x4_f32 v[188:191], v140, v68, v[188:191]
	v_mfma_f32_16x16x4_f32 v[224:227], v144, v72, v[224:227]
	v_mfma_f32_16x16x4_f32 v[184:187], v101, v69, v[184:187]
	v_mfma_f32_16x16x4_f32 v[192:195], v105, v73, v[192:195]
	v_mfma_f32_16x16x4_f32 v[188:191], v141, v69, v[188:191]
	v_mfma_f32_16x16x4_f32 v[224:227], v145, v73, v[224:227]
	v_mfma_f32_16x16x4_f32 v[184:187], v102, v70, v[184:187]
	v_mfma_f32_16x16x4_f32 v[192:195], v106, v74, v[192:195]
	v_mfma_f32_16x16x4_f32 v[188:191], v142, v70, v[188:191]
	v_mfma_f32_16x16x4_f32 v[224:227], v146, v74, v[224:227]
	v_mfma_f32_16x16x4_f32 v[184:187], v103, v71, v[184:187]
	v_mfma_f32_16x16x4_f32 v[192:195], v107, v75, v[192:195]
	v_mfma_f32_16x16x4_f32 v[188:191], v143, v71, v[188:191]
	v_mfma_f32_16x16x4_f32 v[224:227], v147, v75, v[224:227]
	v_mfma_f32_16x16x4_f32 v[184:187], v108, v76, v[184:187]
	v_mfma_f32_16x16x4_f32 v[192:195], v112, v80, v[192:195]
	v_mfma_f32_16x16x4_f32 v[188:191], v148, v76, v[188:191]
	v_mfma_f32_16x16x4_f32 v[224:227], v152, v80, v[224:227]
	v_mfma_f32_16x16x4_f32 v[184:187], v109, v77, v[184:187]
	v_mfma_f32_16x16x4_f32 v[192:195], v113, v81, v[192:195]
	v_mfma_f32_16x16x4_f32 v[188:191], v149, v77, v[188:191]
	v_mfma_f32_16x16x4_f32 v[224:227], v153, v81, v[224:227]
	v_mfma_f32_16x16x4_f32 v[184:187], v110, v78, v[184:187]
	v_mfma_f32_16x16x4_f32 v[192:195], v114, v82, v[192:195]
	v_mfma_f32_16x16x4_f32 v[188:191], v150, v78, v[188:191]
	v_mfma_f32_16x16x4_f32 v[224:227], v154, v82, v[224:227]
	v_mfma_f32_16x16x4_f32 v[184:187], v111, v79, v[184:187]
	v_mfma_f32_16x16x4_f32 v[192:195], v115, v83, v[192:195]
	v_mfma_f32_16x16x4_f32 v[188:191], v151, v79, v[188:191]
	v_mfma_f32_16x16x4_f32 v[224:227], v155, v83, v[224:227]
	s_cmp_ge_u32 s0, 128
	s_cbranch_scc1 .Ls5b_nofin2
	s_and_b32 s55, s0, 7
	s_cmp_lg_u32 s55, 0
	s_cbranch_scc1 .Ls5b_nofin2
	s_lshr_b32 s55, s0, 3
	s_lshl_b32 s55, s55, 2
	s_add_i32 s55, s55, s32
	s_lshl_b32 s55, s55, 1
	s_add_i32 s55, s55, 1
	s_lshl_b32 s55, s55, 4
	s_add_i32 s55, s55, s6
	s_lshl_b32 s55, s55, 8
	s_add_u32 s48, s92, 0x4000000
	s_addc_u32 s49, s93, 0
	s_add_u32 s48, s48, s55
	s_addc_u32 s49, s49, 0
	s_add_u32 s50, s48, 0x80000
	s_addc_u32 s51, s49, 0
	s_mov_b64 exec, s[52:53]
	global_store_dwordx4 v10, v[84:87], s[48:49] offset:0
	global_store_dwordx4 v10, v[88:91], s[50:51] offset:0
	global_store_dwordx4 v10, v[92:95], s[48:49] offset:64
	global_store_dwordx4 v10, v[96:99], s[50:51] offset:64
	global_store_dwordx4 v10, v[100:103], s[48:49] offset:128
	global_store_dwordx4 v10, v[104:107], s[50:51] offset:128
	global_store_dwordx4 v10, v[108:111], s[48:49] offset:192
	global_store_dwordx4 v10, v[112:115], s[50:51] offset:192
	s_mov_b64 exec, -1
	s_waitcnt vmcnt(0)
.Ls5b_nofin2:
	s_nop 9
	v_add_f32_e32 v184, v184, v192
	v_add_f32_e32 v185, v185, v193
	v_add_f32_e32 v186, v186, v194
	v_add_f32_e32 v187, v187, v195
	v_add_f32_e32 v188, v188, v224
	v_add_f32_e32 v189, v189, v225
	v_add_f32_e32 v190, v190, v226
	v_add_f32_e32 v191, v191, v227
	global_load_dword v60, v16, s[20:21]
	global_load_dword v52, v11, s[8:9] offset:0
	global_load_dword v53, v11, s[8:9] offset:2048
	global_load_dword v54, v12, s[8:9] offset:0
	global_load_dword v55, v12, s[8:9] offset:2048
	global_load_dword v56, v11, s[8:9] offset:1024
	global_load_dword v57, v11, s[8:9] offset:3072
	global_load_dword v58, v12, s[8:9] offset:1024
	global_load_dword v59, v12, s[8:9] offset:3072
	s_waitcnt vmcnt(8)
	s_waitcnt vmcnt(7)
	v_fmac_f32_e32 v184, v52, v60
	s_waitcnt vmcnt(6)
	v_fmac_f32_e32 v185, v53, v60
	s_waitcnt vmcnt(5)
	v_fmac_f32_e32 v186, v54, v60
	s_waitcnt vmcnt(4)
	v_fmac_f32_e32 v187, v55, v60
	s_waitcnt vmcnt(3)
	v_fmac_f32_e32 v188, v56, v60
	s_waitcnt vmcnt(2)
	v_fmac_f32_e32 v189, v57, v60
	s_waitcnt vmcnt(1)
	v_fmac_f32_e32 v190, v58, v60
	s_waitcnt vmcnt(0)
	v_fmac_f32_e32 v191, v59, v60
	v_cvt_pk_bf16_f32 v192, v184, v184
	v_cvt_pk_bf16_f32 v193, v185, v185
	v_cvt_pk_bf16_f32 v194, v186, v186
	v_cvt_pk_bf16_f32 v195, v187, v187
	v_cvt_pk_bf16_f32 v224, v188, v188
	v_cvt_pk_bf16_f32 v225, v189, v189
	v_cvt_pk_bf16_f32 v226, v190, v190
	v_cvt_pk_bf16_f32 v227, v191, v191
	global_store_short v13, v192, s[44:45] offset:0
	global_store_short v13, v193, s[44:45] offset:1024
	global_store_short v13, v194, s[44:45] offset:2048
	global_store_short v13, v195, s[44:45] offset:3072
	global_store_short v13, v224, s[44:45] offset:512
	global_store_short v13, v225, s[44:45] offset:1536
	global_store_short v13, v226, s[44:45] offset:2560
	global_store_short v13, v227, s[44:45] offset:3584
	s_movk_i32 s33, 0x1ff
	v_readlane_b32 s4, v249, 11
	v_readlane_b32 s5, v249, 12
	v_readlane_b32 s6, v249, 13
	v_readlane_b32 s7, v249, 14
	v_readlane_b32 s8, v249, 15
	v_readlane_b32 s9, v249, 16
	v_readlane_b32 s10, v249, 17
	v_readlane_b32 s11, v249, 18
	v_readlane_b32 s12, v249, 19
	v_readlane_b32 s13, v249, 20
	v_readlane_b32 s14, v249, 21
	v_readlane_b32 s15, v249, 22
	v_readlane_b32 s16, v249, 23
	v_readlane_b32 s17, v249, 24
	v_readlane_b32 s18, v249, 25
	v_readlane_b32 s19, v249, 26
	s_branch .LBB0_408

.LBB0_608:
	s_and_b64 vcc, exec, s[0:1]
	s_cbranch_vccz .LBB0_618
	s_add_i32 s0, s86, 0xffffff00
	v_lshrrev_b32_e32 v0, 6, v135
	v_readlane_b32 s32, v249, 47
	v_readfirstlane_b32 s4, v0
	s_nop 3
	v_and_b32_e32 v2, 63, v135
	v_lshrrev_b32_e32 v3, 4, v2
	v_and_b32_e32 v4, 15, v2
	v_lshlrev_b32_e32 v5, 11, v4
	v_lshl_add_u32 v5, v3, 4, v5
	v_lshlrev_b32_e32 v6, 4, v4
	v_lshl_add_u32 v6, v3, 11, v6
	v_lshlrev_b32_e32 v7, 3, v2
	v_lshlrev_b32_e32 v10, 5, v3
	s_mul_i32 s54, s4, 0xa00
	s_add_i32 s54, s54, 0x18400
	v_lshl_add_u32 v8, v2, 2, s54
	v_lshl_add_u32 v9, v3, 4, s54
	s_mov_b32 s52, 0x00010001
	s_mov_b32 s53, 0x00010001
	s_lshl_b32 s6, s4, 1
	s_lshl_b32 s55, s0, 15
	s_lshl_b32 s56, s6, 6
	s_add_u32 s55, s55, s56
	s_add_u32 s8, s94, 0x8a40000
	s_addc_u32 s9, s95, 0
	s_add_u32 s8, s8, s55
	s_addc_u32 s9, s9, 0
	global_load_dwordx4 v[172:175], v5, s[8:9] offset:0
	global_load_dwordx4 v[176:179], v5, s[8:9] offset:1024
	s_mov_b32 s10, 0x80008000
	s_mov_b32 s11, 0x80008000
	s_add_i32 s55, s6, 0
	s_lshl_b32 s56, s55, 13
	s_add_u32 s12, s94, 0x12d96000
	s_addc_u32 s13, s95, 0
	s_add_u32 s12, s12, s56
	s_addc_u32 s13, s13, 0
	s_lshl_b32 s56, s55, 9
	s_add_u32 s38, s94, 0x12d92000
	s_addc_u32 s39, s95, 0
	s_add_u32 s38, s38, s56
	s_addc_u32 s39, s39, 0
	s_lshl_b32 s56, s0, 5
	s_lshl_b32 s55, s6, 1
	s_add_i32 s56, s56, s55
	s_add_i32 s56, s56, 0
	s_lshl_b32 s56, s56, 9
	s_add_u32 s36, s94, 0x12dd6000
	s_addc_u32 s37, s95, 0
	s_add_u32 s36, s36, s56
	s_addc_u32 s37, s37, 0
	global_load_dwordx2 v[2:3], v7, s[38:39]
	global_load_dwordx4 v[12:15], v6, s[12:13] offset:0
	global_load_dwordx4 v[16:19], v6, s[12:13] offset:1024
	global_load_dwordx4 v[20:23], v6, s[12:13] offset:256
	global_load_dwordx4 v[24:27], v6, s[12:13] offset:1280
	global_load_dwordx4 v[28:31], v6, s[12:13] offset:512
	global_load_dwordx4 v[32:35], v6, s[12:13] offset:1536
	global_load_dwordx4 v[36:39], v6, s[12:13] offset:768
	global_load_dwordx4 v[40:43], v6, s[12:13] offset:1792
	s_waitcnt vmcnt(8)
	ds_write_b32 v8, v2 offset:0
	ds_write_b32 v8, v3 offset:256
	v_mul_f32_e32 v168, v3, v3
	v_mul_f32_e32 v169, v2, v3
	v_fma_f32 v2, v2, v2, -v168
	v_add_f32_e32 v3, v169, v169
	ds_write_b32 v8, v2 offset:512
	ds_write_b32 v8, v3 offset:768
	v_mul_f32_e32 v168, v3, v3
	v_mul_f32_e32 v169, v2, v3
	v_fma_f32 v2, v2, v2, -v168
	v_add_f32_e32 v3, v169, v169
	ds_write_b32 v8, v2 offset:1024
	ds_write_b32 v8, v3 offset:1280
	v_mul_f32_e32 v168, v3, v3
	v_mul_f32_e32 v169, v2, v3
	v_fma_f32 v2, v2, v2, -v168
	v_add_f32_e32 v3, v169, v169
	ds_write_b32 v8, v2 offset:1536
	ds_write_b32 v8, v3 offset:1792
	v_mul_f32_e32 v168, v3, v3
	v_mul_f32_e32 v169, v2, v3
	v_fma_f32 v2, v2, v2, -v168
	v_add_f32_e32 v3, v169, v169
	ds_write_b32 v8, v2 offset:2048
	ds_write_b32 v8, v3 offset:2304
	s_waitcnt lgkmcnt(0)
	s_waitcnt vmcnt(7)
	v_mfma_f32_16x16x4_f32 v[44:47], v12, v172, 0
	v_mfma_f32_16x16x4_f32 v[52:55], v13, v172, 0
	v_mfma_f32_16x16x4_f32 v[80:83], v12, v176, 0
	v_mfma_f32_16x16x4_f32 v[84:87], v13, v176, 0
	s_waitcnt vmcnt(5)
	v_mfma_f32_16x16x4_f32 v[56:59], v20, v172, 0
	v_mfma_f32_16x16x4_f32 v[60:63], v21, v172, 0
	v_mfma_f32_16x16x4_f32 v[112:115], v20, v176, 0
	v_mfma_f32_16x16x4_f32 v[116:119], v21, v176, 0
	s_waitcnt vmcnt(3)
	v_mfma_f32_16x16x4_f32 v[64:67], v28, v172, 0
	v_mfma_f32_16x16x4_f32 v[68:71], v29, v172, 0
	v_mfma_f32_16x16x4_f32 v[120:123], v28, v176, 0
	v_mfma_f32_16x16x4_f32 v[124:127], v29, v176, 0
	s_waitcnt vmcnt(1)
	v_mfma_f32_16x16x4_f32 v[72:75], v36, v172, 0
	v_mfma_f32_16x16x4_f32 v[76:79], v37, v172, 0
	v_mfma_f32_16x16x4_f32 v[128:131], v36, v176, 0
	v_mfma_f32_16x16x4_f32 v[140:143], v37, v176, 0
	v_mfma_f32_16x16x4_f32 v[44:47], v14, v173, v[44:47]
	v_mfma_f32_16x16x4_f32 v[52:55], v15, v173, v[52:55]
	v_mfma_f32_16x16x4_f32 v[80:83], v14, v177, v[80:83]
	v_mfma_f32_16x16x4_f32 v[84:87], v15, v177, v[84:87]
	v_mfma_f32_16x16x4_f32 v[56:59], v22, v173, v[56:59]
	v_mfma_f32_16x16x4_f32 v[60:63], v23, v173, v[60:63]
	v_mfma_f32_16x16x4_f32 v[112:115], v22, v177, v[112:115]
	v_mfma_f32_16x16x4_f32 v[116:119], v23, v177, v[116:119]
	v_mfma_f32_16x16x4_f32 v[64:67], v30, v173, v[64:67]
	v_mfma_f32_16x16x4_f32 v[68:71], v31, v173, v[68:71]
	v_mfma_f32_16x16x4_f32 v[120:123], v30, v177, v[120:123]
	v_mfma_f32_16x16x4_f32 v[124:127], v31, v177, v[124:127]
	v_mfma_f32_16x16x4_f32 v[72:75], v38, v173, v[72:75]
	v_mfma_f32_16x16x4_f32 v[76:79], v39, v173, v[76:79]
	v_mfma_f32_16x16x4_f32 v[128:131], v38, v177, v[128:131]
	v_mfma_f32_16x16x4_f32 v[140:143], v39, v177, v[140:143]
	v_mfma_f32_16x16x4_f32 v[44:47], v16, v174, v[44:47]
	v_mfma_f32_16x16x4_f32 v[52:55], v17, v174, v[52:55]
	v_mfma_f32_16x16x4_f32 v[80:83], v16, v178, v[80:83]
	v_mfma_f32_16x16x4_f32 v[84:87], v17, v178, v[84:87]
	v_mfma_f32_16x16x4_f32 v[56:59], v24, v174, v[56:59]
	v_mfma_f32_16x16x4_f32 v[60:63], v25, v174, v[60:63]
	v_mfma_f32_16x16x4_f32 v[112:115], v24, v178, v[112:115]
	v_mfma_f32_16x16x4_f32 v[116:119], v25, v178, v[116:119]
	v_mfma_f32_16x16x4_f32 v[64:67], v32, v174, v[64:67]
	v_mfma_f32_16x16x4_f32 v[68:71], v33, v174, v[68:71]
	v_mfma_f32_16x16x4_f32 v[120:123], v32, v178, v[120:123]
	v_mfma_f32_16x16x4_f32 v[124:127], v33, v178, v[124:127]
	s_waitcnt vmcnt(0)
	v_mfma_f32_16x16x4_f32 v[72:75], v40, v174, v[72:75]
	v_mfma_f32_16x16x4_f32 v[76:79], v41, v174, v[76:79]
	v_mfma_f32_16x16x4_f32 v[128:131], v40, v178, v[128:131]
	v_mfma_f32_16x16x4_f32 v[140:143], v41, v178, v[140:143]
	v_mfma_f32_16x16x4_f32 v[44:47], v18, v175, v[44:47]
	v_mfma_f32_16x16x4_f32 v[52:55], v19, v175, v[52:55]
	v_mfma_f32_16x16x4_f32 v[80:83], v18, v179, v[80:83]
	v_mfma_f32_16x16x4_f32 v[84:87], v19, v179, v[84:87]
	v_mfma_f32_16x16x4_f32 v[56:59], v26, v175, v[56:59]
	v_mfma_f32_16x16x4_f32 v[60:63], v27, v175, v[60:63]
	v_mfma_f32_16x16x4_f32 v[112:115], v26, v179, v[112:115]
	v_mfma_f32_16x16x4_f32 v[116:119], v27, v179, v[116:119]
	v_mfma_f32_16x16x4_f32 v[64:67], v34, v175, v[64:67]
	v_mfma_f32_16x16x4_f32 v[68:71], v35, v175, v[68:71]
	v_mfma_f32_16x16x4_f32 v[120:123], v34, v179, v[120:123]
	v_mfma_f32_16x16x4_f32 v[124:127], v35, v179, v[124:127]
	v_mfma_f32_16x16x4_f32 v[72:75], v42, v175, v[72:75]
	v_mfma_f32_16x16x4_f32 v[76:79], v43, v175, v[76:79]
	v_mfma_f32_16x16x4_f32 v[128:131], v42, v179, v[128:131]
	v_mfma_f32_16x16x4_f32 v[140:143], v43, v179, v[140:143]
	s_nop 9
	ds_read_b128 v[144:147], v9 offset:0
	ds_read_b128 v[148:151], v9 offset:256
	ds_read_b128 v[152:155], v9 offset:64
	ds_read_b128 v[156:159], v9 offset:320
	s_waitcnt lgkmcnt(2)
	v_fmac_f32_e32 v80, v144, v44
	v_fmac_f32_e32 v81, v145, v45
	v_fmac_f32_e32 v82, v146, v46
	v_fmac_f32_e32 v83, v147, v47
	v_fma_f32 v80, -v148, v52, v80
	v_fma_f32 v81, -v149, v53, v81
	v_fma_f32 v82, -v150, v54, v82
	v_fma_f32 v83, -v151, v55, v83
	v_fmac_f32_e32 v84, v144, v52
	v_fmac_f32_e32 v85, v145, v53
	v_fmac_f32_e32 v86, v146, v54
	v_fmac_f32_e32 v87, v147, v55
	v_fmac_f32_e32 v84, v148, v44
	v_fmac_f32_e32 v85, v149, v45
	v_fmac_f32_e32 v86, v150, v46
	v_fmac_f32_e32 v87, v151, v47
	ds_read_b128 v[144:147], v9 offset:128
	ds_read_b128 v[148:151], v9 offset:384
	s_waitcnt lgkmcnt(2)
	v_fmac_f32_e32 v112, v152, v56
	v_fmac_f32_e32 v113, v153, v57
	v_fmac_f32_e32 v114, v154, v58
	v_fmac_f32_e32 v115, v155, v59
	v_fma_f32 v112, -v156, v60, v112
	v_fma_f32 v113, -v157, v61, v113
	v_fma_f32 v114, -v158, v62, v114
	v_fma_f32 v115, -v159, v63, v115
	v_fmac_f32_e32 v116, v152, v60
	v_fmac_f32_e32 v117, v153, v61
	v_fmac_f32_e32 v118, v154, v62
	v_fmac_f32_e32 v119, v155, v63
	v_fmac_f32_e32 v116, v156, v56
	v_fmac_f32_e32 v117, v157, v57
	v_fmac_f32_e32 v118, v158, v58
	v_fmac_f32_e32 v119, v159, v59
	ds_read_b128 v[152:155], v9 offset:192
	ds_read_b128 v[156:159], v9 offset:448
	s_waitcnt lgkmcnt(2)
	v_fmac_f32_e32 v120, v144, v64
	v_fmac_f32_e32 v121, v145, v65
	v_fmac_f32_e32 v122, v146, v66
	v_fmac_f32_e32 v123, v147, v67
	v_fma_f32 v120, -v148, v68, v120
	v_fma_f32 v121, -v149, v69, v121
	v_fma_f32 v122, -v150, v70, v122
	v_fma_f32 v123, -v151, v71, v123
	v_fmac_f32_e32 v124, v144, v68
	v_fmac_f32_e32 v125, v145, v69
	v_fmac_f32_e32 v126, v146, v70
	v_fmac_f32_e32 v127, v147, v71
	v_fmac_f32_e32 v124, v148, v64
	v_fmac_f32_e32 v125, v149, v65
	v_fmac_f32_e32 v126, v150, v66
	v_fmac_f32_e32 v127, v151, v67
	s_waitcnt lgkmcnt(0)
	v_fmac_f32_e32 v128, v152, v72
	v_fmac_f32_e32 v129, v153, v73
	v_fmac_f32_e32 v130, v154, v74
	v_fmac_f32_e32 v131, v155, v75
	v_fma_f32 v128, -v156, v76, v128
	v_fma_f32 v129, -v157, v77, v129
	v_fma_f32 v130, -v158, v78, v130
	v_fma_f32 v131, -v159, v79, v131
	v_fmac_f32_e32 v140, v152, v76
	v_fmac_f32_e32 v141, v153, v77
	v_fmac_f32_e32 v142, v154, v78
	v_fmac_f32_e32 v143, v155, v79
	v_fmac_f32_e32 v140, v156, v72
	v_fmac_f32_e32 v141, v157, v73
	v_fmac_f32_e32 v142, v158, v74
	v_fmac_f32_e32 v143, v159, v75
	ds_read_b128 v[144:147], v9 offset:512
	ds_read_b128 v[148:151], v9 offset:768
	ds_read_b128 v[152:155], v9 offset:576
	ds_read_b128 v[156:159], v9 offset:832
	s_waitcnt lgkmcnt(2)
	v_mov_b32_e32 v168, v80
	v_mov_b32_e32 v169, v81
	v_mov_b32_e32 v170, v82
	v_mov_b32_e32 v171, v83
	s_nop 1
	v_fmac_f32_dpp v80, v80, v144 row_shr:1 row_mask:0xf bank_mask:0xf bound_ctrl:0
	v_fmac_f32_dpp v81, v81, v145 row_shr:1 row_mask:0xf bank_mask:0xf bound_ctrl:0
	v_fmac_f32_dpp v82, v82, v146 row_shr:1 row_mask:0xf bank_mask:0xf bound_ctrl:0
	v_fmac_f32_dpp v83, v83, v147 row_shr:1 row_mask:0xf bank_mask:0xf bound_ctrl:0
	v_fmac_f32_dpp v80, v84, -v148 row_shr:1 row_mask:0xf bank_mask:0xf bound_ctrl:0
	v_fmac_f32_dpp v81, v85, -v149 row_shr:1 row_mask:0xf bank_mask:0xf bound_ctrl:0
	v_fmac_f32_dpp v82, v86, -v150 row_shr:1 row_mask:0xf bank_mask:0xf bound_ctrl:0
	v_fmac_f32_dpp v83, v87, -v151 row_shr:1 row_mask:0xf bank_mask:0xf bound_ctrl:0
	v_fmac_f32_dpp v84, v84, v144 row_shr:1 row_mask:0xf bank_mask:0xf bound_ctrl:0
	v_fmac_f32_dpp v85, v85, v145 row_shr:1 row_mask:0xf bank_mask:0xf bound_ctrl:0
	v_fmac_f32_dpp v86, v86, v146 row_shr:1 row_mask:0xf bank_mask:0xf bound_ctrl:0
	v_fmac_f32_dpp v87, v87, v147 row_shr:1 row_mask:0xf bank_mask:0xf bound_ctrl:0
	v_fmac_f32_dpp v84, v168, v148 row_shr:1 row_mask:0xf bank_mask:0xf bound_ctrl:0
	v_fmac_f32_dpp v85, v169, v149 row_shr:1 row_mask:0xf bank_mask:0xf bound_ctrl:0
	v_fmac_f32_dpp v86, v170, v150 row_shr:1 row_mask:0xf bank_mask:0xf bound_ctrl:0
	v_fmac_f32_dpp v87, v171, v151 row_shr:1 row_mask:0xf bank_mask:0xf bound_ctrl:0
	ds_read_b128 v[144:147], v9 offset:640
	ds_read_b128 v[148:151], v9 offset:896
	s_waitcnt lgkmcnt(2)
	v_mov_b32_e32 v168, v112
	v_mov_b32_e32 v169, v113
	v_mov_b32_e32 v170, v114
	v_mov_b32_e32 v171, v115
	v_fmac_f32_dpp v112, v112, v152 row_shr:1 row_mask:0xf bank_mask:0xf bound_ctrl:0
	v_fmac_f32_dpp v113, v113, v153 row_shr:1 row_mask:0xf bank_mask:0xf bound_ctrl:0
	v_fmac_f32_dpp v114, v114, v154 row_shr:1 row_mask:0xf bank_mask:0xf bound_ctrl:0
	v_fmac_f32_dpp v115, v115, v155 row_shr:1 row_mask:0xf bank_mask:0xf bound_ctrl:0
	v_fmac_f32_dpp v112, v116, -v156 row_shr:1 row_mask:0xf bank_mask:0xf bound_ctrl:0
	v_fmac_f32_dpp v113, v117, -v157 row_shr:1 row_mask:0xf bank_mask:0xf bound_ctrl:0
	v_fmac_f32_dpp v114, v118, -v158 row_shr:1 row_mask:0xf bank_mask:0xf bound_ctrl:0
	v_fmac_f32_dpp v115, v119, -v159 row_shr:1 row_mask:0xf bank_mask:0xf bound_ctrl:0
	v_fmac_f32_dpp v116, v116, v152 row_shr:1 row_mask:0xf bank_mask:0xf bound_ctrl:0
	v_fmac_f32_dpp v117, v117, v153 row_shr:1 row_mask:0xf bank_mask:0xf bound_ctrl:0
	v_fmac_f32_dpp v118, v118, v154 row_shr:1 row_mask:0xf bank_mask:0xf bound_ctrl:0
	v_fmac_f32_dpp v119, v119, v155 row_shr:1 row_mask:0xf bank_mask:0xf bound_ctrl:0
	v_fmac_f32_dpp v116, v168, v156 row_shr:1 row_mask:0xf bank_mask:0xf bound_ctrl:0
	v_fmac_f32_dpp v117, v169, v157 row_shr:1 row_mask:0xf bank_mask:0xf bound_ctrl:0
	v_fmac_f32_dpp v118, v170, v158 row_shr:1 row_mask:0xf bank_mask:0xf bound_ctrl:0
	v_fmac_f32_dpp v119, v171, v159 row_shr:1 row_mask:0xf bank_mask:0xf bound_ctrl:0
	ds_read_b128 v[152:155], v9 offset:704
	ds_read_b128 v[156:159], v9 offset:960
	s_waitcnt lgkmcnt(2)
	v_mov_b32_e32 v168, v120
	v_mov_b32_e32 v169, v121
	v_mov_b32_e32 v170, v122
	v_mov_b32_e32 v171, v123
	v_fmac_f32_dpp v120, v120, v144 row_shr:1 row_mask:0xf bank_mask:0xf bound_ctrl:0
	v_fmac_f32_dpp v121, v121, v145 row_shr:1 row_mask:0xf bank_mask:0xf bound_ctrl:0
	v_fmac_f32_dpp v122, v122, v146 row_shr:1 row_mask:0xf bank_mask:0xf bound_ctrl:0
	v_fmac_f32_dpp v123, v123, v147 row_shr:1 row_mask:0xf bank_mask:0xf bound_ctrl:0
	v_fmac_f32_dpp v120, v124, -v148 row_shr:1 row_mask:0xf bank_mask:0xf bound_ctrl:0
	v_fmac_f32_dpp v121, v125, -v149 row_shr:1 row_mask:0xf bank_mask:0xf bound_ctrl:0
	v_fmac_f32_dpp v122, v126, -v150 row_shr:1 row_mask:0xf bank_mask:0xf bound_ctrl:0
	v_fmac_f32_dpp v123, v127, -v151 row_shr:1 row_mask:0xf bank_mask:0xf bound_ctrl:0
	v_fmac_f32_dpp v124, v124, v144 row_shr:1 row_mask:0xf bank_mask:0xf bound_ctrl:0
	v_fmac_f32_dpp v125, v125, v145 row_shr:1 row_mask:0xf bank_mask:0xf bound_ctrl:0
	v_fmac_f32_dpp v126, v126, v146 row_shr:1 row_mask:0xf bank_mask:0xf bound_ctrl:0
	v_fmac_f32_dpp v127, v127, v147 row_shr:1 row_mask:0xf bank_mask:0xf bound_ctrl:0
	v_fmac_f32_dpp v124, v168, v148 row_shr:1 row_mask:0xf bank_mask:0xf bound_ctrl:0
	v_fmac_f32_dpp v125, v169, v149 row_shr:1 row_mask:0xf bank_mask:0xf bound_ctrl:0
	v_fmac_f32_dpp v126, v170, v150 row_shr:1 row_mask:0xf bank_mask:0xf bound_ctrl:0
	v_fmac_f32_dpp v127, v171, v151 row_shr:1 row_mask:0xf bank_mask:0xf bound_ctrl:0
	ds_read_b128 v[144:147], v9 offset:1024
	ds_read_b128 v[148:151], v9 offset:1280
	s_waitcnt lgkmcnt(2)
	v_mov_b32_e32 v168, v128
	v_mov_b32_e32 v169, v129
	v_mov_b32_e32 v170, v130
	v_mov_b32_e32 v171, v131
	v_fmac_f32_dpp v128, v128, v152 row_shr:1 row_mask:0xf bank_mask:0xf bound_ctrl:0
	v_fmac_f32_dpp v129, v129, v153 row_shr:1 row_mask:0xf bank_mask:0xf bound_ctrl:0
	v_fmac_f32_dpp v130, v130, v154 row_shr:1 row_mask:0xf bank_mask:0xf bound_ctrl:0
	v_fmac_f32_dpp v131, v131, v155 row_shr:1 row_mask:0xf bank_mask:0xf bound_ctrl:0
	v_fmac_f32_dpp v128, v140, -v156 row_shr:1 row_mask:0xf bank_mask:0xf bound_ctrl:0
	v_fmac_f32_dpp v129, v141, -v157 row_shr:1 row_mask:0xf bank_mask:0xf bound_ctrl:0
	v_fmac_f32_dpp v130, v142, -v158 row_shr:1 row_mask:0xf bank_mask:0xf bound_ctrl:0
	v_fmac_f32_dpp v131, v143, -v159 row_shr:1 row_mask:0xf bank_mask:0xf bound_ctrl:0
	v_fmac_f32_dpp v140, v140, v152 row_shr:1 row_mask:0xf bank_mask:0xf bound_ctrl:0
	v_fmac_f32_dpp v141, v141, v153 row_shr:1 row_mask:0xf bank_mask:0xf bound_ctrl:0
	v_fmac_f32_dpp v142, v142, v154 row_shr:1 row_mask:0xf bank_mask:0xf bound_ctrl:0
	v_fmac_f32_dpp v143, v143, v155 row_shr:1 row_mask:0xf bank_mask:0xf bound_ctrl:0
	v_fmac_f32_dpp v140, v168, v156 row_shr:1 row_mask:0xf bank_mask:0xf bound_ctrl:0
	v_fmac_f32_dpp v141, v169, v157 row_shr:1 row_mask:0xf bank_mask:0xf bound_ctrl:0
	v_fmac_f32_dpp v142, v170, v158 row_shr:1 row_mask:0xf bank_mask:0xf bound_ctrl:0
	v_fmac_f32_dpp v143, v171, v159 row_shr:1 row_mask:0xf bank_mask:0xf bound_ctrl:0
	ds_read_b128 v[152:155], v9 offset:1088
	ds_read_b128 v[156:159], v9 offset:1344
	s_waitcnt lgkmcnt(2)
	v_mov_b32_e32 v168, v80
	v_mov_b32_e32 v169, v81
	v_mov_b32_e32 v170, v82
	v_mov_b32_e32 v171, v83
	v_fmac_f32_dpp v80, v80, v144 row_shr:2 row_mask:0xf bank_mask:0xf bound_ctrl:0
	v_fmac_f32_dpp v81, v81, v145 row_shr:2 row_mask:0xf bank_mask:0xf bound_ctrl:0
	v_fmac_f32_dpp v82, v82, v146 row_shr:2 row_mask:0xf bank_mask:0xf bound_ctrl:0
	v_fmac_f32_dpp v83, v83, v147 row_shr:2 row_mask:0xf bank_mask:0xf bound_ctrl:0
	v_fmac_f32_dpp v80, v84, -v148 row_shr:2 row_mask:0xf bank_mask:0xf bound_ctrl:0
	v_fmac_f32_dpp v81, v85, -v149 row_shr:2 row_mask:0xf bank_mask:0xf bound_ctrl:0
	v_fmac_f32_dpp v82, v86, -v150 row_shr:2 row_mask:0xf bank_mask:0xf bound_ctrl:0
	v_fmac_f32_dpp v83, v87, -v151 row_shr:2 row_mask:0xf bank_mask:0xf bound_ctrl:0
	v_fmac_f32_dpp v84, v84, v144 row_shr:2 row_mask:0xf bank_mask:0xf bound_ctrl:0
	v_fmac_f32_dpp v85, v85, v145 row_shr:2 row_mask:0xf bank_mask:0xf bound_ctrl:0
	v_fmac_f32_dpp v86, v86, v146 row_shr:2 row_mask:0xf bank_mask:0xf bound_ctrl:0
	v_fmac_f32_dpp v87, v87, v147 row_shr:2 row_mask:0xf bank_mask:0xf bound_ctrl:0
	v_fmac_f32_dpp v84, v168, v148 row_shr:2 row_mask:0xf bank_mask:0xf bound_ctrl:0
	v_fmac_f32_dpp v85, v169, v149 row_shr:2 row_mask:0xf bank_mask:0xf bound_ctrl:0
	v_fmac_f32_dpp v86, v170, v150 row_shr:2 row_mask:0xf bank_mask:0xf bound_ctrl:0
	v_fmac_f32_dpp v87, v171, v151 row_shr:2 row_mask:0xf bank_mask:0xf bound_ctrl:0
	ds_read_b128 v[144:147], v9 offset:1152
	ds_read_b128 v[148:151], v9 offset:1408
	s_waitcnt lgkmcnt(2)
	v_mov_b32_e32 v168, v112
	v_mov_b32_e32 v169, v113
	v_mov_b32_e32 v170, v114
	v_mov_b32_e32 v171, v115
	v_fmac_f32_dpp v112, v112, v152 row_shr:2 row_mask:0xf bank_mask:0xf bound_ctrl:0
	v_fmac_f32_dpp v113, v113, v153 row_shr:2 row_mask:0xf bank_mask:0xf bound_ctrl:0
	v_fmac_f32_dpp v114, v114, v154 row_shr:2 row_mask:0xf bank_mask:0xf bound_ctrl:0
	v_fmac_f32_dpp v115, v115, v155 row_shr:2 row_mask:0xf bank_mask:0xf bound_ctrl:0
	v_fmac_f32_dpp v112, v116, -v156 row_shr:2 row_mask:0xf bank_mask:0xf bound_ctrl:0
	v_fmac_f32_dpp v113, v117, -v157 row_shr:2 row_mask:0xf bank_mask:0xf bound_ctrl:0
	v_fmac_f32_dpp v114, v118, -v158 row_shr:2 row_mask:0xf bank_mask:0xf bound_ctrl:0
	v_fmac_f32_dpp v115, v119, -v159 row_shr:2 row_mask:0xf bank_mask:0xf bound_ctrl:0
	v_fmac_f32_dpp v116, v116, v152 row_shr:2 row_mask:0xf bank_mask:0xf bound_ctrl:0
	v_fmac_f32_dpp v117, v117, v153 row_shr:2 row_mask:0xf bank_mask:0xf bound_ctrl:0
	v_fmac_f32_dpp v118, v118, v154 row_shr:2 row_mask:0xf bank_mask:0xf bound_ctrl:0
	v_fmac_f32_dpp v119, v119, v155 row_shr:2 row_mask:0xf bank_mask:0xf bound_ctrl:0
	v_fmac_f32_dpp v116, v168, v156 row_shr:2 row_mask:0xf bank_mask:0xf bound_ctrl:0
	v_fmac_f32_dpp v117, v169, v157 row_shr:2 row_mask:0xf bank_mask:0xf bound_ctrl:0
	v_fmac_f32_dpp v118, v170, v158 row_shr:2 row_mask:0xf bank_mask:0xf bound_ctrl:0
	v_fmac_f32_dpp v119, v171, v159 row_shr:2 row_mask:0xf bank_mask:0xf bound_ctrl:0
	ds_read_b128 v[152:155], v9 offset:1216
	ds_read_b128 v[156:159], v9 offset:1472
	s_waitcnt lgkmcnt(2)
	v_mov_b32_e32 v168, v120
	v_mov_b32_e32 v169, v121
	v_mov_b32_e32 v170, v122
	v_mov_b32_e32 v171, v123
	v_fmac_f32_dpp v120, v120, v144 row_shr:2 row_mask:0xf bank_mask:0xf bound_ctrl:0
	v_fmac_f32_dpp v121, v121, v145 row_shr:2 row_mask:0xf bank_mask:0xf bound_ctrl:0
	v_fmac_f32_dpp v122, v122, v146 row_shr:2 row_mask:0xf bank_mask:0xf bound_ctrl:0
	v_fmac_f32_dpp v123, v123, v147 row_shr:2 row_mask:0xf bank_mask:0xf bound_ctrl:0
	v_fmac_f32_dpp v120, v124, -v148 row_shr:2 row_mask:0xf bank_mask:0xf bound_ctrl:0
	v_fmac_f32_dpp v121, v125, -v149 row_shr:2 row_mask:0xf bank_mask:0xf bound_ctrl:0
	v_fmac_f32_dpp v122, v126, -v150 row_shr:2 row_mask:0xf bank_mask:0xf bound_ctrl:0
	v_fmac_f32_dpp v123, v127, -v151 row_shr:2 row_mask:0xf bank_mask:0xf bound_ctrl:0
	v_fmac_f32_dpp v124, v124, v144 row_shr:2 row_mask:0xf bank_mask:0xf bound_ctrl:0
	v_fmac_f32_dpp v125, v125, v145 row_shr:2 row_mask:0xf bank_mask:0xf bound_ctrl:0
	v_fmac_f32_dpp v126, v126, v146 row_shr:2 row_mask:0xf bank_mask:0xf bound_ctrl:0
	v_fmac_f32_dpp v127, v127, v147 row_shr:2 row_mask:0xf bank_mask:0xf bound_ctrl:0
	v_fmac_f32_dpp v124, v168, v148 row_shr:2 row_mask:0xf bank_mask:0xf bound_ctrl:0
	v_fmac_f32_dpp v125, v169, v149 row_shr:2 row_mask:0xf bank_mask:0xf bound_ctrl:0
	v_fmac_f32_dpp v126, v170, v150 row_shr:2 row_mask:0xf bank_mask:0xf bound_ctrl:0
	v_fmac_f32_dpp v127, v171, v151 row_shr:2 row_mask:0xf bank_mask:0xf bound_ctrl:0
	ds_read_b128 v[144:147], v9 offset:1536
	ds_read_b128 v[148:151], v9 offset:1792
	s_waitcnt lgkmcnt(2)
	v_mov_b32_e32 v168, v128
	v_mov_b32_e32 v169, v129
	v_mov_b32_e32 v170, v130
	v_mov_b32_e32 v171, v131
	v_fmac_f32_dpp v128, v128, v152 row_shr:2 row_mask:0xf bank_mask:0xf bound_ctrl:0
	v_fmac_f32_dpp v129, v129, v153 row_shr:2 row_mask:0xf bank_mask:0xf bound_ctrl:0
	v_fmac_f32_dpp v130, v130, v154 row_shr:2 row_mask:0xf bank_mask:0xf bound_ctrl:0
	v_fmac_f32_dpp v131, v131, v155 row_shr:2 row_mask:0xf bank_mask:0xf bound_ctrl:0
	v_fmac_f32_dpp v128, v140, -v156 row_shr:2 row_mask:0xf bank_mask:0xf bound_ctrl:0
	v_fmac_f32_dpp v129, v141, -v157 row_shr:2 row_mask:0xf bank_mask:0xf bound_ctrl:0
	v_fmac_f32_dpp v130, v142, -v158 row_shr:2 row_mask:0xf bank_mask:0xf bound_ctrl:0
	v_fmac_f32_dpp v131, v143, -v159 row_shr:2 row_mask:0xf bank_mask:0xf bound_ctrl:0
	v_fmac_f32_dpp v140, v140, v152 row_shr:2 row_mask:0xf bank_mask:0xf bound_ctrl:0
	v_fmac_f32_dpp v141, v141, v153 row_shr:2 row_mask:0xf bank_mask:0xf bound_ctrl:0
	v_fmac_f32_dpp v142, v142, v154 row_shr:2 row_mask:0xf bank_mask:0xf bound_ctrl:0
	v_fmac_f32_dpp v143, v143, v155 row_shr:2 row_mask:0xf bank_mask:0xf bound_ctrl:0
	v_fmac_f32_dpp v140, v168, v156 row_shr:2 row_mask:0xf bank_mask:0xf bound_ctrl:0
	v_fmac_f32_dpp v141, v169, v157 row_shr:2 row_mask:0xf bank_mask:0xf bound_ctrl:0
	v_fmac_f32_dpp v142, v170, v158 row_shr:2 row_mask:0xf bank_mask:0xf bound_ctrl:0
	v_fmac_f32_dpp v143, v171, v159 row_shr:2 row_mask:0xf bank_mask:0xf bound_ctrl:0
	ds_read_b128 v[152:155], v9 offset:1600
	ds_read_b128 v[156:159], v9 offset:1856
	s_waitcnt lgkmcnt(2)
	v_mov_b32_e32 v168, v80
	v_mov_b32_e32 v169, v81
	v_mov_b32_e32 v170, v82
	v_mov_b32_e32 v171, v83
	v_fmac_f32_dpp v80, v80, v144 row_shr:4 row_mask:0xf bank_mask:0xf bound_ctrl:0
	v_fmac_f32_dpp v81, v81, v145 row_shr:4 row_mask:0xf bank_mask:0xf bound_ctrl:0
	v_fmac_f32_dpp v82, v82, v146 row_shr:4 row_mask:0xf bank_mask:0xf bound_ctrl:0
	v_fmac_f32_dpp v83, v83, v147 row_shr:4 row_mask:0xf bank_mask:0xf bound_ctrl:0
	v_fmac_f32_dpp v80, v84, -v148 row_shr:4 row_mask:0xf bank_mask:0xf bound_ctrl:0
	v_fmac_f32_dpp v81, v85, -v149 row_shr:4 row_mask:0xf bank_mask:0xf bound_ctrl:0
	v_fmac_f32_dpp v82, v86, -v150 row_shr:4 row_mask:0xf bank_mask:0xf bound_ctrl:0
	v_fmac_f32_dpp v83, v87, -v151 row_shr:4 row_mask:0xf bank_mask:0xf bound_ctrl:0
	v_fmac_f32_dpp v84, v84, v144 row_shr:4 row_mask:0xf bank_mask:0xf bound_ctrl:0
	v_fmac_f32_dpp v85, v85, v145 row_shr:4 row_mask:0xf bank_mask:0xf bound_ctrl:0
	v_fmac_f32_dpp v86, v86, v146 row_shr:4 row_mask:0xf bank_mask:0xf bound_ctrl:0
	v_fmac_f32_dpp v87, v87, v147 row_shr:4 row_mask:0xf bank_mask:0xf bound_ctrl:0
	v_fmac_f32_dpp v84, v168, v148 row_shr:4 row_mask:0xf bank_mask:0xf bound_ctrl:0
	v_fmac_f32_dpp v85, v169, v149 row_shr:4 row_mask:0xf bank_mask:0xf bound_ctrl:0
	v_fmac_f32_dpp v86, v170, v150 row_shr:4 row_mask:0xf bank_mask:0xf bound_ctrl:0
	v_fmac_f32_dpp v87, v171, v151 row_shr:4 row_mask:0xf bank_mask:0xf bound_ctrl:0
	ds_read_b128 v[144:147], v9 offset:1664
	ds_read_b128 v[148:151], v9 offset:1920
	s_waitcnt lgkmcnt(2)
	v_mov_b32_e32 v168, v112
	v_mov_b32_e32 v169, v113
	v_mov_b32_e32 v170, v114
	v_mov_b32_e32 v171, v115
	v_fmac_f32_dpp v112, v112, v152 row_shr:4 row_mask:0xf bank_mask:0xf bound_ctrl:0
	v_fmac_f32_dpp v113, v113, v153 row_shr:4 row_mask:0xf bank_mask:0xf bound_ctrl:0
	v_fmac_f32_dpp v114, v114, v154 row_shr:4 row_mask:0xf bank_mask:0xf bound_ctrl:0
	v_fmac_f32_dpp v115, v115, v155 row_shr:4 row_mask:0xf bank_mask:0xf bound_ctrl:0
	v_fmac_f32_dpp v112, v116, -v156 row_shr:4 row_mask:0xf bank_mask:0xf bound_ctrl:0
	v_fmac_f32_dpp v113, v117, -v157 row_shr:4 row_mask:0xf bank_mask:0xf bound_ctrl:0
	v_fmac_f32_dpp v114, v118, -v158 row_shr:4 row_mask:0xf bank_mask:0xf bound_ctrl:0
	v_fmac_f32_dpp v115, v119, -v159 row_shr:4 row_mask:0xf bank_mask:0xf bound_ctrl:0
	v_fmac_f32_dpp v116, v116, v152 row_shr:4 row_mask:0xf bank_mask:0xf bound_ctrl:0
	v_fmac_f32_dpp v117, v117, v153 row_shr:4 row_mask:0xf bank_mask:0xf bound_ctrl:0
	v_fmac_f32_dpp v118, v118, v154 row_shr:4 row_mask:0xf bank_mask:0xf bound_ctrl:0
	v_fmac_f32_dpp v119, v119, v155 row_shr:4 row_mask:0xf bank_mask:0xf bound_ctrl:0
	v_fmac_f32_dpp v116, v168, v156 row_shr:4 row_mask:0xf bank_mask:0xf bound_ctrl:0
	v_fmac_f32_dpp v117, v169, v157 row_shr:4 row_mask:0xf bank_mask:0xf bound_ctrl:0
	v_fmac_f32_dpp v118, v170, v158 row_shr:4 row_mask:0xf bank_mask:0xf bound_ctrl:0
	v_fmac_f32_dpp v119, v171, v159 row_shr:4 row_mask:0xf bank_mask:0xf bound_ctrl:0
	ds_read_b128 v[152:155], v9 offset:1728
	ds_read_b128 v[156:159], v9 offset:1984
	s_waitcnt lgkmcnt(2)
	v_mov_b32_e32 v168, v120
	v_mov_b32_e32 v169, v121
	v_mov_b32_e32 v170, v122
	v_mov_b32_e32 v171, v123
	v_fmac_f32_dpp v120, v120, v144 row_shr:4 row_mask:0xf bank_mask:0xf bound_ctrl:0
	v_fmac_f32_dpp v121, v121, v145 row_shr:4 row_mask:0xf bank_mask:0xf bound_ctrl:0
	v_fmac_f32_dpp v122, v122, v146 row_shr:4 row_mask:0xf bank_mask:0xf bound_ctrl:0
	v_fmac_f32_dpp v123, v123, v147 row_shr:4 row_mask:0xf bank_mask:0xf bound_ctrl:0
	v_fmac_f32_dpp v120, v124, -v148 row_shr:4 row_mask:0xf bank_mask:0xf bound_ctrl:0
	v_fmac_f32_dpp v121, v125, -v149 row_shr:4 row_mask:0xf bank_mask:0xf bound_ctrl:0
	v_fmac_f32_dpp v122, v126, -v150 row_shr:4 row_mask:0xf bank_mask:0xf bound_ctrl:0
	v_fmac_f32_dpp v123, v127, -v151 row_shr:4 row_mask:0xf bank_mask:0xf bound_ctrl:0
	v_fmac_f32_dpp v124, v124, v144 row_shr:4 row_mask:0xf bank_mask:0xf bound_ctrl:0
	v_fmac_f32_dpp v125, v125, v145 row_shr:4 row_mask:0xf bank_mask:0xf bound_ctrl:0
	v_fmac_f32_dpp v126, v126, v146 row_shr:4 row_mask:0xf bank_mask:0xf bound_ctrl:0
	v_fmac_f32_dpp v127, v127, v147 row_shr:4 row_mask:0xf bank_mask:0xf bound_ctrl:0
	v_fmac_f32_dpp v124, v168, v148 row_shr:4 row_mask:0xf bank_mask:0xf bound_ctrl:0
	v_fmac_f32_dpp v125, v169, v149 row_shr:4 row_mask:0xf bank_mask:0xf bound_ctrl:0
	v_fmac_f32_dpp v126, v170, v150 row_shr:4 row_mask:0xf bank_mask:0xf bound_ctrl:0
	v_fmac_f32_dpp v127, v171, v151 row_shr:4 row_mask:0xf bank_mask:0xf bound_ctrl:0
	ds_read_b128 v[144:147], v9 offset:2048
	ds_read_b128 v[148:151], v9 offset:2304
	s_waitcnt lgkmcnt(2)
	v_mov_b32_e32 v168, v128
	v_mov_b32_e32 v169, v129
	v_mov_b32_e32 v170, v130
	v_mov_b32_e32 v171, v131
	v_fmac_f32_dpp v128, v128, v152 row_shr:4 row_mask:0xf bank_mask:0xf bound_ctrl:0
	v_fmac_f32_dpp v129, v129, v153 row_shr:4 row_mask:0xf bank_mask:0xf bound_ctrl:0
	v_fmac_f32_dpp v130, v130, v154 row_shr:4 row_mask:0xf bank_mask:0xf bound_ctrl:0
	v_fmac_f32_dpp v131, v131, v155 row_shr:4 row_mask:0xf bank_mask:0xf bound_ctrl:0
	v_fmac_f32_dpp v128, v140, -v156 row_shr:4 row_mask:0xf bank_mask:0xf bound_ctrl:0
	v_fmac_f32_dpp v129, v141, -v157 row_shr:4 row_mask:0xf bank_mask:0xf bound_ctrl:0
	v_fmac_f32_dpp v130, v142, -v158 row_shr:4 row_mask:0xf bank_mask:0xf bound_ctrl:0
	v_fmac_f32_dpp v131, v143, -v159 row_shr:4 row_mask:0xf bank_mask:0xf bound_ctrl:0
	v_fmac_f32_dpp v140, v140, v152 row_shr:4 row_mask:0xf bank_mask:0xf bound_ctrl:0
	v_fmac_f32_dpp v141, v141, v153 row_shr:4 row_mask:0xf bank_mask:0xf bound_ctrl:0
	v_fmac_f32_dpp v142, v142, v154 row_shr:4 row_mask:0xf bank_mask:0xf bound_ctrl:0
	v_fmac_f32_dpp v143, v143, v155 row_shr:4 row_mask:0xf bank_mask:0xf bound_ctrl:0
	v_fmac_f32_dpp v140, v168, v156 row_shr:4 row_mask:0xf bank_mask:0xf bound_ctrl:0
	v_fmac_f32_dpp v141, v169, v157 row_shr:4 row_mask:0xf bank_mask:0xf bound_ctrl:0
	v_fmac_f32_dpp v142, v170, v158 row_shr:4 row_mask:0xf bank_mask:0xf bound_ctrl:0
	v_fmac_f32_dpp v143, v171, v159 row_shr:4 row_mask:0xf bank_mask:0xf bound_ctrl:0
	ds_read_b128 v[152:155], v9 offset:2112
	ds_read_b128 v[156:159], v9 offset:2368
	s_waitcnt lgkmcnt(2)
	v_mov_b32_e32 v168, v80
	v_mov_b32_e32 v169, v81
	v_mov_b32_e32 v170, v82
	v_mov_b32_e32 v171, v83
	v_fmac_f32_dpp v80, v80, v144 row_shr:8 row_mask:0xf bank_mask:0xf bound_ctrl:0
	v_fmac_f32_dpp v81, v81, v145 row_shr:8 row_mask:0xf bank_mask:0xf bound_ctrl:0
	v_fmac_f32_dpp v82, v82, v146 row_shr:8 row_mask:0xf bank_mask:0xf bound_ctrl:0
	v_fmac_f32_dpp v83, v83, v147 row_shr:8 row_mask:0xf bank_mask:0xf bound_ctrl:0
	v_fmac_f32_dpp v80, v84, -v148 row_shr:8 row_mask:0xf bank_mask:0xf bound_ctrl:0
	v_fmac_f32_dpp v81, v85, -v149 row_shr:8 row_mask:0xf bank_mask:0xf bound_ctrl:0
	v_fmac_f32_dpp v82, v86, -v150 row_shr:8 row_mask:0xf bank_mask:0xf bound_ctrl:0
	v_fmac_f32_dpp v83, v87, -v151 row_shr:8 row_mask:0xf bank_mask:0xf bound_ctrl:0
	v_fmac_f32_dpp v84, v84, v144 row_shr:8 row_mask:0xf bank_mask:0xf bound_ctrl:0
	v_fmac_f32_dpp v85, v85, v145 row_shr:8 row_mask:0xf bank_mask:0xf bound_ctrl:0
	v_fmac_f32_dpp v86, v86, v146 row_shr:8 row_mask:0xf bank_mask:0xf bound_ctrl:0
	v_fmac_f32_dpp v87, v87, v147 row_shr:8 row_mask:0xf bank_mask:0xf bound_ctrl:0
	v_fmac_f32_dpp v84, v168, v148 row_shr:8 row_mask:0xf bank_mask:0xf bound_ctrl:0
	v_fmac_f32_dpp v85, v169, v149 row_shr:8 row_mask:0xf bank_mask:0xf bound_ctrl:0
	v_fmac_f32_dpp v86, v170, v150 row_shr:8 row_mask:0xf bank_mask:0xf bound_ctrl:0
	v_fmac_f32_dpp v87, v171, v151 row_shr:8 row_mask:0xf bank_mask:0xf bound_ctrl:0
	ds_read_b128 v[144:147], v9 offset:2176
	ds_read_b128 v[148:151], v9 offset:2432
	s_waitcnt lgkmcnt(2)
	v_mov_b32_e32 v168, v112
	v_mov_b32_e32 v169, v113
	v_mov_b32_e32 v170, v114
	v_mov_b32_e32 v171, v115
	v_fmac_f32_dpp v112, v112, v152 row_shr:8 row_mask:0xf bank_mask:0xf bound_ctrl:0
	v_fmac_f32_dpp v113, v113, v153 row_shr:8 row_mask:0xf bank_mask:0xf bound_ctrl:0
	v_fmac_f32_dpp v114, v114, v154 row_shr:8 row_mask:0xf bank_mask:0xf bound_ctrl:0
	v_fmac_f32_dpp v115, v115, v155 row_shr:8 row_mask:0xf bank_mask:0xf bound_ctrl:0
	v_fmac_f32_dpp v112, v116, -v156 row_shr:8 row_mask:0xf bank_mask:0xf bound_ctrl:0
	v_fmac_f32_dpp v113, v117, -v157 row_shr:8 row_mask:0xf bank_mask:0xf bound_ctrl:0
	v_fmac_f32_dpp v114, v118, -v158 row_shr:8 row_mask:0xf bank_mask:0xf bound_ctrl:0
	v_fmac_f32_dpp v115, v119, -v159 row_shr:8 row_mask:0xf bank_mask:0xf bound_ctrl:0
	v_fmac_f32_dpp v116, v116, v152 row_shr:8 row_mask:0xf bank_mask:0xf bound_ctrl:0
	v_fmac_f32_dpp v117, v117, v153 row_shr:8 row_mask:0xf bank_mask:0xf bound_ctrl:0
	v_fmac_f32_dpp v118, v118, v154 row_shr:8 row_mask:0xf bank_mask:0xf bound_ctrl:0
	v_fmac_f32_dpp v119, v119, v155 row_shr:8 row_mask:0xf bank_mask:0xf bound_ctrl:0
	v_fmac_f32_dpp v116, v168, v156 row_shr:8 row_mask:0xf bank_mask:0xf bound_ctrl:0
	v_fmac_f32_dpp v117, v169, v157 row_shr:8 row_mask:0xf bank_mask:0xf bound_ctrl:0
	v_fmac_f32_dpp v118, v170, v158 row_shr:8 row_mask:0xf bank_mask:0xf bound_ctrl:0
	v_fmac_f32_dpp v119, v171, v159 row_shr:8 row_mask:0xf bank_mask:0xf bound_ctrl:0
	ds_read_b128 v[152:155], v9 offset:2240
	ds_read_b128 v[156:159], v9 offset:2496
	s_waitcnt lgkmcnt(2)
	v_mov_b32_e32 v168, v120
	v_mov_b32_e32 v169, v121
	v_mov_b32_e32 v170, v122
	v_mov_b32_e32 v171, v123
	v_fmac_f32_dpp v120, v120, v144 row_shr:8 row_mask:0xf bank_mask:0xf bound_ctrl:0
	v_fmac_f32_dpp v121, v121, v145 row_shr:8 row_mask:0xf bank_mask:0xf bound_ctrl:0
	v_fmac_f32_dpp v122, v122, v146 row_shr:8 row_mask:0xf bank_mask:0xf bound_ctrl:0
	v_fmac_f32_dpp v123, v123, v147 row_shr:8 row_mask:0xf bank_mask:0xf bound_ctrl:0
	v_fmac_f32_dpp v120, v124, -v148 row_shr:8 row_mask:0xf bank_mask:0xf bound_ctrl:0
	v_fmac_f32_dpp v121, v125, -v149 row_shr:8 row_mask:0xf bank_mask:0xf bound_ctrl:0
	v_fmac_f32_dpp v122, v126, -v150 row_shr:8 row_mask:0xf bank_mask:0xf bound_ctrl:0
	v_fmac_f32_dpp v123, v127, -v151 row_shr:8 row_mask:0xf bank_mask:0xf bound_ctrl:0
	v_fmac_f32_dpp v124, v124, v144 row_shr:8 row_mask:0xf bank_mask:0xf bound_ctrl:0
	v_fmac_f32_dpp v125, v125, v145 row_shr:8 row_mask:0xf bank_mask:0xf bound_ctrl:0
	v_fmac_f32_dpp v126, v126, v146 row_shr:8 row_mask:0xf bank_mask:0xf bound_ctrl:0
	v_fmac_f32_dpp v127, v127, v147 row_shr:8 row_mask:0xf bank_mask:0xf bound_ctrl:0
	v_fmac_f32_dpp v124, v168, v148 row_shr:8 row_mask:0xf bank_mask:0xf bound_ctrl:0
	v_fmac_f32_dpp v125, v169, v149 row_shr:8 row_mask:0xf bank_mask:0xf bound_ctrl:0
	v_fmac_f32_dpp v126, v170, v150 row_shr:8 row_mask:0xf bank_mask:0xf bound_ctrl:0
	v_fmac_f32_dpp v127, v171, v151 row_shr:8 row_mask:0xf bank_mask:0xf bound_ctrl:0
	s_waitcnt lgkmcnt(0)
	v_mov_b32_e32 v168, v128
	v_mov_b32_e32 v169, v129
	v_mov_b32_e32 v170, v130
	v_mov_b32_e32 v171, v131
	v_fmac_f32_dpp v128, v128, v152 row_shr:8 row_mask:0xf bank_mask:0xf bound_ctrl:0
	v_fmac_f32_dpp v129, v129, v153 row_shr:8 row_mask:0xf bank_mask:0xf bound_ctrl:0
	v_fmac_f32_dpp v130, v130, v154 row_shr:8 row_mask:0xf bank_mask:0xf bound_ctrl:0
	v_fmac_f32_dpp v131, v131, v155 row_shr:8 row_mask:0xf bank_mask:0xf bound_ctrl:0
	v_fmac_f32_dpp v128, v140, -v156 row_shr:8 row_mask:0xf bank_mask:0xf bound_ctrl:0
	v_fmac_f32_dpp v129, v141, -v157 row_shr:8 row_mask:0xf bank_mask:0xf bound_ctrl:0
	v_fmac_f32_dpp v130, v142, -v158 row_shr:8 row_mask:0xf bank_mask:0xf bound_ctrl:0
	v_fmac_f32_dpp v131, v143, -v159 row_shr:8 row_mask:0xf bank_mask:0xf bound_ctrl:0
	v_fmac_f32_dpp v140, v140, v152 row_shr:8 row_mask:0xf bank_mask:0xf bound_ctrl:0
	v_fmac_f32_dpp v141, v141, v153 row_shr:8 row_mask:0xf bank_mask:0xf bound_ctrl:0
	v_fmac_f32_dpp v142, v142, v154 row_shr:8 row_mask:0xf bank_mask:0xf bound_ctrl:0
	v_fmac_f32_dpp v143, v143, v155 row_shr:8 row_mask:0xf bank_mask:0xf bound_ctrl:0
	v_fmac_f32_dpp v140, v168, v156 row_shr:8 row_mask:0xf bank_mask:0xf bound_ctrl:0
	v_fmac_f32_dpp v141, v169, v157 row_shr:8 row_mask:0xf bank_mask:0xf bound_ctrl:0
	v_fmac_f32_dpp v142, v170, v158 row_shr:8 row_mask:0xf bank_mask:0xf bound_ctrl:0
	v_fmac_f32_dpp v143, v171, v159 row_shr:8 row_mask:0xf bank_mask:0xf bound_ctrl:0
	s_nop 1
	s_mov_b64 exec, s[10:11]
	global_store_dword v10, v80, s[36:37] offset:0
	global_store_dword v10, v84, s[36:37] offset:4
	global_store_dword v10, v81, s[36:37] offset:8
	global_store_dword v10, v85, s[36:37] offset:12
	global_store_dword v10, v82, s[36:37] offset:16
	global_store_dword v10, v86, s[36:37] offset:20
	global_store_dword v10, v83, s[36:37] offset:24
	global_store_dword v10, v87, s[36:37] offset:28
	global_store_dword v10, v112, s[36:37] offset:128
	global_store_dword v10, v116, s[36:37] offset:132
	global_store_dword v10, v113, s[36:37] offset:136
	global_store_dword v10, v117, s[36:37] offset:140
	global_store_dword v10, v114, s[36:37] offset:144
	global_store_dword v10, v118, s[36:37] offset:148
	global_store_dword v10, v115, s[36:37] offset:152
	global_store_dword v10, v119, s[36:37] offset:156
	global_store_dword v10, v120, s[36:37] offset:256
	global_store_dword v10, v124, s[36:37] offset:260
	global_store_dword v10, v121, s[36:37] offset:264
	global_store_dword v10, v125, s[36:37] offset:268
	global_store_dword v10, v122, s[36:37] offset:272
	global_store_dword v10, v126, s[36:37] offset:276
	global_store_dword v10, v123, s[36:37] offset:280
	global_store_dword v10, v127, s[36:37] offset:284
	global_store_dword v10, v128, s[36:37] offset:384
	global_store_dword v10, v140, s[36:37] offset:388
	global_store_dword v10, v129, s[36:37] offset:392
	global_store_dword v10, v141, s[36:37] offset:396
	global_store_dword v10, v130, s[36:37] offset:400
	global_store_dword v10, v142, s[36:37] offset:404
	global_store_dword v10, v131, s[36:37] offset:408
	global_store_dword v10, v143, s[36:37] offset:412
	s_mov_b64 exec, -1
	s_add_i32 s55, s6, 16
	s_lshl_b32 s56, s55, 13
	s_add_u32 s12, s94, 0x12d96000
	s_addc_u32 s13, s95, 0
	s_add_u32 s12, s12, s56
	s_addc_u32 s13, s13, 0
	s_lshl_b32 s56, s55, 9
	s_add_u32 s38, s94, 0x12d92000
	s_addc_u32 s39, s95, 0
	s_add_u32 s38, s38, s56
	s_addc_u32 s39, s39, 0
	s_lshl_b32 s56, s0, 5
	s_lshl_b32 s55, s6, 1
	s_add_i32 s56, s56, s55
	s_add_i32 s56, s56, 1
	s_lshl_b32 s56, s56, 9
	s_add_u32 s36, s94, 0x12dd6000
	s_addc_u32 s37, s95, 0
	s_add_u32 s36, s36, s56
	s_addc_u32 s37, s37, 0
	global_load_dwordx2 v[2:3], v7, s[38:39]
	global_load_dwordx4 v[12:15], v6, s[12:13] offset:0
	global_load_dwordx4 v[16:19], v6, s[12:13] offset:1024
	global_load_dwordx4 v[20:23], v6, s[12:13] offset:256
	global_load_dwordx4 v[24:27], v6, s[12:13] offset:1280
	global_load_dwordx4 v[28:31], v6, s[12:13] offset:512
	global_load_dwordx4 v[32:35], v6, s[12:13] offset:1536
	global_load_dwordx4 v[36:39], v6, s[12:13] offset:768
	global_load_dwordx4 v[40:43], v6, s[12:13] offset:1792
	s_waitcnt vmcnt(8)
	ds_write_b32 v8, v2 offset:0
	ds_write_b32 v8, v3 offset:256
	v_mul_f32_e32 v168, v3, v3
	v_mul_f32_e32 v169, v2, v3
	v_fma_f32 v2, v2, v2, -v168
	v_add_f32_e32 v3, v169, v169
	ds_write_b32 v8, v2 offset:512
	ds_write_b32 v8, v3 offset:768
	v_mul_f32_e32 v168, v3, v3
	v_mul_f32_e32 v169, v2, v3
	v_fma_f32 v2, v2, v2, -v168
	v_add_f32_e32 v3, v169, v169
	ds_write_b32 v8, v2 offset:1024
	ds_write_b32 v8, v3 offset:1280
	v_mul_f32_e32 v168, v3, v3
	v_mul_f32_e32 v169, v2, v3
	v_fma_f32 v2, v2, v2, -v168
	v_add_f32_e32 v3, v169, v169
	ds_write_b32 v8, v2 offset:1536
	ds_write_b32 v8, v3 offset:1792
	v_mul_f32_e32 v168, v3, v3
	v_mul_f32_e32 v169, v2, v3
	v_fma_f32 v2, v2, v2, -v168
	v_add_f32_e32 v3, v169, v169
	ds_write_b32 v8, v2 offset:2048
	ds_write_b32 v8, v3 offset:2304
	s_waitcnt lgkmcnt(0)
	s_waitcnt vmcnt(7)
	v_mfma_f32_16x16x4_f32 v[44:47], v12, v172, 0
	v_mfma_f32_16x16x4_f32 v[52:55], v13, v172, 0
	v_mfma_f32_16x16x4_f32 v[80:83], v12, v176, 0
	v_mfma_f32_16x16x4_f32 v[84:87], v13, v176, 0
	s_waitcnt vmcnt(5)
	v_mfma_f32_16x16x4_f32 v[56:59], v20, v172, 0
	v_mfma_f32_16x16x4_f32 v[60:63], v21, v172, 0
	v_mfma_f32_16x16x4_f32 v[112:115], v20, v176, 0
	v_mfma_f32_16x16x4_f32 v[116:119], v21, v176, 0
	s_waitcnt vmcnt(3)
	v_mfma_f32_16x16x4_f32 v[64:67], v28, v172, 0
	v_mfma_f32_16x16x4_f32 v[68:71], v29, v172, 0
	v_mfma_f32_16x16x4_f32 v[120:123], v28, v176, 0
	v_mfma_f32_16x16x4_f32 v[124:127], v29, v176, 0
	s_waitcnt vmcnt(1)
	v_mfma_f32_16x16x4_f32 v[72:75], v36, v172, 0
	v_mfma_f32_16x16x4_f32 v[76:79], v37, v172, 0
	v_mfma_f32_16x16x4_f32 v[128:131], v36, v176, 0
	v_mfma_f32_16x16x4_f32 v[140:143], v37, v176, 0
	v_mfma_f32_16x16x4_f32 v[44:47], v14, v173, v[44:47]
	v_mfma_f32_16x16x4_f32 v[52:55], v15, v173, v[52:55]
	v_mfma_f32_16x16x4_f32 v[80:83], v14, v177, v[80:83]
	v_mfma_f32_16x16x4_f32 v[84:87], v15, v177, v[84:87]
	v_mfma_f32_16x16x4_f32 v[56:59], v22, v173, v[56:59]
	v_mfma_f32_16x16x4_f32 v[60:63], v23, v173, v[60:63]
	v_mfma_f32_16x16x4_f32 v[112:115], v22, v177, v[112:115]
	v_mfma_f32_16x16x4_f32 v[116:119], v23, v177, v[116:119]
	v_mfma_f32_16x16x4_f32 v[64:67], v30, v173, v[64:67]
	v_mfma_f32_16x16x4_f32 v[68:71], v31, v173, v[68:71]
	v_mfma_f32_16x16x4_f32 v[120:123], v30, v177, v[120:123]
	v_mfma_f32_16x16x4_f32 v[124:127], v31, v177, v[124:127]
	v_mfma_f32_16x16x4_f32 v[72:75], v38, v173, v[72:75]
	v_mfma_f32_16x16x4_f32 v[76:79], v39, v173, v[76:79]
	v_mfma_f32_16x16x4_f32 v[128:131], v38, v177, v[128:131]
	v_mfma_f32_16x16x4_f32 v[140:143], v39, v177, v[140:143]
	v_mfma_f32_16x16x4_f32 v[44:47], v16, v174, v[44:47]
	v_mfma_f32_16x16x4_f32 v[52:55], v17, v174, v[52:55]
	v_mfma_f32_16x16x4_f32 v[80:83], v16, v178, v[80:83]
	v_mfma_f32_16x16x4_f32 v[84:87], v17, v178, v[84:87]
	v_mfma_f32_16x16x4_f32 v[56:59], v24, v174, v[56:59]
	v_mfma_f32_16x16x4_f32 v[60:63], v25, v174, v[60:63]
	v_mfma_f32_16x16x4_f32 v[112:115], v24, v178, v[112:115]
	v_mfma_f32_16x16x4_f32 v[116:119], v25, v178, v[116:119]
	v_mfma_f32_16x16x4_f32 v[64:67], v32, v174, v[64:67]
	v_mfma_f32_16x16x4_f32 v[68:71], v33, v174, v[68:71]
	v_mfma_f32_16x16x4_f32 v[120:123], v32, v178, v[120:123]
	v_mfma_f32_16x16x4_f32 v[124:127], v33, v178, v[124:127]
	s_waitcnt vmcnt(0)
	v_mfma_f32_16x16x4_f32 v[72:75], v40, v174, v[72:75]
	v_mfma_f32_16x16x4_f32 v[76:79], v41, v174, v[76:79]
	v_mfma_f32_16x16x4_f32 v[128:131], v40, v178, v[128:131]
	v_mfma_f32_16x16x4_f32 v[140:143], v41, v178, v[140:143]
	v_mfma_f32_16x16x4_f32 v[44:47], v18, v175, v[44:47]
	v_mfma_f32_16x16x4_f32 v[52:55], v19, v175, v[52:55]
	v_mfma_f32_16x16x4_f32 v[80:83], v18, v179, v[80:83]
	v_mfma_f32_16x16x4_f32 v[84:87], v19, v179, v[84:87]
	v_mfma_f32_16x16x4_f32 v[56:59], v26, v175, v[56:59]
	v_mfma_f32_16x16x4_f32 v[60:63], v27, v175, v[60:63]
	v_mfma_f32_16x16x4_f32 v[112:115], v26, v179, v[112:115]
	v_mfma_f32_16x16x4_f32 v[116:119], v27, v179, v[116:119]
	v_mfma_f32_16x16x4_f32 v[64:67], v34, v175, v[64:67]
	v_mfma_f32_16x16x4_f32 v[68:71], v35, v175, v[68:71]
	v_mfma_f32_16x16x4_f32 v[120:123], v34, v179, v[120:123]
	v_mfma_f32_16x16x4_f32 v[124:127], v35, v179, v[124:127]
	v_mfma_f32_16x16x4_f32 v[72:75], v42, v175, v[72:75]
	v_mfma_f32_16x16x4_f32 v[76:79], v43, v175, v[76:79]
	v_mfma_f32_16x16x4_f32 v[128:131], v42, v179, v[128:131]
	v_mfma_f32_16x16x4_f32 v[140:143], v43, v179, v[140:143]
	s_nop 9
	ds_read_b128 v[144:147], v9 offset:0
	ds_read_b128 v[148:151], v9 offset:256
	ds_read_b128 v[152:155], v9 offset:64
	ds_read_b128 v[156:159], v9 offset:320
	s_waitcnt lgkmcnt(2)
	v_fmac_f32_e32 v44, v144, v80
	v_fmac_f32_e32 v45, v145, v81
	v_fmac_f32_e32 v46, v146, v82
	v_fmac_f32_e32 v47, v147, v83
	v_fma_f32 v44, -v148, v84, v44
	v_fma_f32 v45, -v149, v85, v45
	v_fma_f32 v46, -v150, v86, v46
	v_fma_f32 v47, -v151, v87, v47
	v_fmac_f32_e32 v52, v144, v84
	v_fmac_f32_e32 v53, v145, v85
	v_fmac_f32_e32 v54, v146, v86
	v_fmac_f32_e32 v55, v147, v87
	v_fmac_f32_e32 v52, v148, v80
	v_fmac_f32_e32 v53, v149, v81
	v_fmac_f32_e32 v54, v150, v82
	v_fmac_f32_e32 v55, v151, v83
	ds_read_b128 v[144:147], v9 offset:128
	ds_read_b128 v[148:151], v9 offset:384
	s_waitcnt lgkmcnt(2)
	v_fmac_f32_e32 v56, v152, v112
	v_fmac_f32_e32 v57, v153, v113
	v_fmac_f32_e32 v58, v154, v114
	v_fmac_f32_e32 v59, v155, v115
	v_fma_f32 v56, -v156, v116, v56
	v_fma_f32 v57, -v157, v117, v57
	v_fma_f32 v58, -v158, v118, v58
	v_fma_f32 v59, -v159, v119, v59
	v_fmac_f32_e32 v60, v152, v116
	v_fmac_f32_e32 v61, v153, v117
	v_fmac_f32_e32 v62, v154, v118
	v_fmac_f32_e32 v63, v155, v119
	v_fmac_f32_e32 v60, v156, v112
	v_fmac_f32_e32 v61, v157, v113
	v_fmac_f32_e32 v62, v158, v114
	v_fmac_f32_e32 v63, v159, v115
	ds_read_b128 v[152:155], v9 offset:192
	ds_read_b128 v[156:159], v9 offset:448
	s_waitcnt lgkmcnt(2)
	v_fmac_f32_e32 v64, v144, v120
	v_fmac_f32_e32 v65, v145, v121
	v_fmac_f32_e32 v66, v146, v122
	v_fmac_f32_e32 v67, v147, v123
	v_fma_f32 v64, -v148, v124, v64
	v_fma_f32 v65, -v149, v125, v65
	v_fma_f32 v66, -v150, v126, v66
	v_fma_f32 v67, -v151, v127, v67
	v_fmac_f32_e32 v68, v144, v124
	v_fmac_f32_e32 v69, v145, v125
	v_fmac_f32_e32 v70, v146, v126
	v_fmac_f32_e32 v71, v147, v127
	v_fmac_f32_e32 v68, v148, v120
	v_fmac_f32_e32 v69, v149, v121
	v_fmac_f32_e32 v70, v150, v122
	v_fmac_f32_e32 v71, v151, v123
	s_waitcnt lgkmcnt(0)
	v_fmac_f32_e32 v72, v152, v128
	v_fmac_f32_e32 v73, v153, v129
	v_fmac_f32_e32 v74, v154, v130
	v_fmac_f32_e32 v75, v155, v131
	v_fma_f32 v72, -v156, v140, v72
	v_fma_f32 v73, -v157, v141, v73
	v_fma_f32 v74, -v158, v142, v74
	v_fma_f32 v75, -v159, v143, v75
	v_fmac_f32_e32 v76, v152, v140
	v_fmac_f32_e32 v77, v153, v141
	v_fmac_f32_e32 v78, v154, v142
	v_fmac_f32_e32 v79, v155, v143
	v_fmac_f32_e32 v76, v156, v128
	v_fmac_f32_e32 v77, v157, v129
	v_fmac_f32_e32 v78, v158, v130
	v_fmac_f32_e32 v79, v159, v131
	ds_read_b128 v[144:147], v9 offset:512
	ds_read_b128 v[148:151], v9 offset:768
	ds_read_b128 v[152:155], v9 offset:576
	ds_read_b128 v[156:159], v9 offset:832
	s_waitcnt lgkmcnt(2)
	v_mov_b32_e32 v168, v44
	v_mov_b32_e32 v169, v45
	v_mov_b32_e32 v170, v46
	v_mov_b32_e32 v171, v47
	s_nop 1
	v_fmac_f32_dpp v44, v44, v144 row_shl:1 row_mask:0xf bank_mask:0xf bound_ctrl:0
	v_fmac_f32_dpp v45, v45, v145 row_shl:1 row_mask:0xf bank_mask:0xf bound_ctrl:0
	v_fmac_f32_dpp v46, v46, v146 row_shl:1 row_mask:0xf bank_mask:0xf bound_ctrl:0
	v_fmac_f32_dpp v47, v47, v147 row_shl:1 row_mask:0xf bank_mask:0xf bound_ctrl:0
	v_fmac_f32_dpp v44, v52, -v148 row_shl:1 row_mask:0xf bank_mask:0xf bound_ctrl:0
	v_fmac_f32_dpp v45, v53, -v149 row_shl:1 row_mask:0xf bank_mask:0xf bound_ctrl:0
	v_fmac_f32_dpp v46, v54, -v150 row_shl:1 row_mask:0xf bank_mask:0xf bound_ctrl:0
	v_fmac_f32_dpp v47, v55, -v151 row_shl:1 row_mask:0xf bank_mask:0xf bound_ctrl:0
	v_fmac_f32_dpp v52, v52, v144 row_shl:1 row_mask:0xf bank_mask:0xf bound_ctrl:0
	v_fmac_f32_dpp v53, v53, v145 row_shl:1 row_mask:0xf bank_mask:0xf bound_ctrl:0
	v_fmac_f32_dpp v54, v54, v146 row_shl:1 row_mask:0xf bank_mask:0xf bound_ctrl:0
	v_fmac_f32_dpp v55, v55, v147 row_shl:1 row_mask:0xf bank_mask:0xf bound_ctrl:0
	v_fmac_f32_dpp v52, v168, v148 row_shl:1 row_mask:0xf bank_mask:0xf bound_ctrl:0
	v_fmac_f32_dpp v53, v169, v149 row_shl:1 row_mask:0xf bank_mask:0xf bound_ctrl:0
	v_fmac_f32_dpp v54, v170, v150 row_shl:1 row_mask:0xf bank_mask:0xf bound_ctrl:0
	v_fmac_f32_dpp v55, v171, v151 row_shl:1 row_mask:0xf bank_mask:0xf bound_ctrl:0
	ds_read_b128 v[144:147], v9 offset:640
	ds_read_b128 v[148:151], v9 offset:896
	s_waitcnt lgkmcnt(2)
	v_mov_b32_e32 v168, v56
	v_mov_b32_e32 v169, v57
	v_mov_b32_e32 v170, v58
	v_mov_b32_e32 v171, v59
	v_fmac_f32_dpp v56, v56, v152 row_shl:1 row_mask:0xf bank_mask:0xf bound_ctrl:0
	v_fmac_f32_dpp v57, v57, v153 row_shl:1 row_mask:0xf bank_mask:0xf bound_ctrl:0
	v_fmac_f32_dpp v58, v58, v154 row_shl:1 row_mask:0xf bank_mask:0xf bound_ctrl:0
	v_fmac_f32_dpp v59, v59, v155 row_shl:1 row_mask:0xf bank_mask:0xf bound_ctrl:0
	v_fmac_f32_dpp v56, v60, -v156 row_shl:1 row_mask:0xf bank_mask:0xf bound_ctrl:0
	v_fmac_f32_dpp v57, v61, -v157 row_shl:1 row_mask:0xf bank_mask:0xf bound_ctrl:0
	v_fmac_f32_dpp v58, v62, -v158 row_shl:1 row_mask:0xf bank_mask:0xf bound_ctrl:0
	v_fmac_f32_dpp v59, v63, -v159 row_shl:1 row_mask:0xf bank_mask:0xf bound_ctrl:0
	v_fmac_f32_dpp v60, v60, v152 row_shl:1 row_mask:0xf bank_mask:0xf bound_ctrl:0
	v_fmac_f32_dpp v61, v61, v153 row_shl:1 row_mask:0xf bank_mask:0xf bound_ctrl:0
	v_fmac_f32_dpp v62, v62, v154 row_shl:1 row_mask:0xf bank_mask:0xf bound_ctrl:0
	v_fmac_f32_dpp v63, v63, v155 row_shl:1 row_mask:0xf bank_mask:0xf bound_ctrl:0
	v_fmac_f32_dpp v60, v168, v156 row_shl:1 row_mask:0xf bank_mask:0xf bound_ctrl:0
	v_fmac_f32_dpp v61, v169, v157 row_shl:1 row_mask:0xf bank_mask:0xf bound_ctrl:0
	v_fmac_f32_dpp v62, v170, v158 row_shl:1 row_mask:0xf bank_mask:0xf bound_ctrl:0
	v_fmac_f32_dpp v63, v171, v159 row_shl:1 row_mask:0xf bank_mask:0xf bound_ctrl:0
	ds_read_b128 v[152:155], v9 offset:704
	ds_read_b128 v[156:159], v9 offset:960
	s_waitcnt lgkmcnt(2)
	v_mov_b32_e32 v168, v64
	v_mov_b32_e32 v169, v65
	v_mov_b32_e32 v170, v66
	v_mov_b32_e32 v171, v67
	v_fmac_f32_dpp v64, v64, v144 row_shl:1 row_mask:0xf bank_mask:0xf bound_ctrl:0
	v_fmac_f32_dpp v65, v65, v145 row_shl:1 row_mask:0xf bank_mask:0xf bound_ctrl:0
	v_fmac_f32_dpp v66, v66, v146 row_shl:1 row_mask:0xf bank_mask:0xf bound_ctrl:0
	v_fmac_f32_dpp v67, v67, v147 row_shl:1 row_mask:0xf bank_mask:0xf bound_ctrl:0
	v_fmac_f32_dpp v64, v68, -v148 row_shl:1 row_mask:0xf bank_mask:0xf bound_ctrl:0
	v_fmac_f32_dpp v65, v69, -v149 row_shl:1 row_mask:0xf bank_mask:0xf bound_ctrl:0
	v_fmac_f32_dpp v66, v70, -v150 row_shl:1 row_mask:0xf bank_mask:0xf bound_ctrl:0
	v_fmac_f32_dpp v67, v71, -v151 row_shl:1 row_mask:0xf bank_mask:0xf bound_ctrl:0
	v_fmac_f32_dpp v68, v68, v144 row_shl:1 row_mask:0xf bank_mask:0xf bound_ctrl:0
	v_fmac_f32_dpp v69, v69, v145 row_shl:1 row_mask:0xf bank_mask:0xf bound_ctrl:0
	v_fmac_f32_dpp v70, v70, v146 row_shl:1 row_mask:0xf bank_mask:0xf bound_ctrl:0
	v_fmac_f32_dpp v71, v71, v147 row_shl:1 row_mask:0xf bank_mask:0xf bound_ctrl:0
	v_fmac_f32_dpp v68, v168, v148 row_shl:1 row_mask:0xf bank_mask:0xf bound_ctrl:0
	v_fmac_f32_dpp v69, v169, v149 row_shl:1 row_mask:0xf bank_mask:0xf bound_ctrl:0
	v_fmac_f32_dpp v70, v170, v150 row_shl:1 row_mask:0xf bank_mask:0xf bound_ctrl:0
	v_fmac_f32_dpp v71, v171, v151 row_shl:1 row_mask:0xf bank_mask:0xf bound_ctrl:0
	ds_read_b128 v[144:147], v9 offset:1024
	ds_read_b128 v[148:151], v9 offset:1280
	s_waitcnt lgkmcnt(2)
	v_mov_b32_e32 v168, v72
	v_mov_b32_e32 v169, v73
	v_mov_b32_e32 v170, v74
	v_mov_b32_e32 v171, v75
	v_fmac_f32_dpp v72, v72, v152 row_shl:1 row_mask:0xf bank_mask:0xf bound_ctrl:0
	v_fmac_f32_dpp v73, v73, v153 row_shl:1 row_mask:0xf bank_mask:0xf bound_ctrl:0
	v_fmac_f32_dpp v74, v74, v154 row_shl:1 row_mask:0xf bank_mask:0xf bound_ctrl:0
	v_fmac_f32_dpp v75, v75, v155 row_shl:1 row_mask:0xf bank_mask:0xf bound_ctrl:0
	v_fmac_f32_dpp v72, v76, -v156 row_shl:1 row_mask:0xf bank_mask:0xf bound_ctrl:0
	v_fmac_f32_dpp v73, v77, -v157 row_shl:1 row_mask:0xf bank_mask:0xf bound_ctrl:0
	v_fmac_f32_dpp v74, v78, -v158 row_shl:1 row_mask:0xf bank_mask:0xf bound_ctrl:0
	v_fmac_f32_dpp v75, v79, -v159 row_shl:1 row_mask:0xf bank_mask:0xf bound_ctrl:0
	v_fmac_f32_dpp v76, v76, v152 row_shl:1 row_mask:0xf bank_mask:0xf bound_ctrl:0
	v_fmac_f32_dpp v77, v77, v153 row_shl:1 row_mask:0xf bank_mask:0xf bound_ctrl:0
	v_fmac_f32_dpp v78, v78, v154 row_shl:1 row_mask:0xf bank_mask:0xf bound_ctrl:0
	v_fmac_f32_dpp v79, v79, v155 row_shl:1 row_mask:0xf bank_mask:0xf bound_ctrl:0
	v_fmac_f32_dpp v76, v168, v156 row_shl:1 row_mask:0xf bank_mask:0xf bound_ctrl:0
	v_fmac_f32_dpp v77, v169, v157 row_shl:1 row_mask:0xf bank_mask:0xf bound_ctrl:0
	v_fmac_f32_dpp v78, v170, v158 row_shl:1 row_mask:0xf bank_mask:0xf bound_ctrl:0
	v_fmac_f32_dpp v79, v171, v159 row_shl:1 row_mask:0xf bank_mask:0xf bound_ctrl:0
	ds_read_b128 v[152:155], v9 offset:1088
	ds_read_b128 v[156:159], v9 offset:1344
	s_waitcnt lgkmcnt(2)
	v_mov_b32_e32 v168, v44
	v_mov_b32_e32 v169, v45
	v_mov_b32_e32 v170, v46
	v_mov_b32_e32 v171, v47
	v_fmac_f32_dpp v44, v44, v144 row_shl:2 row_mask:0xf bank_mask:0xf bound_ctrl:0
	v_fmac_f32_dpp v45, v45, v145 row_shl:2 row_mask:0xf bank_mask:0xf bound_ctrl:0
	v_fmac_f32_dpp v46, v46, v146 row_shl:2 row_mask:0xf bank_mask:0xf bound_ctrl:0
	v_fmac_f32_dpp v47, v47, v147 row_shl:2 row_mask:0xf bank_mask:0xf bound_ctrl:0
	v_fmac_f32_dpp v44, v52, -v148 row_shl:2 row_mask:0xf bank_mask:0xf bound_ctrl:0
	v_fmac_f32_dpp v45, v53, -v149 row_shl:2 row_mask:0xf bank_mask:0xf bound_ctrl:0
	v_fmac_f32_dpp v46, v54, -v150 row_shl:2 row_mask:0xf bank_mask:0xf bound_ctrl:0
	v_fmac_f32_dpp v47, v55, -v151 row_shl:2 row_mask:0xf bank_mask:0xf bound_ctrl:0
	v_fmac_f32_dpp v52, v52, v144 row_shl:2 row_mask:0xf bank_mask:0xf bound_ctrl:0
	v_fmac_f32_dpp v53, v53, v145 row_shl:2 row_mask:0xf bank_mask:0xf bound_ctrl:0
	v_fmac_f32_dpp v54, v54, v146 row_shl:2 row_mask:0xf bank_mask:0xf bound_ctrl:0
	v_fmac_f32_dpp v55, v55, v147 row_shl:2 row_mask:0xf bank_mask:0xf bound_ctrl:0
	v_fmac_f32_dpp v52, v168, v148 row_shl:2 row_mask:0xf bank_mask:0xf bound_ctrl:0
	v_fmac_f32_dpp v53, v169, v149 row_shl:2 row_mask:0xf bank_mask:0xf bound_ctrl:0
	v_fmac_f32_dpp v54, v170, v150 row_shl:2 row_mask:0xf bank_mask:0xf bound_ctrl:0
	v_fmac_f32_dpp v55, v171, v151 row_shl:2 row_mask:0xf bank_mask:0xf bound_ctrl:0
	ds_read_b128 v[144:147], v9 offset:1152
	ds_read_b128 v[148:151], v9 offset:1408
	s_waitcnt lgkmcnt(2)
	v_mov_b32_e32 v168, v56
	v_mov_b32_e32 v169, v57
	v_mov_b32_e32 v170, v58
	v_mov_b32_e32 v171, v59
	v_fmac_f32_dpp v56, v56, v152 row_shl:2 row_mask:0xf bank_mask:0xf bound_ctrl:0
	v_fmac_f32_dpp v57, v57, v153 row_shl:2 row_mask:0xf bank_mask:0xf bound_ctrl:0
	v_fmac_f32_dpp v58, v58, v154 row_shl:2 row_mask:0xf bank_mask:0xf bound_ctrl:0
	v_fmac_f32_dpp v59, v59, v155 row_shl:2 row_mask:0xf bank_mask:0xf bound_ctrl:0
	v_fmac_f32_dpp v56, v60, -v156 row_shl:2 row_mask:0xf bank_mask:0xf bound_ctrl:0
	v_fmac_f32_dpp v57, v61, -v157 row_shl:2 row_mask:0xf bank_mask:0xf bound_ctrl:0
	v_fmac_f32_dpp v58, v62, -v158 row_shl:2 row_mask:0xf bank_mask:0xf bound_ctrl:0
	v_fmac_f32_dpp v59, v63, -v159 row_shl:2 row_mask:0xf bank_mask:0xf bound_ctrl:0
	v_fmac_f32_dpp v60, v60, v152 row_shl:2 row_mask:0xf bank_mask:0xf bound_ctrl:0
	v_fmac_f32_dpp v61, v61, v153 row_shl:2 row_mask:0xf bank_mask:0xf bound_ctrl:0
	v_fmac_f32_dpp v62, v62, v154 row_shl:2 row_mask:0xf bank_mask:0xf bound_ctrl:0
	v_fmac_f32_dpp v63, v63, v155 row_shl:2 row_mask:0xf bank_mask:0xf bound_ctrl:0
	v_fmac_f32_dpp v60, v168, v156 row_shl:2 row_mask:0xf bank_mask:0xf bound_ctrl:0
	v_fmac_f32_dpp v61, v169, v157 row_shl:2 row_mask:0xf bank_mask:0xf bound_ctrl:0
	v_fmac_f32_dpp v62, v170, v158 row_shl:2 row_mask:0xf bank_mask:0xf bound_ctrl:0
	v_fmac_f32_dpp v63, v171, v159 row_shl:2 row_mask:0xf bank_mask:0xf bound_ctrl:0
	ds_read_b128 v[152:155], v9 offset:1216
	ds_read_b128 v[156:159], v9 offset:1472
	s_waitcnt lgkmcnt(2)
	v_mov_b32_e32 v168, v64
	v_mov_b32_e32 v169, v65
	v_mov_b32_e32 v170, v66
	v_mov_b32_e32 v171, v67
	v_fmac_f32_dpp v64, v64, v144 row_shl:2 row_mask:0xf bank_mask:0xf bound_ctrl:0
	v_fmac_f32_dpp v65, v65, v145 row_shl:2 row_mask:0xf bank_mask:0xf bound_ctrl:0
	v_fmac_f32_dpp v66, v66, v146 row_shl:2 row_mask:0xf bank_mask:0xf bound_ctrl:0
	v_fmac_f32_dpp v67, v67, v147 row_shl:2 row_mask:0xf bank_mask:0xf bound_ctrl:0
	v_fmac_f32_dpp v64, v68, -v148 row_shl:2 row_mask:0xf bank_mask:0xf bound_ctrl:0
	v_fmac_f32_dpp v65, v69, -v149 row_shl:2 row_mask:0xf bank_mask:0xf bound_ctrl:0
	v_fmac_f32_dpp v66, v70, -v150 row_shl:2 row_mask:0xf bank_mask:0xf bound_ctrl:0
	v_fmac_f32_dpp v67, v71, -v151 row_shl:2 row_mask:0xf bank_mask:0xf bound_ctrl:0
	v_fmac_f32_dpp v68, v68, v144 row_shl:2 row_mask:0xf bank_mask:0xf bound_ctrl:0
	v_fmac_f32_dpp v69, v69, v145 row_shl:2 row_mask:0xf bank_mask:0xf bound_ctrl:0
	v_fmac_f32_dpp v70, v70, v146 row_shl:2 row_mask:0xf bank_mask:0xf bound_ctrl:0
	v_fmac_f32_dpp v71, v71, v147 row_shl:2 row_mask:0xf bank_mask:0xf bound_ctrl:0
	v_fmac_f32_dpp v68, v168, v148 row_shl:2 row_mask:0xf bank_mask:0xf bound_ctrl:0
	v_fmac_f32_dpp v69, v169, v149 row_shl:2 row_mask:0xf bank_mask:0xf bound_ctrl:0
	v_fmac_f32_dpp v70, v170, v150 row_shl:2 row_mask:0xf bank_mask:0xf bound_ctrl:0
	v_fmac_f32_dpp v71, v171, v151 row_shl:2 row_mask:0xf bank_mask:0xf bound_ctrl:0
	ds_read_b128 v[144:147], v9 offset:1536
	ds_read_b128 v[148:151], v9 offset:1792
	s_waitcnt lgkmcnt(2)
	v_mov_b32_e32 v168, v72
	v_mov_b32_e32 v169, v73
	v_mov_b32_e32 v170, v74
	v_mov_b32_e32 v171, v75
	v_fmac_f32_dpp v72, v72, v152 row_shl:2 row_mask:0xf bank_mask:0xf bound_ctrl:0
	v_fmac_f32_dpp v73, v73, v153 row_shl:2 row_mask:0xf bank_mask:0xf bound_ctrl:0
	v_fmac_f32_dpp v74, v74, v154 row_shl:2 row_mask:0xf bank_mask:0xf bound_ctrl:0
	v_fmac_f32_dpp v75, v75, v155 row_shl:2 row_mask:0xf bank_mask:0xf bound_ctrl:0
	v_fmac_f32_dpp v72, v76, -v156 row_shl:2 row_mask:0xf bank_mask:0xf bound_ctrl:0
	v_fmac_f32_dpp v73, v77, -v157 row_shl:2 row_mask:0xf bank_mask:0xf bound_ctrl:0
	v_fmac_f32_dpp v74, v78, -v158 row_shl:2 row_mask:0xf bank_mask:0xf bound_ctrl:0
	v_fmac_f32_dpp v75, v79, -v159 row_shl:2 row_mask:0xf bank_mask:0xf bound_ctrl:0
	v_fmac_f32_dpp v76, v76, v152 row_shl:2 row_mask:0xf bank_mask:0xf bound_ctrl:0
	v_fmac_f32_dpp v77, v77, v153 row_shl:2 row_mask:0xf bank_mask:0xf bound_ctrl:0
	v_fmac_f32_dpp v78, v78, v154 row_shl:2 row_mask:0xf bank_mask:0xf bound_ctrl:0
	v_fmac_f32_dpp v79, v79, v155 row_shl:2 row_mask:0xf bank_mask:0xf bound_ctrl:0
	v_fmac_f32_dpp v76, v168, v156 row_shl:2 row_mask:0xf bank_mask:0xf bound_ctrl:0
	v_fmac_f32_dpp v77, v169, v157 row_shl:2 row_mask:0xf bank_mask:0xf bound_ctrl:0
	v_fmac_f32_dpp v78, v170, v158 row_shl:2 row_mask:0xf bank_mask:0xf bound_ctrl:0
	v_fmac_f32_dpp v79, v171, v159 row_shl:2 row_mask:0xf bank_mask:0xf bound_ctrl:0
	ds_read_b128 v[152:155], v9 offset:1600
	ds_read_b128 v[156:159], v9 offset:1856
	s_waitcnt lgkmcnt(2)
	v_mov_b32_e32 v168, v44
	v_mov_b32_e32 v169, v45
	v_mov_b32_e32 v170, v46
	v_mov_b32_e32 v171, v47
	v_fmac_f32_dpp v44, v44, v144 row_shl:4 row_mask:0xf bank_mask:0xf bound_ctrl:0
	v_fmac_f32_dpp v45, v45, v145 row_shl:4 row_mask:0xf bank_mask:0xf bound_ctrl:0
	v_fmac_f32_dpp v46, v46, v146 row_shl:4 row_mask:0xf bank_mask:0xf bound_ctrl:0
	v_fmac_f32_dpp v47, v47, v147 row_shl:4 row_mask:0xf bank_mask:0xf bound_ctrl:0
	v_fmac_f32_dpp v44, v52, -v148 row_shl:4 row_mask:0xf bank_mask:0xf bound_ctrl:0
	v_fmac_f32_dpp v45, v53, -v149 row_shl:4 row_mask:0xf bank_mask:0xf bound_ctrl:0
	v_fmac_f32_dpp v46, v54, -v150 row_shl:4 row_mask:0xf bank_mask:0xf bound_ctrl:0
	v_fmac_f32_dpp v47, v55, -v151 row_shl:4 row_mask:0xf bank_mask:0xf bound_ctrl:0
	v_fmac_f32_dpp v52, v52, v144 row_shl:4 row_mask:0xf bank_mask:0xf bound_ctrl:0
	v_fmac_f32_dpp v53, v53, v145 row_shl:4 row_mask:0xf bank_mask:0xf bound_ctrl:0
	v_fmac_f32_dpp v54, v54, v146 row_shl:4 row_mask:0xf bank_mask:0xf bound_ctrl:0
	v_fmac_f32_dpp v55, v55, v147 row_shl:4 row_mask:0xf bank_mask:0xf bound_ctrl:0
	v_fmac_f32_dpp v52, v168, v148 row_shl:4 row_mask:0xf bank_mask:0xf bound_ctrl:0
	v_fmac_f32_dpp v53, v169, v149 row_shl:4 row_mask:0xf bank_mask:0xf bound_ctrl:0
	v_fmac_f32_dpp v54, v170, v150 row_shl:4 row_mask:0xf bank_mask:0xf bound_ctrl:0
	v_fmac_f32_dpp v55, v171, v151 row_shl:4 row_mask:0xf bank_mask:0xf bound_ctrl:0
	ds_read_b128 v[144:147], v9 offset:1664
	ds_read_b128 v[148:151], v9 offset:1920
	s_waitcnt lgkmcnt(2)
	v_mov_b32_e32 v168, v56
	v_mov_b32_e32 v169, v57
	v_mov_b32_e32 v170, v58
	v_mov_b32_e32 v171, v59
	v_fmac_f32_dpp v56, v56, v152 row_shl:4 row_mask:0xf bank_mask:0xf bound_ctrl:0
	v_fmac_f32_dpp v57, v57, v153 row_shl:4 row_mask:0xf bank_mask:0xf bound_ctrl:0
	v_fmac_f32_dpp v58, v58, v154 row_shl:4 row_mask:0xf bank_mask:0xf bound_ctrl:0
	v_fmac_f32_dpp v59, v59, v155 row_shl:4 row_mask:0xf bank_mask:0xf bound_ctrl:0
	v_fmac_f32_dpp v56, v60, -v156 row_shl:4 row_mask:0xf bank_mask:0xf bound_ctrl:0
	v_fmac_f32_dpp v57, v61, -v157 row_shl:4 row_mask:0xf bank_mask:0xf bound_ctrl:0
	v_fmac_f32_dpp v58, v62, -v158 row_shl:4 row_mask:0xf bank_mask:0xf bound_ctrl:0
	v_fmac_f32_dpp v59, v63, -v159 row_shl:4 row_mask:0xf bank_mask:0xf bound_ctrl:0
	v_fmac_f32_dpp v60, v60, v152 row_shl:4 row_mask:0xf bank_mask:0xf bound_ctrl:0
	v_fmac_f32_dpp v61, v61, v153 row_shl:4 row_mask:0xf bank_mask:0xf bound_ctrl:0
	v_fmac_f32_dpp v62, v62, v154 row_shl:4 row_mask:0xf bank_mask:0xf bound_ctrl:0
	v_fmac_f32_dpp v63, v63, v155 row_shl:4 row_mask:0xf bank_mask:0xf bound_ctrl:0
	v_fmac_f32_dpp v60, v168, v156 row_shl:4 row_mask:0xf bank_mask:0xf bound_ctrl:0
	v_fmac_f32_dpp v61, v169, v157 row_shl:4 row_mask:0xf bank_mask:0xf bound_ctrl:0
	v_fmac_f32_dpp v62, v170, v158 row_shl:4 row_mask:0xf bank_mask:0xf bound_ctrl:0
	v_fmac_f32_dpp v63, v171, v159 row_shl:4 row_mask:0xf bank_mask:0xf bound_ctrl:0
	ds_read_b128 v[152:155], v9 offset:1728
	ds_read_b128 v[156:159], v9 offset:1984
	s_waitcnt lgkmcnt(2)
	v_mov_b32_e32 v168, v64
	v_mov_b32_e32 v169, v65
	v_mov_b32_e32 v170, v66
	v_mov_b32_e32 v171, v67
	v_fmac_f32_dpp v64, v64, v144 row_shl:4 row_mask:0xf bank_mask:0xf bound_ctrl:0
	v_fmac_f32_dpp v65, v65, v145 row_shl:4 row_mask:0xf bank_mask:0xf bound_ctrl:0
	v_fmac_f32_dpp v66, v66, v146 row_shl:4 row_mask:0xf bank_mask:0xf bound_ctrl:0
	v_fmac_f32_dpp v67, v67, v147 row_shl:4 row_mask:0xf bank_mask:0xf bound_ctrl:0
	v_fmac_f32_dpp v64, v68, -v148 row_shl:4 row_mask:0xf bank_mask:0xf bound_ctrl:0
	v_fmac_f32_dpp v65, v69, -v149 row_shl:4 row_mask:0xf bank_mask:0xf bound_ctrl:0
	v_fmac_f32_dpp v66, v70, -v150 row_shl:4 row_mask:0xf bank_mask:0xf bound_ctrl:0
	v_fmac_f32_dpp v67, v71, -v151 row_shl:4 row_mask:0xf bank_mask:0xf bound_ctrl:0
	v_fmac_f32_dpp v68, v68, v144 row_shl:4 row_mask:0xf bank_mask:0xf bound_ctrl:0
	v_fmac_f32_dpp v69, v69, v145 row_shl:4 row_mask:0xf bank_mask:0xf bound_ctrl:0
	v_fmac_f32_dpp v70, v70, v146 row_shl:4 row_mask:0xf bank_mask:0xf bound_ctrl:0
	v_fmac_f32_dpp v71, v71, v147 row_shl:4 row_mask:0xf bank_mask:0xf bound_ctrl:0
	v_fmac_f32_dpp v68, v168, v148 row_shl:4 row_mask:0xf bank_mask:0xf bound_ctrl:0
	v_fmac_f32_dpp v69, v169, v149 row_shl:4 row_mask:0xf bank_mask:0xf bound_ctrl:0
	v_fmac_f32_dpp v70, v170, v150 row_shl:4 row_mask:0xf bank_mask:0xf bound_ctrl:0
	v_fmac_f32_dpp v71, v171, v151 row_shl:4 row_mask:0xf bank_mask:0xf bound_ctrl:0
	ds_read_b128 v[144:147], v9 offset:2048
	ds_read_b128 v[148:151], v9 offset:2304
	s_waitcnt lgkmcnt(2)
	v_mov_b32_e32 v168, v72
	v_mov_b32_e32 v169, v73
	v_mov_b32_e32 v170, v74
	v_mov_b32_e32 v171, v75
	v_fmac_f32_dpp v72, v72, v152 row_shl:4 row_mask:0xf bank_mask:0xf bound_ctrl:0
	v_fmac_f32_dpp v73, v73, v153 row_shl:4 row_mask:0xf bank_mask:0xf bound_ctrl:0
	v_fmac_f32_dpp v74, v74, v154 row_shl:4 row_mask:0xf bank_mask:0xf bound_ctrl:0
	v_fmac_f32_dpp v75, v75, v155 row_shl:4 row_mask:0xf bank_mask:0xf bound_ctrl:0
	v_fmac_f32_dpp v72, v76, -v156 row_shl:4 row_mask:0xf bank_mask:0xf bound_ctrl:0
	v_fmac_f32_dpp v73, v77, -v157 row_shl:4 row_mask:0xf bank_mask:0xf bound_ctrl:0
	v_fmac_f32_dpp v74, v78, -v158 row_shl:4 row_mask:0xf bank_mask:0xf bound_ctrl:0
	v_fmac_f32_dpp v75, v79, -v159 row_shl:4 row_mask:0xf bank_mask:0xf bound_ctrl:0
	v_fmac_f32_dpp v76, v76, v152 row_shl:4 row_mask:0xf bank_mask:0xf bound_ctrl:0
	v_fmac_f32_dpp v77, v77, v153 row_shl:4 row_mask:0xf bank_mask:0xf bound_ctrl:0
	v_fmac_f32_dpp v78, v78, v154 row_shl:4 row_mask:0xf bank_mask:0xf bound_ctrl:0
	v_fmac_f32_dpp v79, v79, v155 row_shl:4 row_mask:0xf bank_mask:0xf bound_ctrl:0
	v_fmac_f32_dpp v76, v168, v156 row_shl:4 row_mask:0xf bank_mask:0xf bound_ctrl:0
	v_fmac_f32_dpp v77, v169, v157 row_shl:4 row_mask:0xf bank_mask:0xf bound_ctrl:0
	v_fmac_f32_dpp v78, v170, v158 row_shl:4 row_mask:0xf bank_mask:0xf bound_ctrl:0
	v_fmac_f32_dpp v79, v171, v159 row_shl:4 row_mask:0xf bank_mask:0xf bound_ctrl:0
	ds_read_b128 v[152:155], v9 offset:2112
	ds_read_b128 v[156:159], v9 offset:2368
	s_waitcnt lgkmcnt(2)
	v_mov_b32_e32 v168, v44
	v_mov_b32_e32 v169, v45
	v_mov_b32_e32 v170, v46
	v_mov_b32_e32 v171, v47
	v_fmac_f32_dpp v44, v44, v144 row_shl:8 row_mask:0xf bank_mask:0xf bound_ctrl:0
	v_fmac_f32_dpp v45, v45, v145 row_shl:8 row_mask:0xf bank_mask:0xf bound_ctrl:0
	v_fmac_f32_dpp v46, v46, v146 row_shl:8 row_mask:0xf bank_mask:0xf bound_ctrl:0
	v_fmac_f32_dpp v47, v47, v147 row_shl:8 row_mask:0xf bank_mask:0xf bound_ctrl:0
	v_fmac_f32_dpp v44, v52, -v148 row_shl:8 row_mask:0xf bank_mask:0xf bound_ctrl:0
	v_fmac_f32_dpp v45, v53, -v149 row_shl:8 row_mask:0xf bank_mask:0xf bound_ctrl:0
	v_fmac_f32_dpp v46, v54, -v150 row_shl:8 row_mask:0xf bank_mask:0xf bound_ctrl:0
	v_fmac_f32_dpp v47, v55, -v151 row_shl:8 row_mask:0xf bank_mask:0xf bound_ctrl:0
	v_fmac_f32_dpp v52, v52, v144 row_shl:8 row_mask:0xf bank_mask:0xf bound_ctrl:0
	v_fmac_f32_dpp v53, v53, v145 row_shl:8 row_mask:0xf bank_mask:0xf bound_ctrl:0
	v_fmac_f32_dpp v54, v54, v146 row_shl:8 row_mask:0xf bank_mask:0xf bound_ctrl:0
	v_fmac_f32_dpp v55, v55, v147 row_shl:8 row_mask:0xf bank_mask:0xf bound_ctrl:0
	v_fmac_f32_dpp v52, v168, v148 row_shl:8 row_mask:0xf bank_mask:0xf bound_ctrl:0
	v_fmac_f32_dpp v53, v169, v149 row_shl:8 row_mask:0xf bank_mask:0xf bound_ctrl:0
	v_fmac_f32_dpp v54, v170, v150 row_shl:8 row_mask:0xf bank_mask:0xf bound_ctrl:0
	v_fmac_f32_dpp v55, v171, v151 row_shl:8 row_mask:0xf bank_mask:0xf bound_ctrl:0
	ds_read_b128 v[144:147], v9 offset:2176
	ds_read_b128 v[148:151], v9 offset:2432
	s_waitcnt lgkmcnt(2)
	v_mov_b32_e32 v168, v56
	v_mov_b32_e32 v169, v57
	v_mov_b32_e32 v170, v58
	v_mov_b32_e32 v171, v59
	v_fmac_f32_dpp v56, v56, v152 row_shl:8 row_mask:0xf bank_mask:0xf bound_ctrl:0
	v_fmac_f32_dpp v57, v57, v153 row_shl:8 row_mask:0xf bank_mask:0xf bound_ctrl:0
	v_fmac_f32_dpp v58, v58, v154 row_shl:8 row_mask:0xf bank_mask:0xf bound_ctrl:0
	v_fmac_f32_dpp v59, v59, v155 row_shl:8 row_mask:0xf bank_mask:0xf bound_ctrl:0
	v_fmac_f32_dpp v56, v60, -v156 row_shl:8 row_mask:0xf bank_mask:0xf bound_ctrl:0
	v_fmac_f32_dpp v57, v61, -v157 row_shl:8 row_mask:0xf bank_mask:0xf bound_ctrl:0
	v_fmac_f32_dpp v58, v62, -v158 row_shl:8 row_mask:0xf bank_mask:0xf bound_ctrl:0
	v_fmac_f32_dpp v59, v63, -v159 row_shl:8 row_mask:0xf bank_mask:0xf bound_ctrl:0
	v_fmac_f32_dpp v60, v60, v152 row_shl:8 row_mask:0xf bank_mask:0xf bound_ctrl:0
	v_fmac_f32_dpp v61, v61, v153 row_shl:8 row_mask:0xf bank_mask:0xf bound_ctrl:0
	v_fmac_f32_dpp v62, v62, v154 row_shl:8 row_mask:0xf bank_mask:0xf bound_ctrl:0
	v_fmac_f32_dpp v63, v63, v155 row_shl:8 row_mask:0xf bank_mask:0xf bound_ctrl:0
	v_fmac_f32_dpp v60, v168, v156 row_shl:8 row_mask:0xf bank_mask:0xf bound_ctrl:0
	v_fmac_f32_dpp v61, v169, v157 row_shl:8 row_mask:0xf bank_mask:0xf bound_ctrl:0
	v_fmac_f32_dpp v62, v170, v158 row_shl:8 row_mask:0xf bank_mask:0xf bound_ctrl:0
	v_fmac_f32_dpp v63, v171, v159 row_shl:8 row_mask:0xf bank_mask:0xf bound_ctrl:0
	ds_read_b128 v[152:155], v9 offset:2240
	ds_read_b128 v[156:159], v9 offset:2496
	s_waitcnt lgkmcnt(2)
	v_mov_b32_e32 v168, v64
	v_mov_b32_e32 v169, v65
	v_mov_b32_e32 v170, v66
	v_mov_b32_e32 v171, v67
	v_fmac_f32_dpp v64, v64, v144 row_shl:8 row_mask:0xf bank_mask:0xf bound_ctrl:0
	v_fmac_f32_dpp v65, v65, v145 row_shl:8 row_mask:0xf bank_mask:0xf bound_ctrl:0
	v_fmac_f32_dpp v66, v66, v146 row_shl:8 row_mask:0xf bank_mask:0xf bound_ctrl:0
	v_fmac_f32_dpp v67, v67, v147 row_shl:8 row_mask:0xf bank_mask:0xf bound_ctrl:0
	v_fmac_f32_dpp v64, v68, -v148 row_shl:8 row_mask:0xf bank_mask:0xf bound_ctrl:0
	v_fmac_f32_dpp v65, v69, -v149 row_shl:8 row_mask:0xf bank_mask:0xf bound_ctrl:0
	v_fmac_f32_dpp v66, v70, -v150 row_shl:8 row_mask:0xf bank_mask:0xf bound_ctrl:0
	v_fmac_f32_dpp v67, v71, -v151 row_shl:8 row_mask:0xf bank_mask:0xf bound_ctrl:0
	v_fmac_f32_dpp v68, v68, v144 row_shl:8 row_mask:0xf bank_mask:0xf bound_ctrl:0
	v_fmac_f32_dpp v69, v69, v145 row_shl:8 row_mask:0xf bank_mask:0xf bound_ctrl:0
	v_fmac_f32_dpp v70, v70, v146 row_shl:8 row_mask:0xf bank_mask:0xf bound_ctrl:0
	v_fmac_f32_dpp v71, v71, v147 row_shl:8 row_mask:0xf bank_mask:0xf bound_ctrl:0
	v_fmac_f32_dpp v68, v168, v148 row_shl:8 row_mask:0xf bank_mask:0xf bound_ctrl:0
	v_fmac_f32_dpp v69, v169, v149 row_shl:8 row_mask:0xf bank_mask:0xf bound_ctrl:0
	v_fmac_f32_dpp v70, v170, v150 row_shl:8 row_mask:0xf bank_mask:0xf bound_ctrl:0
	v_fmac_f32_dpp v71, v171, v151 row_shl:8 row_mask:0xf bank_mask:0xf bound_ctrl:0
	s_waitcnt lgkmcnt(0)
	v_mov_b32_e32 v168, v72
	v_mov_b32_e32 v169, v73
	v_mov_b32_e32 v170, v74
	v_mov_b32_e32 v171, v75
	v_fmac_f32_dpp v72, v72, v152 row_shl:8 row_mask:0xf bank_mask:0xf bound_ctrl:0
	v_fmac_f32_dpp v73, v73, v153 row_shl:8 row_mask:0xf bank_mask:0xf bound_ctrl:0
	v_fmac_f32_dpp v74, v74, v154 row_shl:8 row_mask:0xf bank_mask:0xf bound_ctrl:0
	v_fmac_f32_dpp v75, v75, v155 row_shl:8 row_mask:0xf bank_mask:0xf bound_ctrl:0
	v_fmac_f32_dpp v72, v76, -v156 row_shl:8 row_mask:0xf bank_mask:0xf bound_ctrl:0
	v_fmac_f32_dpp v73, v77, -v157 row_shl:8 row_mask:0xf bank_mask:0xf bound_ctrl:0
	v_fmac_f32_dpp v74, v78, -v158 row_shl:8 row_mask:0xf bank_mask:0xf bound_ctrl:0
	v_fmac_f32_dpp v75, v79, -v159 row_shl:8 row_mask:0xf bank_mask:0xf bound_ctrl:0
	v_fmac_f32_dpp v76, v76, v152 row_shl:8 row_mask:0xf bank_mask:0xf bound_ctrl:0
	v_fmac_f32_dpp v77, v77, v153 row_shl:8 row_mask:0xf bank_mask:0xf bound_ctrl:0
	v_fmac_f32_dpp v78, v78, v154 row_shl:8 row_mask:0xf bank_mask:0xf bound_ctrl:0
	v_fmac_f32_dpp v79, v79, v155 row_shl:8 row_mask:0xf bank_mask:0xf bound_ctrl:0
	v_fmac_f32_dpp v76, v168, v156 row_shl:8 row_mask:0xf bank_mask:0xf bound_ctrl:0
	v_fmac_f32_dpp v77, v169, v157 row_shl:8 row_mask:0xf bank_mask:0xf bound_ctrl:0
	v_fmac_f32_dpp v78, v170, v158 row_shl:8 row_mask:0xf bank_mask:0xf bound_ctrl:0
	v_fmac_f32_dpp v79, v171, v159 row_shl:8 row_mask:0xf bank_mask:0xf bound_ctrl:0
	s_nop 1
	s_mov_b64 exec, s[52:53]
	global_store_dword v10, v44, s[36:37] offset:0
	global_store_dword v10, v52, s[36:37] offset:4
	global_store_dword v10, v45, s[36:37] offset:8
	global_store_dword v10, v53, s[36:37] offset:12
	global_store_dword v10, v46, s[36:37] offset:16
	global_store_dword v10, v54, s[36:37] offset:20
	global_store_dword v10, v47, s[36:37] offset:24
	global_store_dword v10, v55, s[36:37] offset:28
	global_store_dword v10, v56, s[36:37] offset:128
	global_store_dword v10, v60, s[36:37] offset:132
	global_store_dword v10, v57, s[36:37] offset:136
	global_store_dword v10, v61, s[36:37] offset:140
	global_store_dword v10, v58, s[36:37] offset:144
	global_store_dword v10, v62, s[36:37] offset:148
	global_store_dword v10, v59, s[36:37] offset:152
	global_store_dword v10, v63, s[36:37] offset:156
	global_store_dword v10, v64, s[36:37] offset:256
	global_store_dword v10, v68, s[36:37] offset:260
	global_store_dword v10, v65, s[36:37] offset:264
	global_store_dword v10, v69, s[36:37] offset:268
	global_store_dword v10, v66, s[36:37] offset:272
	global_store_dword v10, v70, s[36:37] offset:276
	global_store_dword v10, v67, s[36:37] offset:280
	global_store_dword v10, v71, s[36:37] offset:284
	global_store_dword v10, v72, s[36:37] offset:384
	global_store_dword v10, v76, s[36:37] offset:388
	global_store_dword v10, v73, s[36:37] offset:392
	global_store_dword v10, v77, s[36:37] offset:396
	global_store_dword v10, v74, s[36:37] offset:400
	global_store_dword v10, v78, s[36:37] offset:404
	global_store_dword v10, v75, s[36:37] offset:408
	global_store_dword v10, v79, s[36:37] offset:412
	s_mov_b64 exec, -1
	s_lshl_b32 s6, s4, 1
	s_add_i32 s6, s6, 1
	s_lshl_b32 s55, s0, 15
	s_lshl_b32 s56, s6, 6
	s_add_u32 s55, s55, s56
	s_add_u32 s8, s94, 0x8a40000
	s_addc_u32 s9, s95, 0
	s_add_u32 s8, s8, s55
	s_addc_u32 s9, s9, 0
	global_load_dwordx4 v[180:183], v5, s[8:9] offset:0
	global_load_dwordx4 v[184:187], v5, s[8:9] offset:1024
	s_add_i32 s55, s6, 0
	s_lshl_b32 s56, s55, 13
	s_add_u32 s12, s94, 0x12d96000
	s_addc_u32 s13, s95, 0
	s_add_u32 s12, s12, s56
	s_addc_u32 s13, s13, 0
	s_lshl_b32 s56, s55, 9
	s_add_u32 s38, s94, 0x12d92000
	s_addc_u32 s39, s95, 0
	s_add_u32 s38, s38, s56
	s_addc_u32 s39, s39, 0
	s_lshl_b32 s56, s0, 5
	s_lshl_b32 s55, s6, 1
	s_add_i32 s56, s56, s55
	s_add_i32 s56, s56, 0
	s_lshl_b32 s56, s56, 9
	s_add_u32 s36, s94, 0x12dd6000
	s_addc_u32 s37, s95, 0
	s_add_u32 s36, s36, s56
	s_addc_u32 s37, s37, 0
	global_load_dwordx2 v[2:3], v7, s[38:39]
	global_load_dwordx4 v[12:15], v6, s[12:13] offset:0
	global_load_dwordx4 v[16:19], v6, s[12:13] offset:1024
	global_load_dwordx4 v[20:23], v6, s[12:13] offset:256
	global_load_dwordx4 v[24:27], v6, s[12:13] offset:1280
	global_load_dwordx4 v[28:31], v6, s[12:13] offset:512
	global_load_dwordx4 v[32:35], v6, s[12:13] offset:1536
	global_load_dwordx4 v[36:39], v6, s[12:13] offset:768
	global_load_dwordx4 v[40:43], v6, s[12:13] offset:1792
	s_waitcnt vmcnt(8)
	ds_write_b32 v8, v2 offset:0
	ds_write_b32 v8, v3 offset:256
	v_mul_f32_e32 v168, v3, v3
	v_mul_f32_e32 v169, v2, v3
	v_fma_f32 v2, v2, v2, -v168
	v_add_f32_e32 v3, v169, v169
	ds_write_b32 v8, v2 offset:512
	ds_write_b32 v8, v3 offset:768
	v_mul_f32_e32 v168, v3, v3
	v_mul_f32_e32 v169, v2, v3
	v_fma_f32 v2, v2, v2, -v168
	v_add_f32_e32 v3, v169, v169
	ds_write_b32 v8, v2 offset:1024
	ds_write_b32 v8, v3 offset:1280
	v_mul_f32_e32 v168, v3, v3
	v_mul_f32_e32 v169, v2, v3
	v_fma_f32 v2, v2, v2, -v168
	v_add_f32_e32 v3, v169, v169
	ds_write_b32 v8, v2 offset:1536
	ds_write_b32 v8, v3 offset:1792
	v_mul_f32_e32 v168, v3, v3
	v_mul_f32_e32 v169, v2, v3
	v_fma_f32 v2, v2, v2, -v168
	v_add_f32_e32 v3, v169, v169
	ds_write_b32 v8, v2 offset:2048
	ds_write_b32 v8, v3 offset:2304
	s_waitcnt lgkmcnt(0)
	s_waitcnt vmcnt(7)
	v_mfma_f32_16x16x4_f32 v[44:47], v12, v180, 0
	v_mfma_f32_16x16x4_f32 v[52:55], v13, v180, 0
	v_mfma_f32_16x16x4_f32 v[80:83], v12, v184, 0
	v_mfma_f32_16x16x4_f32 v[84:87], v13, v184, 0
	s_waitcnt vmcnt(5)
	v_mfma_f32_16x16x4_f32 v[56:59], v20, v180, 0
	v_mfma_f32_16x16x4_f32 v[60:63], v21, v180, 0
	v_mfma_f32_16x16x4_f32 v[112:115], v20, v184, 0
	v_mfma_f32_16x16x4_f32 v[116:119], v21, v184, 0
	s_waitcnt vmcnt(3)
	v_mfma_f32_16x16x4_f32 v[64:67], v28, v180, 0
	v_mfma_f32_16x16x4_f32 v[68:71], v29, v180, 0
	v_mfma_f32_16x16x4_f32 v[120:123], v28, v184, 0
	v_mfma_f32_16x16x4_f32 v[124:127], v29, v184, 0
	s_waitcnt vmcnt(1)
	v_mfma_f32_16x16x4_f32 v[72:75], v36, v180, 0
	v_mfma_f32_16x16x4_f32 v[76:79], v37, v180, 0
	v_mfma_f32_16x16x4_f32 v[128:131], v36, v184, 0
	v_mfma_f32_16x16x4_f32 v[140:143], v37, v184, 0
	v_mfma_f32_16x16x4_f32 v[44:47], v14, v181, v[44:47]
	v_mfma_f32_16x16x4_f32 v[52:55], v15, v181, v[52:55]
	v_mfma_f32_16x16x4_f32 v[80:83], v14, v185, v[80:83]
	v_mfma_f32_16x16x4_f32 v[84:87], v15, v185, v[84:87]
	v_mfma_f32_16x16x4_f32 v[56:59], v22, v181, v[56:59]
	v_mfma_f32_16x16x4_f32 v[60:63], v23, v181, v[60:63]
	v_mfma_f32_16x16x4_f32 v[112:115], v22, v185, v[112:115]
	v_mfma_f32_16x16x4_f32 v[116:119], v23, v185, v[116:119]
	v_mfma_f32_16x16x4_f32 v[64:67], v30, v181, v[64:67]
	v_mfma_f32_16x16x4_f32 v[68:71], v31, v181, v[68:71]
	v_mfma_f32_16x16x4_f32 v[120:123], v30, v185, v[120:123]
	v_mfma_f32_16x16x4_f32 v[124:127], v31, v185, v[124:127]
	v_mfma_f32_16x16x4_f32 v[72:75], v38, v181, v[72:75]
	v_mfma_f32_16x16x4_f32 v[76:79], v39, v181, v[76:79]
	v_mfma_f32_16x16x4_f32 v[128:131], v38, v185, v[128:131]
	v_mfma_f32_16x16x4_f32 v[140:143], v39, v185, v[140:143]
	v_mfma_f32_16x16x4_f32 v[44:47], v16, v182, v[44:47]
	v_mfma_f32_16x16x4_f32 v[52:55], v17, v182, v[52:55]
	v_mfma_f32_16x16x4_f32 v[80:83], v16, v186, v[80:83]
	v_mfma_f32_16x16x4_f32 v[84:87], v17, v186, v[84:87]
	v_mfma_f32_16x16x4_f32 v[56:59], v24, v182, v[56:59]
	v_mfma_f32_16x16x4_f32 v[60:63], v25, v182, v[60:63]
	v_mfma_f32_16x16x4_f32 v[112:115], v24, v186, v[112:115]
	v_mfma_f32_16x16x4_f32 v[116:119], v25, v186, v[116:119]
	v_mfma_f32_16x16x4_f32 v[64:67], v32, v182, v[64:67]
	v_mfma_f32_16x16x4_f32 v[68:71], v33, v182, v[68:71]
	v_mfma_f32_16x16x4_f32 v[120:123], v32, v186, v[120:123]
	v_mfma_f32_16x16x4_f32 v[124:127], v33, v186, v[124:127]
	s_waitcnt vmcnt(0)
	v_mfma_f32_16x16x4_f32 v[72:75], v40, v182, v[72:75]
	v_mfma_f32_16x16x4_f32 v[76:79], v41, v182, v[76:79]
	v_mfma_f32_16x16x4_f32 v[128:131], v40, v186, v[128:131]
	v_mfma_f32_16x16x4_f32 v[140:143], v41, v186, v[140:143]
	v_mfma_f32_16x16x4_f32 v[44:47], v18, v183, v[44:47]
	v_mfma_f32_16x16x4_f32 v[52:55], v19, v183, v[52:55]
	v_mfma_f32_16x16x4_f32 v[80:83], v18, v187, v[80:83]
	v_mfma_f32_16x16x4_f32 v[84:87], v19, v187, v[84:87]
	v_mfma_f32_16x16x4_f32 v[56:59], v26, v183, v[56:59]
	v_mfma_f32_16x16x4_f32 v[60:63], v27, v183, v[60:63]
	v_mfma_f32_16x16x4_f32 v[112:115], v26, v187, v[112:115]
	v_mfma_f32_16x16x4_f32 v[116:119], v27, v187, v[116:119]
	v_mfma_f32_16x16x4_f32 v[64:67], v34, v183, v[64:67]
	v_mfma_f32_16x16x4_f32 v[68:71], v35, v183, v[68:71]
	v_mfma_f32_16x16x4_f32 v[120:123], v34, v187, v[120:123]
	v_mfma_f32_16x16x4_f32 v[124:127], v35, v187, v[124:127]
	v_mfma_f32_16x16x4_f32 v[72:75], v42, v183, v[72:75]
	v_mfma_f32_16x16x4_f32 v[76:79], v43, v183, v[76:79]
	v_mfma_f32_16x16x4_f32 v[128:131], v42, v187, v[128:131]
	v_mfma_f32_16x16x4_f32 v[140:143], v43, v187, v[140:143]
	s_nop 9
	ds_read_b128 v[144:147], v9 offset:0
	ds_read_b128 v[148:151], v9 offset:256
	ds_read_b128 v[152:155], v9 offset:64
	ds_read_b128 v[156:159], v9 offset:320
	s_waitcnt lgkmcnt(2)
	v_fmac_f32_e32 v80, v144, v44
	v_fmac_f32_e32 v81, v145, v45
	v_fmac_f32_e32 v82, v146, v46
	v_fmac_f32_e32 v83, v147, v47
	v_fma_f32 v80, -v148, v52, v80
	v_fma_f32 v81, -v149, v53, v81
	v_fma_f32 v82, -v150, v54, v82
	v_fma_f32 v83, -v151, v55, v83
	v_fmac_f32_e32 v84, v144, v52
	v_fmac_f32_e32 v85, v145, v53
	v_fmac_f32_e32 v86, v146, v54
	v_fmac_f32_e32 v87, v147, v55
	v_fmac_f32_e32 v84, v148, v44
	v_fmac_f32_e32 v85, v149, v45
	v_fmac_f32_e32 v86, v150, v46
	v_fmac_f32_e32 v87, v151, v47
	ds_read_b128 v[144:147], v9 offset:128
	ds_read_b128 v[148:151], v9 offset:384
	s_waitcnt lgkmcnt(2)
	v_fmac_f32_e32 v112, v152, v56
	v_fmac_f32_e32 v113, v153, v57
	v_fmac_f32_e32 v114, v154, v58
	v_fmac_f32_e32 v115, v155, v59
	v_fma_f32 v112, -v156, v60, v112
	v_fma_f32 v113, -v157, v61, v113
	v_fma_f32 v114, -v158, v62, v114
	v_fma_f32 v115, -v159, v63, v115
	v_fmac_f32_e32 v116, v152, v60
	v_fmac_f32_e32 v117, v153, v61
	v_fmac_f32_e32 v118, v154, v62
	v_fmac_f32_e32 v119, v155, v63
	v_fmac_f32_e32 v116, v156, v56
	v_fmac_f32_e32 v117, v157, v57
	v_fmac_f32_e32 v118, v158, v58
	v_fmac_f32_e32 v119, v159, v59
	ds_read_b128 v[152:155], v9 offset:192
	ds_read_b128 v[156:159], v9 offset:448
	s_waitcnt lgkmcnt(2)
	v_fmac_f32_e32 v120, v144, v64
	v_fmac_f32_e32 v121, v145, v65
	v_fmac_f32_e32 v122, v146, v66
	v_fmac_f32_e32 v123, v147, v67
	v_fma_f32 v120, -v148, v68, v120
	v_fma_f32 v121, -v149, v69, v121
	v_fma_f32 v122, -v150, v70, v122
	v_fma_f32 v123, -v151, v71, v123
	v_fmac_f32_e32 v124, v144, v68
	v_fmac_f32_e32 v125, v145, v69
	v_fmac_f32_e32 v126, v146, v70
	v_fmac_f32_e32 v127, v147, v71
	v_fmac_f32_e32 v124, v148, v64
	v_fmac_f32_e32 v125, v149, v65
	v_fmac_f32_e32 v126, v150, v66
	v_fmac_f32_e32 v127, v151, v67
	s_waitcnt lgkmcnt(0)
	v_fmac_f32_e32 v128, v152, v72
	v_fmac_f32_e32 v129, v153, v73
	v_fmac_f32_e32 v130, v154, v74
	v_fmac_f32_e32 v131, v155, v75
	v_fma_f32 v128, -v156, v76, v128
	v_fma_f32 v129, -v157, v77, v129
	v_fma_f32 v130, -v158, v78, v130
	v_fma_f32 v131, -v159, v79, v131
	v_fmac_f32_e32 v140, v152, v76
	v_fmac_f32_e32 v141, v153, v77
	v_fmac_f32_e32 v142, v154, v78
	v_fmac_f32_e32 v143, v155, v79
	v_fmac_f32_e32 v140, v156, v72
	v_fmac_f32_e32 v141, v157, v73
	v_fmac_f32_e32 v142, v158, v74
	v_fmac_f32_e32 v143, v159, v75
	ds_read_b128 v[144:147], v9 offset:512
	ds_read_b128 v[148:151], v9 offset:768
	ds_read_b128 v[152:155], v9 offset:576
	ds_read_b128 v[156:159], v9 offset:832
	s_waitcnt lgkmcnt(2)
	v_mov_b32_e32 v168, v80
	v_mov_b32_e32 v169, v81
	v_mov_b32_e32 v170, v82
	v_mov_b32_e32 v171, v83
	s_nop 1
	v_fmac_f32_dpp v80, v80, v144 row_shr:1 row_mask:0xf bank_mask:0xf bound_ctrl:0
	v_fmac_f32_dpp v81, v81, v145 row_shr:1 row_mask:0xf bank_mask:0xf bound_ctrl:0
	v_fmac_f32_dpp v82, v82, v146 row_shr:1 row_mask:0xf bank_mask:0xf bound_ctrl:0
	v_fmac_f32_dpp v83, v83, v147 row_shr:1 row_mask:0xf bank_mask:0xf bound_ctrl:0
	v_fmac_f32_dpp v80, v84, -v148 row_shr:1 row_mask:0xf bank_mask:0xf bound_ctrl:0
	v_fmac_f32_dpp v81, v85, -v149 row_shr:1 row_mask:0xf bank_mask:0xf bound_ctrl:0
	v_fmac_f32_dpp v82, v86, -v150 row_shr:1 row_mask:0xf bank_mask:0xf bound_ctrl:0
	v_fmac_f32_dpp v83, v87, -v151 row_shr:1 row_mask:0xf bank_mask:0xf bound_ctrl:0
	v_fmac_f32_dpp v84, v84, v144 row_shr:1 row_mask:0xf bank_mask:0xf bound_ctrl:0
	v_fmac_f32_dpp v85, v85, v145 row_shr:1 row_mask:0xf bank_mask:0xf bound_ctrl:0
	v_fmac_f32_dpp v86, v86, v146 row_shr:1 row_mask:0xf bank_mask:0xf bound_ctrl:0
	v_fmac_f32_dpp v87, v87, v147 row_shr:1 row_mask:0xf bank_mask:0xf bound_ctrl:0
	v_fmac_f32_dpp v84, v168, v148 row_shr:1 row_mask:0xf bank_mask:0xf bound_ctrl:0
	v_fmac_f32_dpp v85, v169, v149 row_shr:1 row_mask:0xf bank_mask:0xf bound_ctrl:0
	v_fmac_f32_dpp v86, v170, v150 row_shr:1 row_mask:0xf bank_mask:0xf bound_ctrl:0
	v_fmac_f32_dpp v87, v171, v151 row_shr:1 row_mask:0xf bank_mask:0xf bound_ctrl:0
	ds_read_b128 v[144:147], v9 offset:640
	ds_read_b128 v[148:151], v9 offset:896
	s_waitcnt lgkmcnt(2)
	v_mov_b32_e32 v168, v112
	v_mov_b32_e32 v169, v113
	v_mov_b32_e32 v170, v114
	v_mov_b32_e32 v171, v115
	v_fmac_f32_dpp v112, v112, v152 row_shr:1 row_mask:0xf bank_mask:0xf bound_ctrl:0
	v_fmac_f32_dpp v113, v113, v153 row_shr:1 row_mask:0xf bank_mask:0xf bound_ctrl:0
	v_fmac_f32_dpp v114, v114, v154 row_shr:1 row_mask:0xf bank_mask:0xf bound_ctrl:0
	v_fmac_f32_dpp v115, v115, v155 row_shr:1 row_mask:0xf bank_mask:0xf bound_ctrl:0
	v_fmac_f32_dpp v112, v116, -v156 row_shr:1 row_mask:0xf bank_mask:0xf bound_ctrl:0
	v_fmac_f32_dpp v113, v117, -v157 row_shr:1 row_mask:0xf bank_mask:0xf bound_ctrl:0
	v_fmac_f32_dpp v114, v118, -v158 row_shr:1 row_mask:0xf bank_mask:0xf bound_ctrl:0
	v_fmac_f32_dpp v115, v119, -v159 row_shr:1 row_mask:0xf bank_mask:0xf bound_ctrl:0
	v_fmac_f32_dpp v116, v116, v152 row_shr:1 row_mask:0xf bank_mask:0xf bound_ctrl:0
	v_fmac_f32_dpp v117, v117, v153 row_shr:1 row_mask:0xf bank_mask:0xf bound_ctrl:0
	v_fmac_f32_dpp v118, v118, v154 row_shr:1 row_mask:0xf bank_mask:0xf bound_ctrl:0
	v_fmac_f32_dpp v119, v119, v155 row_shr:1 row_mask:0xf bank_mask:0xf bound_ctrl:0
	v_fmac_f32_dpp v116, v168, v156 row_shr:1 row_mask:0xf bank_mask:0xf bound_ctrl:0
	v_fmac_f32_dpp v117, v169, v157 row_shr:1 row_mask:0xf bank_mask:0xf bound_ctrl:0
	v_fmac_f32_dpp v118, v170, v158 row_shr:1 row_mask:0xf bank_mask:0xf bound_ctrl:0
	v_fmac_f32_dpp v119, v171, v159 row_shr:1 row_mask:0xf bank_mask:0xf bound_ctrl:0
	ds_read_b128 v[152:155], v9 offset:704
	ds_read_b128 v[156:159], v9 offset:960
	s_waitcnt lgkmcnt(2)
	v_mov_b32_e32 v168, v120
	v_mov_b32_e32 v169, v121
	v_mov_b32_e32 v170, v122
	v_mov_b32_e32 v171, v123
	v_fmac_f32_dpp v120, v120, v144 row_shr:1 row_mask:0xf bank_mask:0xf bound_ctrl:0
	v_fmac_f32_dpp v121, v121, v145 row_shr:1 row_mask:0xf bank_mask:0xf bound_ctrl:0
	v_fmac_f32_dpp v122, v122, v146 row_shr:1 row_mask:0xf bank_mask:0xf bound_ctrl:0
	v_fmac_f32_dpp v123, v123, v147 row_shr:1 row_mask:0xf bank_mask:0xf bound_ctrl:0
	v_fmac_f32_dpp v120, v124, -v148 row_shr:1 row_mask:0xf bank_mask:0xf bound_ctrl:0
	v_fmac_f32_dpp v121, v125, -v149 row_shr:1 row_mask:0xf bank_mask:0xf bound_ctrl:0
	v_fmac_f32_dpp v122, v126, -v150 row_shr:1 row_mask:0xf bank_mask:0xf bound_ctrl:0
	v_fmac_f32_dpp v123, v127, -v151 row_shr:1 row_mask:0xf bank_mask:0xf bound_ctrl:0
	v_fmac_f32_dpp v124, v124, v144 row_shr:1 row_mask:0xf bank_mask:0xf bound_ctrl:0
	v_fmac_f32_dpp v125, v125, v145 row_shr:1 row_mask:0xf bank_mask:0xf bound_ctrl:0
	v_fmac_f32_dpp v126, v126, v146 row_shr:1 row_mask:0xf bank_mask:0xf bound_ctrl:0
	v_fmac_f32_dpp v127, v127, v147 row_shr:1 row_mask:0xf bank_mask:0xf bound_ctrl:0
	v_fmac_f32_dpp v124, v168, v148 row_shr:1 row_mask:0xf bank_mask:0xf bound_ctrl:0
	v_fmac_f32_dpp v125, v169, v149 row_shr:1 row_mask:0xf bank_mask:0xf bound_ctrl:0
	v_fmac_f32_dpp v126, v170, v150 row_shr:1 row_mask:0xf bank_mask:0xf bound_ctrl:0
	v_fmac_f32_dpp v127, v171, v151 row_shr:1 row_mask:0xf bank_mask:0xf bound_ctrl:0
	ds_read_b128 v[144:147], v9 offset:1024
	ds_read_b128 v[148:151], v9 offset:1280
	s_waitcnt lgkmcnt(2)
	v_mov_b32_e32 v168, v128
	v_mov_b32_e32 v169, v129
	v_mov_b32_e32 v170, v130
	v_mov_b32_e32 v171, v131
	v_fmac_f32_dpp v128, v128, v152 row_shr:1 row_mask:0xf bank_mask:0xf bound_ctrl:0
	v_fmac_f32_dpp v129, v129, v153 row_shr:1 row_mask:0xf bank_mask:0xf bound_ctrl:0
	v_fmac_f32_dpp v130, v130, v154 row_shr:1 row_mask:0xf bank_mask:0xf bound_ctrl:0
	v_fmac_f32_dpp v131, v131, v155 row_shr:1 row_mask:0xf bank_mask:0xf bound_ctrl:0
	v_fmac_f32_dpp v128, v140, -v156 row_shr:1 row_mask:0xf bank_mask:0xf bound_ctrl:0
	v_fmac_f32_dpp v129, v141, -v157 row_shr:1 row_mask:0xf bank_mask:0xf bound_ctrl:0
	v_fmac_f32_dpp v130, v142, -v158 row_shr:1 row_mask:0xf bank_mask:0xf bound_ctrl:0
	v_fmac_f32_dpp v131, v143, -v159 row_shr:1 row_mask:0xf bank_mask:0xf bound_ctrl:0
	v_fmac_f32_dpp v140, v140, v152 row_shr:1 row_mask:0xf bank_mask:0xf bound_ctrl:0
	v_fmac_f32_dpp v141, v141, v153 row_shr:1 row_mask:0xf bank_mask:0xf bound_ctrl:0
	v_fmac_f32_dpp v142, v142, v154 row_shr:1 row_mask:0xf bank_mask:0xf bound_ctrl:0
	v_fmac_f32_dpp v143, v143, v155 row_shr:1 row_mask:0xf bank_mask:0xf bound_ctrl:0
	v_fmac_f32_dpp v140, v168, v156 row_shr:1 row_mask:0xf bank_mask:0xf bound_ctrl:0
	v_fmac_f32_dpp v141, v169, v157 row_shr:1 row_mask:0xf bank_mask:0xf bound_ctrl:0
	v_fmac_f32_dpp v142, v170, v158 row_shr:1 row_mask:0xf bank_mask:0xf bound_ctrl:0
	v_fmac_f32_dpp v143, v171, v159 row_shr:1 row_mask:0xf bank_mask:0xf bound_ctrl:0
	ds_read_b128 v[152:155], v9 offset:1088
	ds_read_b128 v[156:159], v9 offset:1344
	s_waitcnt lgkmcnt(2)
	v_mov_b32_e32 v168, v80
	v_mov_b32_e32 v169, v81
	v_mov_b32_e32 v170, v82
	v_mov_b32_e32 v171, v83
	v_fmac_f32_dpp v80, v80, v144 row_shr:2 row_mask:0xf bank_mask:0xf bound_ctrl:0
	v_fmac_f32_dpp v81, v81, v145 row_shr:2 row_mask:0xf bank_mask:0xf bound_ctrl:0
	v_fmac_f32_dpp v82, v82, v146 row_shr:2 row_mask:0xf bank_mask:0xf bound_ctrl:0
	v_fmac_f32_dpp v83, v83, v147 row_shr:2 row_mask:0xf bank_mask:0xf bound_ctrl:0
	v_fmac_f32_dpp v80, v84, -v148 row_shr:2 row_mask:0xf bank_mask:0xf bound_ctrl:0
	v_fmac_f32_dpp v81, v85, -v149 row_shr:2 row_mask:0xf bank_mask:0xf bound_ctrl:0
	v_fmac_f32_dpp v82, v86, -v150 row_shr:2 row_mask:0xf bank_mask:0xf bound_ctrl:0
	v_fmac_f32_dpp v83, v87, -v151 row_shr:2 row_mask:0xf bank_mask:0xf bound_ctrl:0
	v_fmac_f32_dpp v84, v84, v144 row_shr:2 row_mask:0xf bank_mask:0xf bound_ctrl:0
	v_fmac_f32_dpp v85, v85, v145 row_shr:2 row_mask:0xf bank_mask:0xf bound_ctrl:0
	v_fmac_f32_dpp v86, v86, v146 row_shr:2 row_mask:0xf bank_mask:0xf bound_ctrl:0
	v_fmac_f32_dpp v87, v87, v147 row_shr:2 row_mask:0xf bank_mask:0xf bound_ctrl:0
	v_fmac_f32_dpp v84, v168, v148 row_shr:2 row_mask:0xf bank_mask:0xf bound_ctrl:0
	v_fmac_f32_dpp v85, v169, v149 row_shr:2 row_mask:0xf bank_mask:0xf bound_ctrl:0
	v_fmac_f32_dpp v86, v170, v150 row_shr:2 row_mask:0xf bank_mask:0xf bound_ctrl:0
	v_fmac_f32_dpp v87, v171, v151 row_shr:2 row_mask:0xf bank_mask:0xf bound_ctrl:0
	ds_read_b128 v[144:147], v9 offset:1152
	ds_read_b128 v[148:151], v9 offset:1408
	s_waitcnt lgkmcnt(2)
	v_mov_b32_e32 v168, v112
	v_mov_b32_e32 v169, v113
	v_mov_b32_e32 v170, v114
	v_mov_b32_e32 v171, v115
	v_fmac_f32_dpp v112, v112, v152 row_shr:2 row_mask:0xf bank_mask:0xf bound_ctrl:0
	v_fmac_f32_dpp v113, v113, v153 row_shr:2 row_mask:0xf bank_mask:0xf bound_ctrl:0
	v_fmac_f32_dpp v114, v114, v154 row_shr:2 row_mask:0xf bank_mask:0xf bound_ctrl:0
	v_fmac_f32_dpp v115, v115, v155 row_shr:2 row_mask:0xf bank_mask:0xf bound_ctrl:0
	v_fmac_f32_dpp v112, v116, -v156 row_shr:2 row_mask:0xf bank_mask:0xf bound_ctrl:0
	v_fmac_f32_dpp v113, v117, -v157 row_shr:2 row_mask:0xf bank_mask:0xf bound_ctrl:0
	v_fmac_f32_dpp v114, v118, -v158 row_shr:2 row_mask:0xf bank_mask:0xf bound_ctrl:0
	v_fmac_f32_dpp v115, v119, -v159 row_shr:2 row_mask:0xf bank_mask:0xf bound_ctrl:0
	v_fmac_f32_dpp v116, v116, v152 row_shr:2 row_mask:0xf bank_mask:0xf bound_ctrl:0
	v_fmac_f32_dpp v117, v117, v153 row_shr:2 row_mask:0xf bank_mask:0xf bound_ctrl:0
	v_fmac_f32_dpp v118, v118, v154 row_shr:2 row_mask:0xf bank_mask:0xf bound_ctrl:0
	v_fmac_f32_dpp v119, v119, v155 row_shr:2 row_mask:0xf bank_mask:0xf bound_ctrl:0
	v_fmac_f32_dpp v116, v168, v156 row_shr:2 row_mask:0xf bank_mask:0xf bound_ctrl:0
	v_fmac_f32_dpp v117, v169, v157 row_shr:2 row_mask:0xf bank_mask:0xf bound_ctrl:0
	v_fmac_f32_dpp v118, v170, v158 row_shr:2 row_mask:0xf bank_mask:0xf bound_ctrl:0
	v_fmac_f32_dpp v119, v171, v159 row_shr:2 row_mask:0xf bank_mask:0xf bound_ctrl:0
	ds_read_b128 v[152:155], v9 offset:1216
	ds_read_b128 v[156:159], v9 offset:1472
	s_waitcnt lgkmcnt(2)
	v_mov_b32_e32 v168, v120
	v_mov_b32_e32 v169, v121
	v_mov_b32_e32 v170, v122
	v_mov_b32_e32 v171, v123
	v_fmac_f32_dpp v120, v120, v144 row_shr:2 row_mask:0xf bank_mask:0xf bound_ctrl:0
	v_fmac_f32_dpp v121, v121, v145 row_shr:2 row_mask:0xf bank_mask:0xf bound_ctrl:0
	v_fmac_f32_dpp v122, v122, v146 row_shr:2 row_mask:0xf bank_mask:0xf bound_ctrl:0
	v_fmac_f32_dpp v123, v123, v147 row_shr:2 row_mask:0xf bank_mask:0xf bound_ctrl:0
	v_fmac_f32_dpp v120, v124, -v148 row_shr:2 row_mask:0xf bank_mask:0xf bound_ctrl:0
	v_fmac_f32_dpp v121, v125, -v149 row_shr:2 row_mask:0xf bank_mask:0xf bound_ctrl:0
	v_fmac_f32_dpp v122, v126, -v150 row_shr:2 row_mask:0xf bank_mask:0xf bound_ctrl:0
	v_fmac_f32_dpp v123, v127, -v151 row_shr:2 row_mask:0xf bank_mask:0xf bound_ctrl:0
	v_fmac_f32_dpp v124, v124, v144 row_shr:2 row_mask:0xf bank_mask:0xf bound_ctrl:0
	v_fmac_f32_dpp v125, v125, v145 row_shr:2 row_mask:0xf bank_mask:0xf bound_ctrl:0
	v_fmac_f32_dpp v126, v126, v146 row_shr:2 row_mask:0xf bank_mask:0xf bound_ctrl:0
	v_fmac_f32_dpp v127, v127, v147 row_shr:2 row_mask:0xf bank_mask:0xf bound_ctrl:0
	v_fmac_f32_dpp v124, v168, v148 row_shr:2 row_mask:0xf bank_mask:0xf bound_ctrl:0
	v_fmac_f32_dpp v125, v169, v149 row_shr:2 row_mask:0xf bank_mask:0xf bound_ctrl:0
	v_fmac_f32_dpp v126, v170, v150 row_shr:2 row_mask:0xf bank_mask:0xf bound_ctrl:0
	v_fmac_f32_dpp v127, v171, v151 row_shr:2 row_mask:0xf bank_mask:0xf bound_ctrl:0
	ds_read_b128 v[144:147], v9 offset:1536
	ds_read_b128 v[148:151], v9 offset:1792
	s_waitcnt lgkmcnt(2)
	v_mov_b32_e32 v168, v128
	v_mov_b32_e32 v169, v129
	v_mov_b32_e32 v170, v130
	v_mov_b32_e32 v171, v131
	v_fmac_f32_dpp v128, v128, v152 row_shr:2 row_mask:0xf bank_mask:0xf bound_ctrl:0
	v_fmac_f32_dpp v129, v129, v153 row_shr:2 row_mask:0xf bank_mask:0xf bound_ctrl:0
	v_fmac_f32_dpp v130, v130, v154 row_shr:2 row_mask:0xf bank_mask:0xf bound_ctrl:0
	v_fmac_f32_dpp v131, v131, v155 row_shr:2 row_mask:0xf bank_mask:0xf bound_ctrl:0
	v_fmac_f32_dpp v128, v140, -v156 row_shr:2 row_mask:0xf bank_mask:0xf bound_ctrl:0
	v_fmac_f32_dpp v129, v141, -v157 row_shr:2 row_mask:0xf bank_mask:0xf bound_ctrl:0
	v_fmac_f32_dpp v130, v142, -v158 row_shr:2 row_mask:0xf bank_mask:0xf bound_ctrl:0
	v_fmac_f32_dpp v131, v143, -v159 row_shr:2 row_mask:0xf bank_mask:0xf bound_ctrl:0
	v_fmac_f32_dpp v140, v140, v152 row_shr:2 row_mask:0xf bank_mask:0xf bound_ctrl:0
	v_fmac_f32_dpp v141, v141, v153 row_shr:2 row_mask:0xf bank_mask:0xf bound_ctrl:0
	v_fmac_f32_dpp v142, v142, v154 row_shr:2 row_mask:0xf bank_mask:0xf bound_ctrl:0
	v_fmac_f32_dpp v143, v143, v155 row_shr:2 row_mask:0xf bank_mask:0xf bound_ctrl:0
	v_fmac_f32_dpp v140, v168, v156 row_shr:2 row_mask:0xf bank_mask:0xf bound_ctrl:0
	v_fmac_f32_dpp v141, v169, v157 row_shr:2 row_mask:0xf bank_mask:0xf bound_ctrl:0
	v_fmac_f32_dpp v142, v170, v158 row_shr:2 row_mask:0xf bank_mask:0xf bound_ctrl:0
	v_fmac_f32_dpp v143, v171, v159 row_shr:2 row_mask:0xf bank_mask:0xf bound_ctrl:0
	ds_read_b128 v[152:155], v9 offset:1600
	ds_read_b128 v[156:159], v9 offset:1856
	s_waitcnt lgkmcnt(2)
	v_mov_b32_e32 v168, v80
	v_mov_b32_e32 v169, v81
	v_mov_b32_e32 v170, v82
	v_mov_b32_e32 v171, v83
	v_fmac_f32_dpp v80, v80, v144 row_shr:4 row_mask:0xf bank_mask:0xf bound_ctrl:0
	v_fmac_f32_dpp v81, v81, v145 row_shr:4 row_mask:0xf bank_mask:0xf bound_ctrl:0
	v_fmac_f32_dpp v82, v82, v146 row_shr:4 row_mask:0xf bank_mask:0xf bound_ctrl:0
	v_fmac_f32_dpp v83, v83, v147 row_shr:4 row_mask:0xf bank_mask:0xf bound_ctrl:0
	v_fmac_f32_dpp v80, v84, -v148 row_shr:4 row_mask:0xf bank_mask:0xf bound_ctrl:0
	v_fmac_f32_dpp v81, v85, -v149 row_shr:4 row_mask:0xf bank_mask:0xf bound_ctrl:0
	v_fmac_f32_dpp v82, v86, -v150 row_shr:4 row_mask:0xf bank_mask:0xf bound_ctrl:0
	v_fmac_f32_dpp v83, v87, -v151 row_shr:4 row_mask:0xf bank_mask:0xf bound_ctrl:0
	v_fmac_f32_dpp v84, v84, v144 row_shr:4 row_mask:0xf bank_mask:0xf bound_ctrl:0
	v_fmac_f32_dpp v85, v85, v145 row_shr:4 row_mask:0xf bank_mask:0xf bound_ctrl:0
	v_fmac_f32_dpp v86, v86, v146 row_shr:4 row_mask:0xf bank_mask:0xf bound_ctrl:0
	v_fmac_f32_dpp v87, v87, v147 row_shr:4 row_mask:0xf bank_mask:0xf bound_ctrl:0
	v_fmac_f32_dpp v84, v168, v148 row_shr:4 row_mask:0xf bank_mask:0xf bound_ctrl:0
	v_fmac_f32_dpp v85, v169, v149 row_shr:4 row_mask:0xf bank_mask:0xf bound_ctrl:0
	v_fmac_f32_dpp v86, v170, v150 row_shr:4 row_mask:0xf bank_mask:0xf bound_ctrl:0
	v_fmac_f32_dpp v87, v171, v151 row_shr:4 row_mask:0xf bank_mask:0xf bound_ctrl:0
	ds_read_b128 v[144:147], v9 offset:1664
	ds_read_b128 v[148:151], v9 offset:1920
	s_waitcnt lgkmcnt(2)
	v_mov_b32_e32 v168, v112
	v_mov_b32_e32 v169, v113
	v_mov_b32_e32 v170, v114
	v_mov_b32_e32 v171, v115
	v_fmac_f32_dpp v112, v112, v152 row_shr:4 row_mask:0xf bank_mask:0xf bound_ctrl:0
	v_fmac_f32_dpp v113, v113, v153 row_shr:4 row_mask:0xf bank_mask:0xf bound_ctrl:0
	v_fmac_f32_dpp v114, v114, v154 row_shr:4 row_mask:0xf bank_mask:0xf bound_ctrl:0
	v_fmac_f32_dpp v115, v115, v155 row_shr:4 row_mask:0xf bank_mask:0xf bound_ctrl:0
	v_fmac_f32_dpp v112, v116, -v156 row_shr:4 row_mask:0xf bank_mask:0xf bound_ctrl:0
	v_fmac_f32_dpp v113, v117, -v157 row_shr:4 row_mask:0xf bank_mask:0xf bound_ctrl:0
	v_fmac_f32_dpp v114, v118, -v158 row_shr:4 row_mask:0xf bank_mask:0xf bound_ctrl:0
	v_fmac_f32_dpp v115, v119, -v159 row_shr:4 row_mask:0xf bank_mask:0xf bound_ctrl:0
	v_fmac_f32_dpp v116, v116, v152 row_shr:4 row_mask:0xf bank_mask:0xf bound_ctrl:0
	v_fmac_f32_dpp v117, v117, v153 row_shr:4 row_mask:0xf bank_mask:0xf bound_ctrl:0
	v_fmac_f32_dpp v118, v118, v154 row_shr:4 row_mask:0xf bank_mask:0xf bound_ctrl:0
	v_fmac_f32_dpp v119, v119, v155 row_shr:4 row_mask:0xf bank_mask:0xf bound_ctrl:0
	v_fmac_f32_dpp v116, v168, v156 row_shr:4 row_mask:0xf bank_mask:0xf bound_ctrl:0
	v_fmac_f32_dpp v117, v169, v157 row_shr:4 row_mask:0xf bank_mask:0xf bound_ctrl:0
	v_fmac_f32_dpp v118, v170, v158 row_shr:4 row_mask:0xf bank_mask:0xf bound_ctrl:0
	v_fmac_f32_dpp v119, v171, v159 row_shr:4 row_mask:0xf bank_mask:0xf bound_ctrl:0
	ds_read_b128 v[152:155], v9 offset:1728
	ds_read_b128 v[156:159], v9 offset:1984
	s_waitcnt lgkmcnt(2)
	v_mov_b32_e32 v168, v120
	v_mov_b32_e32 v169, v121
	v_mov_b32_e32 v170, v122
	v_mov_b32_e32 v171, v123
	v_fmac_f32_dpp v120, v120, v144 row_shr:4 row_mask:0xf bank_mask:0xf bound_ctrl:0
	v_fmac_f32_dpp v121, v121, v145 row_shr:4 row_mask:0xf bank_mask:0xf bound_ctrl:0
	v_fmac_f32_dpp v122, v122, v146 row_shr:4 row_mask:0xf bank_mask:0xf bound_ctrl:0
	v_fmac_f32_dpp v123, v123, v147 row_shr:4 row_mask:0xf bank_mask:0xf bound_ctrl:0
	v_fmac_f32_dpp v120, v124, -v148 row_shr:4 row_mask:0xf bank_mask:0xf bound_ctrl:0
	v_fmac_f32_dpp v121, v125, -v149 row_shr:4 row_mask:0xf bank_mask:0xf bound_ctrl:0
	v_fmac_f32_dpp v122, v126, -v150 row_shr:4 row_mask:0xf bank_mask:0xf bound_ctrl:0
	v_fmac_f32_dpp v123, v127, -v151 row_shr:4 row_mask:0xf bank_mask:0xf bound_ctrl:0
	v_fmac_f32_dpp v124, v124, v144 row_shr:4 row_mask:0xf bank_mask:0xf bound_ctrl:0
	v_fmac_f32_dpp v125, v125, v145 row_shr:4 row_mask:0xf bank_mask:0xf bound_ctrl:0
	v_fmac_f32_dpp v126, v126, v146 row_shr:4 row_mask:0xf bank_mask:0xf bound_ctrl:0
	v_fmac_f32_dpp v127, v127, v147 row_shr:4 row_mask:0xf bank_mask:0xf bound_ctrl:0
	v_fmac_f32_dpp v124, v168, v148 row_shr:4 row_mask:0xf bank_mask:0xf bound_ctrl:0
	v_fmac_f32_dpp v125, v169, v149 row_shr:4 row_mask:0xf bank_mask:0xf bound_ctrl:0
	v_fmac_f32_dpp v126, v170, v150 row_shr:4 row_mask:0xf bank_mask:0xf bound_ctrl:0
	v_fmac_f32_dpp v127, v171, v151 row_shr:4 row_mask:0xf bank_mask:0xf bound_ctrl:0
	ds_read_b128 v[144:147], v9 offset:2048
	ds_read_b128 v[148:151], v9 offset:2304
	s_waitcnt lgkmcnt(2)
	v_mov_b32_e32 v168, v128
	v_mov_b32_e32 v169, v129
	v_mov_b32_e32 v170, v130
	v_mov_b32_e32 v171, v131
	v_fmac_f32_dpp v128, v128, v152 row_shr:4 row_mask:0xf bank_mask:0xf bound_ctrl:0
	v_fmac_f32_dpp v129, v129, v153 row_shr:4 row_mask:0xf bank_mask:0xf bound_ctrl:0
	v_fmac_f32_dpp v130, v130, v154 row_shr:4 row_mask:0xf bank_mask:0xf bound_ctrl:0
	v_fmac_f32_dpp v131, v131, v155 row_shr:4 row_mask:0xf bank_mask:0xf bound_ctrl:0
	v_fmac_f32_dpp v128, v140, -v156 row_shr:4 row_mask:0xf bank_mask:0xf bound_ctrl:0
	v_fmac_f32_dpp v129, v141, -v157 row_shr:4 row_mask:0xf bank_mask:0xf bound_ctrl:0
	v_fmac_f32_dpp v130, v142, -v158 row_shr:4 row_mask:0xf bank_mask:0xf bound_ctrl:0
	v_fmac_f32_dpp v131, v143, -v159 row_shr:4 row_mask:0xf bank_mask:0xf bound_ctrl:0
	v_fmac_f32_dpp v140, v140, v152 row_shr:4 row_mask:0xf bank_mask:0xf bound_ctrl:0
	v_fmac_f32_dpp v141, v141, v153 row_shr:4 row_mask:0xf bank_mask:0xf bound_ctrl:0
	v_fmac_f32_dpp v142, v142, v154 row_shr:4 row_mask:0xf bank_mask:0xf bound_ctrl:0
	v_fmac_f32_dpp v143, v143, v155 row_shr:4 row_mask:0xf bank_mask:0xf bound_ctrl:0
	v_fmac_f32_dpp v140, v168, v156 row_shr:4 row_mask:0xf bank_mask:0xf bound_ctrl:0
	v_fmac_f32_dpp v141, v169, v157 row_shr:4 row_mask:0xf bank_mask:0xf bound_ctrl:0
	v_fmac_f32_dpp v142, v170, v158 row_shr:4 row_mask:0xf bank_mask:0xf bound_ctrl:0
	v_fmac_f32_dpp v143, v171, v159 row_shr:4 row_mask:0xf bank_mask:0xf bound_ctrl:0
	ds_read_b128 v[152:155], v9 offset:2112
	ds_read_b128 v[156:159], v9 offset:2368
	s_waitcnt lgkmcnt(2)
	v_mov_b32_e32 v168, v80
	v_mov_b32_e32 v169, v81
	v_mov_b32_e32 v170, v82
	v_mov_b32_e32 v171, v83
	v_fmac_f32_dpp v80, v80, v144 row_shr:8 row_mask:0xf bank_mask:0xf bound_ctrl:0
	v_fmac_f32_dpp v81, v81, v145 row_shr:8 row_mask:0xf bank_mask:0xf bound_ctrl:0
	v_fmac_f32_dpp v82, v82, v146 row_shr:8 row_mask:0xf bank_mask:0xf bound_ctrl:0
	v_fmac_f32_dpp v83, v83, v147 row_shr:8 row_mask:0xf bank_mask:0xf bound_ctrl:0
	v_fmac_f32_dpp v80, v84, -v148 row_shr:8 row_mask:0xf bank_mask:0xf bound_ctrl:0
	v_fmac_f32_dpp v81, v85, -v149 row_shr:8 row_mask:0xf bank_mask:0xf bound_ctrl:0
	v_fmac_f32_dpp v82, v86, -v150 row_shr:8 row_mask:0xf bank_mask:0xf bound_ctrl:0
	v_fmac_f32_dpp v83, v87, -v151 row_shr:8 row_mask:0xf bank_mask:0xf bound_ctrl:0
	v_fmac_f32_dpp v84, v84, v144 row_shr:8 row_mask:0xf bank_mask:0xf bound_ctrl:0
	v_fmac_f32_dpp v85, v85, v145 row_shr:8 row_mask:0xf bank_mask:0xf bound_ctrl:0
	v_fmac_f32_dpp v86, v86, v146 row_shr:8 row_mask:0xf bank_mask:0xf bound_ctrl:0
	v_fmac_f32_dpp v87, v87, v147 row_shr:8 row_mask:0xf bank_mask:0xf bound_ctrl:0
	v_fmac_f32_dpp v84, v168, v148 row_shr:8 row_mask:0xf bank_mask:0xf bound_ctrl:0
	v_fmac_f32_dpp v85, v169, v149 row_shr:8 row_mask:0xf bank_mask:0xf bound_ctrl:0
	v_fmac_f32_dpp v86, v170, v150 row_shr:8 row_mask:0xf bank_mask:0xf bound_ctrl:0
	v_fmac_f32_dpp v87, v171, v151 row_shr:8 row_mask:0xf bank_mask:0xf bound_ctrl:0
	ds_read_b128 v[144:147], v9 offset:2176
	ds_read_b128 v[148:151], v9 offset:2432
	s_waitcnt lgkmcnt(2)
	v_mov_b32_e32 v168, v112
	v_mov_b32_e32 v169, v113
	v_mov_b32_e32 v170, v114
	v_mov_b32_e32 v171, v115
	v_fmac_f32_dpp v112, v112, v152 row_shr:8 row_mask:0xf bank_mask:0xf bound_ctrl:0
	v_fmac_f32_dpp v113, v113, v153 row_shr:8 row_mask:0xf bank_mask:0xf bound_ctrl:0
	v_fmac_f32_dpp v114, v114, v154 row_shr:8 row_mask:0xf bank_mask:0xf bound_ctrl:0
	v_fmac_f32_dpp v115, v115, v155 row_shr:8 row_mask:0xf bank_mask:0xf bound_ctrl:0
	v_fmac_f32_dpp v112, v116, -v156 row_shr:8 row_mask:0xf bank_mask:0xf bound_ctrl:0
	v_fmac_f32_dpp v113, v117, -v157 row_shr:8 row_mask:0xf bank_mask:0xf bound_ctrl:0
	v_fmac_f32_dpp v114, v118, -v158 row_shr:8 row_mask:0xf bank_mask:0xf bound_ctrl:0
	v_fmac_f32_dpp v115, v119, -v159 row_shr:8 row_mask:0xf bank_mask:0xf bound_ctrl:0
	v_fmac_f32_dpp v116, v116, v152 row_shr:8 row_mask:0xf bank_mask:0xf bound_ctrl:0
	v_fmac_f32_dpp v117, v117, v153 row_shr:8 row_mask:0xf bank_mask:0xf bound_ctrl:0
	v_fmac_f32_dpp v118, v118, v154 row_shr:8 row_mask:0xf bank_mask:0xf bound_ctrl:0
	v_fmac_f32_dpp v119, v119, v155 row_shr:8 row_mask:0xf bank_mask:0xf bound_ctrl:0
	v_fmac_f32_dpp v116, v168, v156 row_shr:8 row_mask:0xf bank_mask:0xf bound_ctrl:0
	v_fmac_f32_dpp v117, v169, v157 row_shr:8 row_mask:0xf bank_mask:0xf bound_ctrl:0
	v_fmac_f32_dpp v118, v170, v158 row_shr:8 row_mask:0xf bank_mask:0xf bound_ctrl:0
	v_fmac_f32_dpp v119, v171, v159 row_shr:8 row_mask:0xf bank_mask:0xf bound_ctrl:0
	ds_read_b128 v[152:155], v9 offset:2240
	ds_read_b128 v[156:159], v9 offset:2496
	s_waitcnt lgkmcnt(2)
	v_mov_b32_e32 v168, v120
	v_mov_b32_e32 v169, v121
	v_mov_b32_e32 v170, v122
	v_mov_b32_e32 v171, v123
	v_fmac_f32_dpp v120, v120, v144 row_shr:8 row_mask:0xf bank_mask:0xf bound_ctrl:0
	v_fmac_f32_dpp v121, v121, v145 row_shr:8 row_mask:0xf bank_mask:0xf bound_ctrl:0
	v_fmac_f32_dpp v122, v122, v146 row_shr:8 row_mask:0xf bank_mask:0xf bound_ctrl:0
	v_fmac_f32_dpp v123, v123, v147 row_shr:8 row_mask:0xf bank_mask:0xf bound_ctrl:0
	v_fmac_f32_dpp v120, v124, -v148 row_shr:8 row_mask:0xf bank_mask:0xf bound_ctrl:0
	v_fmac_f32_dpp v121, v125, -v149 row_shr:8 row_mask:0xf bank_mask:0xf bound_ctrl:0
	v_fmac_f32_dpp v122, v126, -v150 row_shr:8 row_mask:0xf bank_mask:0xf bound_ctrl:0
	v_fmac_f32_dpp v123, v127, -v151 row_shr:8 row_mask:0xf bank_mask:0xf bound_ctrl:0
	v_fmac_f32_dpp v124, v124, v144 row_shr:8 row_mask:0xf bank_mask:0xf bound_ctrl:0
	v_fmac_f32_dpp v125, v125, v145 row_shr:8 row_mask:0xf bank_mask:0xf bound_ctrl:0
	v_fmac_f32_dpp v126, v126, v146 row_shr:8 row_mask:0xf bank_mask:0xf bound_ctrl:0
	v_fmac_f32_dpp v127, v127, v147 row_shr:8 row_mask:0xf bank_mask:0xf bound_ctrl:0
	v_fmac_f32_dpp v124, v168, v148 row_shr:8 row_mask:0xf bank_mask:0xf bound_ctrl:0
	v_fmac_f32_dpp v125, v169, v149 row_shr:8 row_mask:0xf bank_mask:0xf bound_ctrl:0
	v_fmac_f32_dpp v126, v170, v150 row_shr:8 row_mask:0xf bank_mask:0xf bound_ctrl:0
	v_fmac_f32_dpp v127, v171, v151 row_shr:8 row_mask:0xf bank_mask:0xf bound_ctrl:0
	s_waitcnt lgkmcnt(0)
	v_mov_b32_e32 v168, v128
	v_mov_b32_e32 v169, v129
	v_mov_b32_e32 v170, v130
	v_mov_b32_e32 v171, v131
	v_fmac_f32_dpp v128, v128, v152 row_shr:8 row_mask:0xf bank_mask:0xf bound_ctrl:0
	v_fmac_f32_dpp v129, v129, v153 row_shr:8 row_mask:0xf bank_mask:0xf bound_ctrl:0
	v_fmac_f32_dpp v130, v130, v154 row_shr:8 row_mask:0xf bank_mask:0xf bound_ctrl:0
	v_fmac_f32_dpp v131, v131, v155 row_shr:8 row_mask:0xf bank_mask:0xf bound_ctrl:0
	v_fmac_f32_dpp v128, v140, -v156 row_shr:8 row_mask:0xf bank_mask:0xf bound_ctrl:0
	v_fmac_f32_dpp v129, v141, -v157 row_shr:8 row_mask:0xf bank_mask:0xf bound_ctrl:0
	v_fmac_f32_dpp v130, v142, -v158 row_shr:8 row_mask:0xf bank_mask:0xf bound_ctrl:0
	v_fmac_f32_dpp v131, v143, -v159 row_shr:8 row_mask:0xf bank_mask:0xf bound_ctrl:0
	v_fmac_f32_dpp v140, v140, v152 row_shr:8 row_mask:0xf bank_mask:0xf bound_ctrl:0
	v_fmac_f32_dpp v141, v141, v153 row_shr:8 row_mask:0xf bank_mask:0xf bound_ctrl:0
	v_fmac_f32_dpp v142, v142, v154 row_shr:8 row_mask:0xf bank_mask:0xf bound_ctrl:0
	v_fmac_f32_dpp v143, v143, v155 row_shr:8 row_mask:0xf bank_mask:0xf bound_ctrl:0
	v_fmac_f32_dpp v140, v168, v156 row_shr:8 row_mask:0xf bank_mask:0xf bound_ctrl:0
	v_fmac_f32_dpp v141, v169, v157 row_shr:8 row_mask:0xf bank_mask:0xf bound_ctrl:0
	v_fmac_f32_dpp v142, v170, v158 row_shr:8 row_mask:0xf bank_mask:0xf bound_ctrl:0
	v_fmac_f32_dpp v143, v171, v159 row_shr:8 row_mask:0xf bank_mask:0xf bound_ctrl:0
	s_nop 1
	s_mov_b64 exec, s[10:11]
	global_store_dword v10, v80, s[36:37] offset:0
	global_store_dword v10, v84, s[36:37] offset:4
	global_store_dword v10, v81, s[36:37] offset:8
	global_store_dword v10, v85, s[36:37] offset:12
	global_store_dword v10, v82, s[36:37] offset:16
	global_store_dword v10, v86, s[36:37] offset:20
	global_store_dword v10, v83, s[36:37] offset:24
	global_store_dword v10, v87, s[36:37] offset:28
	global_store_dword v10, v112, s[36:37] offset:128
	global_store_dword v10, v116, s[36:37] offset:132
	global_store_dword v10, v113, s[36:37] offset:136
	global_store_dword v10, v117, s[36:37] offset:140
	global_store_dword v10, v114, s[36:37] offset:144
	global_store_dword v10, v118, s[36:37] offset:148
	global_store_dword v10, v115, s[36:37] offset:152
	global_store_dword v10, v119, s[36:37] offset:156
	global_store_dword v10, v120, s[36:37] offset:256
	global_store_dword v10, v124, s[36:37] offset:260
	global_store_dword v10, v121, s[36:37] offset:264
	global_store_dword v10, v125, s[36:37] offset:268
	global_store_dword v10, v122, s[36:37] offset:272
	global_store_dword v10, v126, s[36:37] offset:276
	global_store_dword v10, v123, s[36:37] offset:280
	global_store_dword v10, v127, s[36:37] offset:284
	global_store_dword v10, v128, s[36:37] offset:384
	global_store_dword v10, v140, s[36:37] offset:388
	global_store_dword v10, v129, s[36:37] offset:392
	global_store_dword v10, v141, s[36:37] offset:396
	global_store_dword v10, v130, s[36:37] offset:400
	global_store_dword v10, v142, s[36:37] offset:404
	global_store_dword v10, v131, s[36:37] offset:408
	global_store_dword v10, v143, s[36:37] offset:412
	s_mov_b64 exec, -1
	s_add_i32 s55, s6, 16
	s_lshl_b32 s56, s55, 13
	s_add_u32 s12, s94, 0x12d96000
	s_addc_u32 s13, s95, 0
	s_add_u32 s12, s12, s56
	s_addc_u32 s13, s13, 0
	s_lshl_b32 s56, s55, 9
	s_add_u32 s38, s94, 0x12d92000
	s_addc_u32 s39, s95, 0
	s_add_u32 s38, s38, s56
	s_addc_u32 s39, s39, 0
	s_lshl_b32 s56, s0, 5
	s_lshl_b32 s55, s6, 1
	s_add_i32 s56, s56, s55
	s_add_i32 s56, s56, 1
	s_lshl_b32 s56, s56, 9
	s_add_u32 s36, s94, 0x12dd6000
	s_addc_u32 s37, s95, 0
	s_add_u32 s36, s36, s56
	s_addc_u32 s37, s37, 0
	global_load_dwordx2 v[2:3], v7, s[38:39]
	global_load_dwordx4 v[12:15], v6, s[12:13] offset:0
	global_load_dwordx4 v[16:19], v6, s[12:13] offset:1024
	global_load_dwordx4 v[20:23], v6, s[12:13] offset:256
	global_load_dwordx4 v[24:27], v6, s[12:13] offset:1280
	global_load_dwordx4 v[28:31], v6, s[12:13] offset:512
	global_load_dwordx4 v[32:35], v6, s[12:13] offset:1536
	global_load_dwordx4 v[36:39], v6, s[12:13] offset:768
	global_load_dwordx4 v[40:43], v6, s[12:13] offset:1792
	s_waitcnt vmcnt(8)
	ds_write_b32 v8, v2 offset:0
	ds_write_b32 v8, v3 offset:256
	v_mul_f32_e32 v168, v3, v3
	v_mul_f32_e32 v169, v2, v3
	v_fma_f32 v2, v2, v2, -v168
	v_add_f32_e32 v3, v169, v169
	ds_write_b32 v8, v2 offset:512
	ds_write_b32 v8, v3 offset:768
	v_mul_f32_e32 v168, v3, v3
	v_mul_f32_e32 v169, v2, v3
	v_fma_f32 v2, v2, v2, -v168
	v_add_f32_e32 v3, v169, v169
	ds_write_b32 v8, v2 offset:1024
	ds_write_b32 v8, v3 offset:1280
	v_mul_f32_e32 v168, v3, v3
	v_mul_f32_e32 v169, v2, v3
	v_fma_f32 v2, v2, v2, -v168
	v_add_f32_e32 v3, v169, v169
	ds_write_b32 v8, v2 offset:1536
	ds_write_b32 v8, v3 offset:1792
	v_mul_f32_e32 v168, v3, v3
	v_mul_f32_e32 v169, v2, v3
	v_fma_f32 v2, v2, v2, -v168
	v_add_f32_e32 v3, v169, v169
	ds_write_b32 v8, v2 offset:2048
	ds_write_b32 v8, v3 offset:2304
	s_waitcnt lgkmcnt(0)
	s_waitcnt vmcnt(7)
	v_mfma_f32_16x16x4_f32 v[44:47], v12, v180, 0
	v_mfma_f32_16x16x4_f32 v[52:55], v13, v180, 0
	v_mfma_f32_16x16x4_f32 v[80:83], v12, v184, 0
	v_mfma_f32_16x16x4_f32 v[84:87], v13, v184, 0
	s_waitcnt vmcnt(5)
	v_mfma_f32_16x16x4_f32 v[56:59], v20, v180, 0
	v_mfma_f32_16x16x4_f32 v[60:63], v21, v180, 0
	v_mfma_f32_16x16x4_f32 v[112:115], v20, v184, 0
	v_mfma_f32_16x16x4_f32 v[116:119], v21, v184, 0
	s_waitcnt vmcnt(3)
	v_mfma_f32_16x16x4_f32 v[64:67], v28, v180, 0
	v_mfma_f32_16x16x4_f32 v[68:71], v29, v180, 0
	v_mfma_f32_16x16x4_f32 v[120:123], v28, v184, 0
	v_mfma_f32_16x16x4_f32 v[124:127], v29, v184, 0
	s_waitcnt vmcnt(1)
	v_mfma_f32_16x16x4_f32 v[72:75], v36, v180, 0
	v_mfma_f32_16x16x4_f32 v[76:79], v37, v180, 0
	v_mfma_f32_16x16x4_f32 v[128:131], v36, v184, 0
	v_mfma_f32_16x16x4_f32 v[140:143], v37, v184, 0
	v_mfma_f32_16x16x4_f32 v[44:47], v14, v181, v[44:47]
	v_mfma_f32_16x16x4_f32 v[52:55], v15, v181, v[52:55]
	v_mfma_f32_16x16x4_f32 v[80:83], v14, v185, v[80:83]
	v_mfma_f32_16x16x4_f32 v[84:87], v15, v185, v[84:87]
	v_mfma_f32_16x16x4_f32 v[56:59], v22, v181, v[56:59]
	v_mfma_f32_16x16x4_f32 v[60:63], v23, v181, v[60:63]
	v_mfma_f32_16x16x4_f32 v[112:115], v22, v185, v[112:115]
	v_mfma_f32_16x16x4_f32 v[116:119], v23, v185, v[116:119]
	v_mfma_f32_16x16x4_f32 v[64:67], v30, v181, v[64:67]
	v_mfma_f32_16x16x4_f32 v[68:71], v31, v181, v[68:71]
	v_mfma_f32_16x16x4_f32 v[120:123], v30, v185, v[120:123]
	v_mfma_f32_16x16x4_f32 v[124:127], v31, v185, v[124:127]
	v_mfma_f32_16x16x4_f32 v[72:75], v38, v181, v[72:75]
	v_mfma_f32_16x16x4_f32 v[76:79], v39, v181, v[76:79]
	v_mfma_f32_16x16x4_f32 v[128:131], v38, v185, v[128:131]
	v_mfma_f32_16x16x4_f32 v[140:143], v39, v185, v[140:143]
	v_mfma_f32_16x16x4_f32 v[44:47], v16, v182, v[44:47]
	v_mfma_f32_16x16x4_f32 v[52:55], v17, v182, v[52:55]
	v_mfma_f32_16x16x4_f32 v[80:83], v16, v186, v[80:83]
	v_mfma_f32_16x16x4_f32 v[84:87], v17, v186, v[84:87]
	v_mfma_f32_16x16x4_f32 v[56:59], v24, v182, v[56:59]
	v_mfma_f32_16x16x4_f32 v[60:63], v25, v182, v[60:63]
	v_mfma_f32_16x16x4_f32 v[112:115], v24, v186, v[112:115]
	v_mfma_f32_16x16x4_f32 v[116:119], v25, v186, v[116:119]
	v_mfma_f32_16x16x4_f32 v[64:67], v32, v182, v[64:67]
	v_mfma_f32_16x16x4_f32 v[68:71], v33, v182, v[68:71]
	v_mfma_f32_16x16x4_f32 v[120:123], v32, v186, v[120:123]
	v_mfma_f32_16x16x4_f32 v[124:127], v33, v186, v[124:127]
	s_waitcnt vmcnt(0)
	v_mfma_f32_16x16x4_f32 v[72:75], v40, v182, v[72:75]
	v_mfma_f32_16x16x4_f32 v[76:79], v41, v182, v[76:79]
	v_mfma_f32_16x16x4_f32 v[128:131], v40, v186, v[128:131]
	v_mfma_f32_16x16x4_f32 v[140:143], v41, v186, v[140:143]
	v_mfma_f32_16x16x4_f32 v[44:47], v18, v183, v[44:47]
	v_mfma_f32_16x16x4_f32 v[52:55], v19, v183, v[52:55]
	v_mfma_f32_16x16x4_f32 v[80:83], v18, v187, v[80:83]
	v_mfma_f32_16x16x4_f32 v[84:87], v19, v187, v[84:87]
	v_mfma_f32_16x16x4_f32 v[56:59], v26, v183, v[56:59]
	v_mfma_f32_16x16x4_f32 v[60:63], v27, v183, v[60:63]
	v_mfma_f32_16x16x4_f32 v[112:115], v26, v187, v[112:115]
	v_mfma_f32_16x16x4_f32 v[116:119], v27, v187, v[116:119]
	v_mfma_f32_16x16x4_f32 v[64:67], v34, v183, v[64:67]
	v_mfma_f32_16x16x4_f32 v[68:71], v35, v183, v[68:71]
	v_mfma_f32_16x16x4_f32 v[120:123], v34, v187, v[120:123]
	v_mfma_f32_16x16x4_f32 v[124:127], v35, v187, v[124:127]
	v_mfma_f32_16x16x4_f32 v[72:75], v42, v183, v[72:75]
	v_mfma_f32_16x16x4_f32 v[76:79], v43, v183, v[76:79]
	v_mfma_f32_16x16x4_f32 v[128:131], v42, v187, v[128:131]
	v_mfma_f32_16x16x4_f32 v[140:143], v43, v187, v[140:143]
	s_nop 9
	ds_read_b128 v[144:147], v9 offset:0
	ds_read_b128 v[148:151], v9 offset:256
	ds_read_b128 v[152:155], v9 offset:64
	ds_read_b128 v[156:159], v9 offset:320
	s_waitcnt lgkmcnt(2)
	v_fmac_f32_e32 v44, v144, v80
	v_fmac_f32_e32 v45, v145, v81
	v_fmac_f32_e32 v46, v146, v82
	v_fmac_f32_e32 v47, v147, v83
	v_fma_f32 v44, -v148, v84, v44
	v_fma_f32 v45, -v149, v85, v45
	v_fma_f32 v46, -v150, v86, v46
	v_fma_f32 v47, -v151, v87, v47
	v_fmac_f32_e32 v52, v144, v84
	v_fmac_f32_e32 v53, v145, v85
	v_fmac_f32_e32 v54, v146, v86
	v_fmac_f32_e32 v55, v147, v87
	v_fmac_f32_e32 v52, v148, v80
	v_fmac_f32_e32 v53, v149, v81
	v_fmac_f32_e32 v54, v150, v82
	v_fmac_f32_e32 v55, v151, v83
	ds_read_b128 v[144:147], v9 offset:128
	ds_read_b128 v[148:151], v9 offset:384
	s_waitcnt lgkmcnt(2)
	v_fmac_f32_e32 v56, v152, v112
	v_fmac_f32_e32 v57, v153, v113
	v_fmac_f32_e32 v58, v154, v114
	v_fmac_f32_e32 v59, v155, v115
	v_fma_f32 v56, -v156, v116, v56
	v_fma_f32 v57, -v157, v117, v57
	v_fma_f32 v58, -v158, v118, v58
	v_fma_f32 v59, -v159, v119, v59
	v_fmac_f32_e32 v60, v152, v116
	v_fmac_f32_e32 v61, v153, v117
	v_fmac_f32_e32 v62, v154, v118
	v_fmac_f32_e32 v63, v155, v119
	v_fmac_f32_e32 v60, v156, v112
	v_fmac_f32_e32 v61, v157, v113
	v_fmac_f32_e32 v62, v158, v114
	v_fmac_f32_e32 v63, v159, v115
	ds_read_b128 v[152:155], v9 offset:192
	ds_read_b128 v[156:159], v9 offset:448
	s_waitcnt lgkmcnt(2)
	v_fmac_f32_e32 v64, v144, v120
	v_fmac_f32_e32 v65, v145, v121
	v_fmac_f32_e32 v66, v146, v122
	v_fmac_f32_e32 v67, v147, v123
	v_fma_f32 v64, -v148, v124, v64
	v_fma_f32 v65, -v149, v125, v65
	v_fma_f32 v66, -v150, v126, v66
	v_fma_f32 v67, -v151, v127, v67
	v_fmac_f32_e32 v68, v144, v124
	v_fmac_f32_e32 v69, v145, v125
	v_fmac_f32_e32 v70, v146, v126
	v_fmac_f32_e32 v71, v147, v127
	v_fmac_f32_e32 v68, v148, v120
	v_fmac_f32_e32 v69, v149, v121
	v_fmac_f32_e32 v70, v150, v122
	v_fmac_f32_e32 v71, v151, v123
	s_waitcnt lgkmcnt(0)
	v_fmac_f32_e32 v72, v152, v128
	v_fmac_f32_e32 v73, v153, v129
	v_fmac_f32_e32 v74, v154, v130
	v_fmac_f32_e32 v75, v155, v131
	v_fma_f32 v72, -v156, v140, v72
	v_fma_f32 v73, -v157, v141, v73
	v_fma_f32 v74, -v158, v142, v74
	v_fma_f32 v75, -v159, v143, v75
	v_fmac_f32_e32 v76, v152, v140
	v_fmac_f32_e32 v77, v153, v141
	v_fmac_f32_e32 v78, v154, v142
	v_fmac_f32_e32 v79, v155, v143
	v_fmac_f32_e32 v76, v156, v128
	v_fmac_f32_e32 v77, v157, v129
	v_fmac_f32_e32 v78, v158, v130
	v_fmac_f32_e32 v79, v159, v131
	ds_read_b128 v[144:147], v9 offset:512
	ds_read_b128 v[148:151], v9 offset:768
	ds_read_b128 v[152:155], v9 offset:576
	ds_read_b128 v[156:159], v9 offset:832
	s_waitcnt lgkmcnt(2)
	v_mov_b32_e32 v168, v44
	v_mov_b32_e32 v169, v45
	v_mov_b32_e32 v170, v46
	v_mov_b32_e32 v171, v47
	s_nop 1
	v_fmac_f32_dpp v44, v44, v144 row_shl:1 row_mask:0xf bank_mask:0xf bound_ctrl:0
	v_fmac_f32_dpp v45, v45, v145 row_shl:1 row_mask:0xf bank_mask:0xf bound_ctrl:0
	v_fmac_f32_dpp v46, v46, v146 row_shl:1 row_mask:0xf bank_mask:0xf bound_ctrl:0
	v_fmac_f32_dpp v47, v47, v147 row_shl:1 row_mask:0xf bank_mask:0xf bound_ctrl:0
	v_fmac_f32_dpp v44, v52, -v148 row_shl:1 row_mask:0xf bank_mask:0xf bound_ctrl:0
	v_fmac_f32_dpp v45, v53, -v149 row_shl:1 row_mask:0xf bank_mask:0xf bound_ctrl:0
	v_fmac_f32_dpp v46, v54, -v150 row_shl:1 row_mask:0xf bank_mask:0xf bound_ctrl:0
	v_fmac_f32_dpp v47, v55, -v151 row_shl:1 row_mask:0xf bank_mask:0xf bound_ctrl:0
	v_fmac_f32_dpp v52, v52, v144 row_shl:1 row_mask:0xf bank_mask:0xf bound_ctrl:0
	v_fmac_f32_dpp v53, v53, v145 row_shl:1 row_mask:0xf bank_mask:0xf bound_ctrl:0
	v_fmac_f32_dpp v54, v54, v146 row_shl:1 row_mask:0xf bank_mask:0xf bound_ctrl:0
	v_fmac_f32_dpp v55, v55, v147 row_shl:1 row_mask:0xf bank_mask:0xf bound_ctrl:0
	v_fmac_f32_dpp v52, v168, v148 row_shl:1 row_mask:0xf bank_mask:0xf bound_ctrl:0
	v_fmac_f32_dpp v53, v169, v149 row_shl:1 row_mask:0xf bank_mask:0xf bound_ctrl:0
	v_fmac_f32_dpp v54, v170, v150 row_shl:1 row_mask:0xf bank_mask:0xf bound_ctrl:0
	v_fmac_f32_dpp v55, v171, v151 row_shl:1 row_mask:0xf bank_mask:0xf bound_ctrl:0
	ds_read_b128 v[144:147], v9 offset:640
	ds_read_b128 v[148:151], v9 offset:896
	s_waitcnt lgkmcnt(2)
	v_mov_b32_e32 v168, v56
	v_mov_b32_e32 v169, v57
	v_mov_b32_e32 v170, v58
	v_mov_b32_e32 v171, v59
	v_fmac_f32_dpp v56, v56, v152 row_shl:1 row_mask:0xf bank_mask:0xf bound_ctrl:0
	v_fmac_f32_dpp v57, v57, v153 row_shl:1 row_mask:0xf bank_mask:0xf bound_ctrl:0
	v_fmac_f32_dpp v58, v58, v154 row_shl:1 row_mask:0xf bank_mask:0xf bound_ctrl:0
	v_fmac_f32_dpp v59, v59, v155 row_shl:1 row_mask:0xf bank_mask:0xf bound_ctrl:0
	v_fmac_f32_dpp v56, v60, -v156 row_shl:1 row_mask:0xf bank_mask:0xf bound_ctrl:0
	v_fmac_f32_dpp v57, v61, -v157 row_shl:1 row_mask:0xf bank_mask:0xf bound_ctrl:0
	v_fmac_f32_dpp v58, v62, -v158 row_shl:1 row_mask:0xf bank_mask:0xf bound_ctrl:0
	v_fmac_f32_dpp v59, v63, -v159 row_shl:1 row_mask:0xf bank_mask:0xf bound_ctrl:0
	v_fmac_f32_dpp v60, v60, v152 row_shl:1 row_mask:0xf bank_mask:0xf bound_ctrl:0
	v_fmac_f32_dpp v61, v61, v153 row_shl:1 row_mask:0xf bank_mask:0xf bound_ctrl:0
	v_fmac_f32_dpp v62, v62, v154 row_shl:1 row_mask:0xf bank_mask:0xf bound_ctrl:0
	v_fmac_f32_dpp v63, v63, v155 row_shl:1 row_mask:0xf bank_mask:0xf bound_ctrl:0
	v_fmac_f32_dpp v60, v168, v156 row_shl:1 row_mask:0xf bank_mask:0xf bound_ctrl:0
	v_fmac_f32_dpp v61, v169, v157 row_shl:1 row_mask:0xf bank_mask:0xf bound_ctrl:0
	v_fmac_f32_dpp v62, v170, v158 row_shl:1 row_mask:0xf bank_mask:0xf bound_ctrl:0
	v_fmac_f32_dpp v63, v171, v159 row_shl:1 row_mask:0xf bank_mask:0xf bound_ctrl:0
	ds_read_b128 v[152:155], v9 offset:704
	ds_read_b128 v[156:159], v9 offset:960
	s_waitcnt lgkmcnt(2)
	v_mov_b32_e32 v168, v64
	v_mov_b32_e32 v169, v65
	v_mov_b32_e32 v170, v66
	v_mov_b32_e32 v171, v67
	v_fmac_f32_dpp v64, v64, v144 row_shl:1 row_mask:0xf bank_mask:0xf bound_ctrl:0
	v_fmac_f32_dpp v65, v65, v145 row_shl:1 row_mask:0xf bank_mask:0xf bound_ctrl:0
	v_fmac_f32_dpp v66, v66, v146 row_shl:1 row_mask:0xf bank_mask:0xf bound_ctrl:0
	v_fmac_f32_dpp v67, v67, v147 row_shl:1 row_mask:0xf bank_mask:0xf bound_ctrl:0
	v_fmac_f32_dpp v64, v68, -v148 row_shl:1 row_mask:0xf bank_mask:0xf bound_ctrl:0
	v_fmac_f32_dpp v65, v69, -v149 row_shl:1 row_mask:0xf bank_mask:0xf bound_ctrl:0
	v_fmac_f32_dpp v66, v70, -v150 row_shl:1 row_mask:0xf bank_mask:0xf bound_ctrl:0
	v_fmac_f32_dpp v67, v71, -v151 row_shl:1 row_mask:0xf bank_mask:0xf bound_ctrl:0
	v_fmac_f32_dpp v68, v68, v144 row_shl:1 row_mask:0xf bank_mask:0xf bound_ctrl:0
	v_fmac_f32_dpp v69, v69, v145 row_shl:1 row_mask:0xf bank_mask:0xf bound_ctrl:0
	v_fmac_f32_dpp v70, v70, v146 row_shl:1 row_mask:0xf bank_mask:0xf bound_ctrl:0
	v_fmac_f32_dpp v71, v71, v147 row_shl:1 row_mask:0xf bank_mask:0xf bound_ctrl:0
	v_fmac_f32_dpp v68, v168, v148 row_shl:1 row_mask:0xf bank_mask:0xf bound_ctrl:0
	v_fmac_f32_dpp v69, v169, v149 row_shl:1 row_mask:0xf bank_mask:0xf bound_ctrl:0
	v_fmac_f32_dpp v70, v170, v150 row_shl:1 row_mask:0xf bank_mask:0xf bound_ctrl:0
	v_fmac_f32_dpp v71, v171, v151 row_shl:1 row_mask:0xf bank_mask:0xf bound_ctrl:0
	ds_read_b128 v[144:147], v9 offset:1024
	ds_read_b128 v[148:151], v9 offset:1280
	s_waitcnt lgkmcnt(2)
	v_mov_b32_e32 v168, v72
	v_mov_b32_e32 v169, v73
	v_mov_b32_e32 v170, v74
	v_mov_b32_e32 v171, v75
	v_fmac_f32_dpp v72, v72, v152 row_shl:1 row_mask:0xf bank_mask:0xf bound_ctrl:0
	v_fmac_f32_dpp v73, v73, v153 row_shl:1 row_mask:0xf bank_mask:0xf bound_ctrl:0
	v_fmac_f32_dpp v74, v74, v154 row_shl:1 row_mask:0xf bank_mask:0xf bound_ctrl:0
	v_fmac_f32_dpp v75, v75, v155 row_shl:1 row_mask:0xf bank_mask:0xf bound_ctrl:0
	v_fmac_f32_dpp v72, v76, -v156 row_shl:1 row_mask:0xf bank_mask:0xf bound_ctrl:0
	v_fmac_f32_dpp v73, v77, -v157 row_shl:1 row_mask:0xf bank_mask:0xf bound_ctrl:0
	v_fmac_f32_dpp v74, v78, -v158 row_shl:1 row_mask:0xf bank_mask:0xf bound_ctrl:0
	v_fmac_f32_dpp v75, v79, -v159 row_shl:1 row_mask:0xf bank_mask:0xf bound_ctrl:0
	v_fmac_f32_dpp v76, v76, v152 row_shl:1 row_mask:0xf bank_mask:0xf bound_ctrl:0
	v_fmac_f32_dpp v77, v77, v153 row_shl:1 row_mask:0xf bank_mask:0xf bound_ctrl:0
	v_fmac_f32_dpp v78, v78, v154 row_shl:1 row_mask:0xf bank_mask:0xf bound_ctrl:0
	v_fmac_f32_dpp v79, v79, v155 row_shl:1 row_mask:0xf bank_mask:0xf bound_ctrl:0
	v_fmac_f32_dpp v76, v168, v156 row_shl:1 row_mask:0xf bank_mask:0xf bound_ctrl:0
	v_fmac_f32_dpp v77, v169, v157 row_shl:1 row_mask:0xf bank_mask:0xf bound_ctrl:0
	v_fmac_f32_dpp v78, v170, v158 row_shl:1 row_mask:0xf bank_mask:0xf bound_ctrl:0
	v_fmac_f32_dpp v79, v171, v159 row_shl:1 row_mask:0xf bank_mask:0xf bound_ctrl:0
	ds_read_b128 v[152:155], v9 offset:1088
	ds_read_b128 v[156:159], v9 offset:1344
	s_waitcnt lgkmcnt(2)
	v_mov_b32_e32 v168, v44
	v_mov_b32_e32 v169, v45
	v_mov_b32_e32 v170, v46
	v_mov_b32_e32 v171, v47
	v_fmac_f32_dpp v44, v44, v144 row_shl:2 row_mask:0xf bank_mask:0xf bound_ctrl:0
	v_fmac_f32_dpp v45, v45, v145 row_shl:2 row_mask:0xf bank_mask:0xf bound_ctrl:0
	v_fmac_f32_dpp v46, v46, v146 row_shl:2 row_mask:0xf bank_mask:0xf bound_ctrl:0
	v_fmac_f32_dpp v47, v47, v147 row_shl:2 row_mask:0xf bank_mask:0xf bound_ctrl:0
	v_fmac_f32_dpp v44, v52, -v148 row_shl:2 row_mask:0xf bank_mask:0xf bound_ctrl:0
	v_fmac_f32_dpp v45, v53, -v149 row_shl:2 row_mask:0xf bank_mask:0xf bound_ctrl:0
	v_fmac_f32_dpp v46, v54, -v150 row_shl:2 row_mask:0xf bank_mask:0xf bound_ctrl:0
	v_fmac_f32_dpp v47, v55, -v151 row_shl:2 row_mask:0xf bank_mask:0xf bound_ctrl:0
	v_fmac_f32_dpp v52, v52, v144 row_shl:2 row_mask:0xf bank_mask:0xf bound_ctrl:0
	v_fmac_f32_dpp v53, v53, v145 row_shl:2 row_mask:0xf bank_mask:0xf bound_ctrl:0
	v_fmac_f32_dpp v54, v54, v146 row_shl:2 row_mask:0xf bank_mask:0xf bound_ctrl:0
	v_fmac_f32_dpp v55, v55, v147 row_shl:2 row_mask:0xf bank_mask:0xf bound_ctrl:0
	v_fmac_f32_dpp v52, v168, v148 row_shl:2 row_mask:0xf bank_mask:0xf bound_ctrl:0
	v_fmac_f32_dpp v53, v169, v149 row_shl:2 row_mask:0xf bank_mask:0xf bound_ctrl:0
	v_fmac_f32_dpp v54, v170, v150 row_shl:2 row_mask:0xf bank_mask:0xf bound_ctrl:0
	v_fmac_f32_dpp v55, v171, v151 row_shl:2 row_mask:0xf bank_mask:0xf bound_ctrl:0
	ds_read_b128 v[144:147], v9 offset:1152
	ds_read_b128 v[148:151], v9 offset:1408
	s_waitcnt lgkmcnt(2)
	v_mov_b32_e32 v168, v56
	v_mov_b32_e32 v169, v57
	v_mov_b32_e32 v170, v58
	v_mov_b32_e32 v171, v59
	v_fmac_f32_dpp v56, v56, v152 row_shl:2 row_mask:0xf bank_mask:0xf bound_ctrl:0
	v_fmac_f32_dpp v57, v57, v153 row_shl:2 row_mask:0xf bank_mask:0xf bound_ctrl:0
	v_fmac_f32_dpp v58, v58, v154 row_shl:2 row_mask:0xf bank_mask:0xf bound_ctrl:0
	v_fmac_f32_dpp v59, v59, v155 row_shl:2 row_mask:0xf bank_mask:0xf bound_ctrl:0
	v_fmac_f32_dpp v56, v60, -v156 row_shl:2 row_mask:0xf bank_mask:0xf bound_ctrl:0
	v_fmac_f32_dpp v57, v61, -v157 row_shl:2 row_mask:0xf bank_mask:0xf bound_ctrl:0
	v_fmac_f32_dpp v58, v62, -v158 row_shl:2 row_mask:0xf bank_mask:0xf bound_ctrl:0
	v_fmac_f32_dpp v59, v63, -v159 row_shl:2 row_mask:0xf bank_mask:0xf bound_ctrl:0
	v_fmac_f32_dpp v60, v60, v152 row_shl:2 row_mask:0xf bank_mask:0xf bound_ctrl:0
	v_fmac_f32_dpp v61, v61, v153 row_shl:2 row_mask:0xf bank_mask:0xf bound_ctrl:0
	v_fmac_f32_dpp v62, v62, v154 row_shl:2 row_mask:0xf bank_mask:0xf bound_ctrl:0
	v_fmac_f32_dpp v63, v63, v155 row_shl:2 row_mask:0xf bank_mask:0xf bound_ctrl:0
	v_fmac_f32_dpp v60, v168, v156 row_shl:2 row_mask:0xf bank_mask:0xf bound_ctrl:0
	v_fmac_f32_dpp v61, v169, v157 row_shl:2 row_mask:0xf bank_mask:0xf bound_ctrl:0
	v_fmac_f32_dpp v62, v170, v158 row_shl:2 row_mask:0xf bank_mask:0xf bound_ctrl:0
	v_fmac_f32_dpp v63, v171, v159 row_shl:2 row_mask:0xf bank_mask:0xf bound_ctrl:0
	ds_read_b128 v[152:155], v9 offset:1216
	ds_read_b128 v[156:159], v9 offset:1472
	s_waitcnt lgkmcnt(2)
	v_mov_b32_e32 v168, v64
	v_mov_b32_e32 v169, v65
	v_mov_b32_e32 v170, v66
	v_mov_b32_e32 v171, v67
	v_fmac_f32_dpp v64, v64, v144 row_shl:2 row_mask:0xf bank_mask:0xf bound_ctrl:0
	v_fmac_f32_dpp v65, v65, v145 row_shl:2 row_mask:0xf bank_mask:0xf bound_ctrl:0
	v_fmac_f32_dpp v66, v66, v146 row_shl:2 row_mask:0xf bank_mask:0xf bound_ctrl:0
	v_fmac_f32_dpp v67, v67, v147 row_shl:2 row_mask:0xf bank_mask:0xf bound_ctrl:0
	v_fmac_f32_dpp v64, v68, -v148 row_shl:2 row_mask:0xf bank_mask:0xf bound_ctrl:0
	v_fmac_f32_dpp v65, v69, -v149 row_shl:2 row_mask:0xf bank_mask:0xf bound_ctrl:0
	v_fmac_f32_dpp v66, v70, -v150 row_shl:2 row_mask:0xf bank_mask:0xf bound_ctrl:0
	v_fmac_f32_dpp v67, v71, -v151 row_shl:2 row_mask:0xf bank_mask:0xf bound_ctrl:0
	v_fmac_f32_dpp v68, v68, v144 row_shl:2 row_mask:0xf bank_mask:0xf bound_ctrl:0
	v_fmac_f32_dpp v69, v69, v145 row_shl:2 row_mask:0xf bank_mask:0xf bound_ctrl:0
	v_fmac_f32_dpp v70, v70, v146 row_shl:2 row_mask:0xf bank_mask:0xf bound_ctrl:0
	v_fmac_f32_dpp v71, v71, v147 row_shl:2 row_mask:0xf bank_mask:0xf bound_ctrl:0
	v_fmac_f32_dpp v68, v168, v148 row_shl:2 row_mask:0xf bank_mask:0xf bound_ctrl:0
	v_fmac_f32_dpp v69, v169, v149 row_shl:2 row_mask:0xf bank_mask:0xf bound_ctrl:0
	v_fmac_f32_dpp v70, v170, v150 row_shl:2 row_mask:0xf bank_mask:0xf bound_ctrl:0
	v_fmac_f32_dpp v71, v171, v151 row_shl:2 row_mask:0xf bank_mask:0xf bound_ctrl:0
	ds_read_b128 v[144:147], v9 offset:1536
	ds_read_b128 v[148:151], v9 offset:1792
	s_waitcnt lgkmcnt(2)
	v_mov_b32_e32 v168, v72
	v_mov_b32_e32 v169, v73
	v_mov_b32_e32 v170, v74
	v_mov_b32_e32 v171, v75
	v_fmac_f32_dpp v72, v72, v152 row_shl:2 row_mask:0xf bank_mask:0xf bound_ctrl:0
	v_fmac_f32_dpp v73, v73, v153 row_shl:2 row_mask:0xf bank_mask:0xf bound_ctrl:0
	v_fmac_f32_dpp v74, v74, v154 row_shl:2 row_mask:0xf bank_mask:0xf bound_ctrl:0
	v_fmac_f32_dpp v75, v75, v155 row_shl:2 row_mask:0xf bank_mask:0xf bound_ctrl:0
	v_fmac_f32_dpp v72, v76, -v156 row_shl:2 row_mask:0xf bank_mask:0xf bound_ctrl:0
	v_fmac_f32_dpp v73, v77, -v157 row_shl:2 row_mask:0xf bank_mask:0xf bound_ctrl:0
	v_fmac_f32_dpp v74, v78, -v158 row_shl:2 row_mask:0xf bank_mask:0xf bound_ctrl:0
	v_fmac_f32_dpp v75, v79, -v159 row_shl:2 row_mask:0xf bank_mask:0xf bound_ctrl:0
	v_fmac_f32_dpp v76, v76, v152 row_shl:2 row_mask:0xf bank_mask:0xf bound_ctrl:0
	v_fmac_f32_dpp v77, v77, v153 row_shl:2 row_mask:0xf bank_mask:0xf bound_ctrl:0
	v_fmac_f32_dpp v78, v78, v154 row_shl:2 row_mask:0xf bank_mask:0xf bound_ctrl:0
	v_fmac_f32_dpp v79, v79, v155 row_shl:2 row_mask:0xf bank_mask:0xf bound_ctrl:0
	v_fmac_f32_dpp v76, v168, v156 row_shl:2 row_mask:0xf bank_mask:0xf bound_ctrl:0
	v_fmac_f32_dpp v77, v169, v157 row_shl:2 row_mask:0xf bank_mask:0xf bound_ctrl:0
	v_fmac_f32_dpp v78, v170, v158 row_shl:2 row_mask:0xf bank_mask:0xf bound_ctrl:0
	v_fmac_f32_dpp v79, v171, v159 row_shl:2 row_mask:0xf bank_mask:0xf bound_ctrl:0
	ds_read_b128 v[152:155], v9 offset:1600
	ds_read_b128 v[156:159], v9 offset:1856
	s_waitcnt lgkmcnt(2)
	v_mov_b32_e32 v168, v44
	v_mov_b32_e32 v169, v45
	v_mov_b32_e32 v170, v46
	v_mov_b32_e32 v171, v47
	v_fmac_f32_dpp v44, v44, v144 row_shl:4 row_mask:0xf bank_mask:0xf bound_ctrl:0
	v_fmac_f32_dpp v45, v45, v145 row_shl:4 row_mask:0xf bank_mask:0xf bound_ctrl:0
	v_fmac_f32_dpp v46, v46, v146 row_shl:4 row_mask:0xf bank_mask:0xf bound_ctrl:0
	v_fmac_f32_dpp v47, v47, v147 row_shl:4 row_mask:0xf bank_mask:0xf bound_ctrl:0
	v_fmac_f32_dpp v44, v52, -v148 row_shl:4 row_mask:0xf bank_mask:0xf bound_ctrl:0
	v_fmac_f32_dpp v45, v53, -v149 row_shl:4 row_mask:0xf bank_mask:0xf bound_ctrl:0
	v_fmac_f32_dpp v46, v54, -v150 row_shl:4 row_mask:0xf bank_mask:0xf bound_ctrl:0
	v_fmac_f32_dpp v47, v55, -v151 row_shl:4 row_mask:0xf bank_mask:0xf bound_ctrl:0
	v_fmac_f32_dpp v52, v52, v144 row_shl:4 row_mask:0xf bank_mask:0xf bound_ctrl:0
	v_fmac_f32_dpp v53, v53, v145 row_shl:4 row_mask:0xf bank_mask:0xf bound_ctrl:0
	v_fmac_f32_dpp v54, v54, v146 row_shl:4 row_mask:0xf bank_mask:0xf bound_ctrl:0
	v_fmac_f32_dpp v55, v55, v147 row_shl:4 row_mask:0xf bank_mask:0xf bound_ctrl:0
	v_fmac_f32_dpp v52, v168, v148 row_shl:4 row_mask:0xf bank_mask:0xf bound_ctrl:0
	v_fmac_f32_dpp v53, v169, v149 row_shl:4 row_mask:0xf bank_mask:0xf bound_ctrl:0
	v_fmac_f32_dpp v54, v170, v150 row_shl:4 row_mask:0xf bank_mask:0xf bound_ctrl:0
	v_fmac_f32_dpp v55, v171, v151 row_shl:4 row_mask:0xf bank_mask:0xf bound_ctrl:0
	ds_read_b128 v[144:147], v9 offset:1664
	ds_read_b128 v[148:151], v9 offset:1920
	s_waitcnt lgkmcnt(2)
	v_mov_b32_e32 v168, v56
	v_mov_b32_e32 v169, v57
	v_mov_b32_e32 v170, v58
	v_mov_b32_e32 v171, v59
	v_fmac_f32_dpp v56, v56, v152 row_shl:4 row_mask:0xf bank_mask:0xf bound_ctrl:0
	v_fmac_f32_dpp v57, v57, v153 row_shl:4 row_mask:0xf bank_mask:0xf bound_ctrl:0
	v_fmac_f32_dpp v58, v58, v154 row_shl:4 row_mask:0xf bank_mask:0xf bound_ctrl:0
	v_fmac_f32_dpp v59, v59, v155 row_shl:4 row_mask:0xf bank_mask:0xf bound_ctrl:0
	v_fmac_f32_dpp v56, v60, -v156 row_shl:4 row_mask:0xf bank_mask:0xf bound_ctrl:0
	v_fmac_f32_dpp v57, v61, -v157 row_shl:4 row_mask:0xf bank_mask:0xf bound_ctrl:0
	v_fmac_f32_dpp v58, v62, -v158 row_shl:4 row_mask:0xf bank_mask:0xf bound_ctrl:0
	v_fmac_f32_dpp v59, v63, -v159 row_shl:4 row_mask:0xf bank_mask:0xf bound_ctrl:0
	v_fmac_f32_dpp v60, v60, v152 row_shl:4 row_mask:0xf bank_mask:0xf bound_ctrl:0
	v_fmac_f32_dpp v61, v61, v153 row_shl:4 row_mask:0xf bank_mask:0xf bound_ctrl:0
	v_fmac_f32_dpp v62, v62, v154 row_shl:4 row_mask:0xf bank_mask:0xf bound_ctrl:0
	v_fmac_f32_dpp v63, v63, v155 row_shl:4 row_mask:0xf bank_mask:0xf bound_ctrl:0
	v_fmac_f32_dpp v60, v168, v156 row_shl:4 row_mask:0xf bank_mask:0xf bound_ctrl:0
	v_fmac_f32_dpp v61, v169, v157 row_shl:4 row_mask:0xf bank_mask:0xf bound_ctrl:0
	v_fmac_f32_dpp v62, v170, v158 row_shl:4 row_mask:0xf bank_mask:0xf bound_ctrl:0
	v_fmac_f32_dpp v63, v171, v159 row_shl:4 row_mask:0xf bank_mask:0xf bound_ctrl:0
	ds_read_b128 v[152:155], v9 offset:1728
	ds_read_b128 v[156:159], v9 offset:1984
	s_waitcnt lgkmcnt(2)
	v_mov_b32_e32 v168, v64
	v_mov_b32_e32 v169, v65
	v_mov_b32_e32 v170, v66
	v_mov_b32_e32 v171, v67
	v_fmac_f32_dpp v64, v64, v144 row_shl:4 row_mask:0xf bank_mask:0xf bound_ctrl:0
	v_fmac_f32_dpp v65, v65, v145 row_shl:4 row_mask:0xf bank_mask:0xf bound_ctrl:0
	v_fmac_f32_dpp v66, v66, v146 row_shl:4 row_mask:0xf bank_mask:0xf bound_ctrl:0
	v_fmac_f32_dpp v67, v67, v147 row_shl:4 row_mask:0xf bank_mask:0xf bound_ctrl:0
	v_fmac_f32_dpp v64, v68, -v148 row_shl:4 row_mask:0xf bank_mask:0xf bound_ctrl:0
	v_fmac_f32_dpp v65, v69, -v149 row_shl:4 row_mask:0xf bank_mask:0xf bound_ctrl:0
	v_fmac_f32_dpp v66, v70, -v150 row_shl:4 row_mask:0xf bank_mask:0xf bound_ctrl:0
	v_fmac_f32_dpp v67, v71, -v151 row_shl:4 row_mask:0xf bank_mask:0xf bound_ctrl:0
	v_fmac_f32_dpp v68, v68, v144 row_shl:4 row_mask:0xf bank_mask:0xf bound_ctrl:0
	v_fmac_f32_dpp v69, v69, v145 row_shl:4 row_mask:0xf bank_mask:0xf bound_ctrl:0
	v_fmac_f32_dpp v70, v70, v146 row_shl:4 row_mask:0xf bank_mask:0xf bound_ctrl:0
	v_fmac_f32_dpp v71, v71, v147 row_shl:4 row_mask:0xf bank_mask:0xf bound_ctrl:0
	v_fmac_f32_dpp v68, v168, v148 row_shl:4 row_mask:0xf bank_mask:0xf bound_ctrl:0
	v_fmac_f32_dpp v69, v169, v149 row_shl:4 row_mask:0xf bank_mask:0xf bound_ctrl:0
	v_fmac_f32_dpp v70, v170, v150 row_shl:4 row_mask:0xf bank_mask:0xf bound_ctrl:0
	v_fmac_f32_dpp v71, v171, v151 row_shl:4 row_mask:0xf bank_mask:0xf bound_ctrl:0
	ds_read_b128 v[144:147], v9 offset:2048
	ds_read_b128 v[148:151], v9 offset:2304
	s_waitcnt lgkmcnt(2)
	v_mov_b32_e32 v168, v72
	v_mov_b32_e32 v169, v73
	v_mov_b32_e32 v170, v74
	v_mov_b32_e32 v171, v75
	v_fmac_f32_dpp v72, v72, v152 row_shl:4 row_mask:0xf bank_mask:0xf bound_ctrl:0
	v_fmac_f32_dpp v73, v73, v153 row_shl:4 row_mask:0xf bank_mask:0xf bound_ctrl:0
	v_fmac_f32_dpp v74, v74, v154 row_shl:4 row_mask:0xf bank_mask:0xf bound_ctrl:0
	v_fmac_f32_dpp v75, v75, v155 row_shl:4 row_mask:0xf bank_mask:0xf bound_ctrl:0
	v_fmac_f32_dpp v72, v76, -v156 row_shl:4 row_mask:0xf bank_mask:0xf bound_ctrl:0
	v_fmac_f32_dpp v73, v77, -v157 row_shl:4 row_mask:0xf bank_mask:0xf bound_ctrl:0
	v_fmac_f32_dpp v74, v78, -v158 row_shl:4 row_mask:0xf bank_mask:0xf bound_ctrl:0
	v_fmac_f32_dpp v75, v79, -v159 row_shl:4 row_mask:0xf bank_mask:0xf bound_ctrl:0
	v_fmac_f32_dpp v76, v76, v152 row_shl:4 row_mask:0xf bank_mask:0xf bound_ctrl:0
	v_fmac_f32_dpp v77, v77, v153 row_shl:4 row_mask:0xf bank_mask:0xf bound_ctrl:0
	v_fmac_f32_dpp v78, v78, v154 row_shl:4 row_mask:0xf bank_mask:0xf bound_ctrl:0
	v_fmac_f32_dpp v79, v79, v155 row_shl:4 row_mask:0xf bank_mask:0xf bound_ctrl:0
	v_fmac_f32_dpp v76, v168, v156 row_shl:4 row_mask:0xf bank_mask:0xf bound_ctrl:0
	v_fmac_f32_dpp v77, v169, v157 row_shl:4 row_mask:0xf bank_mask:0xf bound_ctrl:0
	v_fmac_f32_dpp v78, v170, v158 row_shl:4 row_mask:0xf bank_mask:0xf bound_ctrl:0
	v_fmac_f32_dpp v79, v171, v159 row_shl:4 row_mask:0xf bank_mask:0xf bound_ctrl:0
	ds_read_b128 v[152:155], v9 offset:2112
	ds_read_b128 v[156:159], v9 offset:2368
	s_waitcnt lgkmcnt(2)
	v_mov_b32_e32 v168, v44
	v_mov_b32_e32 v169, v45
	v_mov_b32_e32 v170, v46
	v_mov_b32_e32 v171, v47
	v_fmac_f32_dpp v44, v44, v144 row_shl:8 row_mask:0xf bank_mask:0xf bound_ctrl:0
	v_fmac_f32_dpp v45, v45, v145 row_shl:8 row_mask:0xf bank_mask:0xf bound_ctrl:0
	v_fmac_f32_dpp v46, v46, v146 row_shl:8 row_mask:0xf bank_mask:0xf bound_ctrl:0
	v_fmac_f32_dpp v47, v47, v147 row_shl:8 row_mask:0xf bank_mask:0xf bound_ctrl:0
	v_fmac_f32_dpp v44, v52, -v148 row_shl:8 row_mask:0xf bank_mask:0xf bound_ctrl:0
	v_fmac_f32_dpp v45, v53, -v149 row_shl:8 row_mask:0xf bank_mask:0xf bound_ctrl:0
	v_fmac_f32_dpp v46, v54, -v150 row_shl:8 row_mask:0xf bank_mask:0xf bound_ctrl:0
	v_fmac_f32_dpp v47, v55, -v151 row_shl:8 row_mask:0xf bank_mask:0xf bound_ctrl:0
	v_fmac_f32_dpp v52, v52, v144 row_shl:8 row_mask:0xf bank_mask:0xf bound_ctrl:0
	v_fmac_f32_dpp v53, v53, v145 row_shl:8 row_mask:0xf bank_mask:0xf bound_ctrl:0
	v_fmac_f32_dpp v54, v54, v146 row_shl:8 row_mask:0xf bank_mask:0xf bound_ctrl:0
	v_fmac_f32_dpp v55, v55, v147 row_shl:8 row_mask:0xf bank_mask:0xf bound_ctrl:0
	v_fmac_f32_dpp v52, v168, v148 row_shl:8 row_mask:0xf bank_mask:0xf bound_ctrl:0
	v_fmac_f32_dpp v53, v169, v149 row_shl:8 row_mask:0xf bank_mask:0xf bound_ctrl:0
	v_fmac_f32_dpp v54, v170, v150 row_shl:8 row_mask:0xf bank_mask:0xf bound_ctrl:0
	v_fmac_f32_dpp v55, v171, v151 row_shl:8 row_mask:0xf bank_mask:0xf bound_ctrl:0
	ds_read_b128 v[144:147], v9 offset:2176
	ds_read_b128 v[148:151], v9 offset:2432
	s_waitcnt lgkmcnt(2)
	v_mov_b32_e32 v168, v56
	v_mov_b32_e32 v169, v57
	v_mov_b32_e32 v170, v58
	v_mov_b32_e32 v171, v59
	v_fmac_f32_dpp v56, v56, v152 row_shl:8 row_mask:0xf bank_mask:0xf bound_ctrl:0
	v_fmac_f32_dpp v57, v57, v153 row_shl:8 row_mask:0xf bank_mask:0xf bound_ctrl:0
	v_fmac_f32_dpp v58, v58, v154 row_shl:8 row_mask:0xf bank_mask:0xf bound_ctrl:0
	v_fmac_f32_dpp v59, v59, v155 row_shl:8 row_mask:0xf bank_mask:0xf bound_ctrl:0
	v_fmac_f32_dpp v56, v60, -v156 row_shl:8 row_mask:0xf bank_mask:0xf bound_ctrl:0
	v_fmac_f32_dpp v57, v61, -v157 row_shl:8 row_mask:0xf bank_mask:0xf bound_ctrl:0
	v_fmac_f32_dpp v58, v62, -v158 row_shl:8 row_mask:0xf bank_mask:0xf bound_ctrl:0
	v_fmac_f32_dpp v59, v63, -v159 row_shl:8 row_mask:0xf bank_mask:0xf bound_ctrl:0
	v_fmac_f32_dpp v60, v60, v152 row_shl:8 row_mask:0xf bank_mask:0xf bound_ctrl:0
	v_fmac_f32_dpp v61, v61, v153 row_shl:8 row_mask:0xf bank_mask:0xf bound_ctrl:0
	v_fmac_f32_dpp v62, v62, v154 row_shl:8 row_mask:0xf bank_mask:0xf bound_ctrl:0
	v_fmac_f32_dpp v63, v63, v155 row_shl:8 row_mask:0xf bank_mask:0xf bound_ctrl:0
	v_fmac_f32_dpp v60, v168, v156 row_shl:8 row_mask:0xf bank_mask:0xf bound_ctrl:0
	v_fmac_f32_dpp v61, v169, v157 row_shl:8 row_mask:0xf bank_mask:0xf bound_ctrl:0
	v_fmac_f32_dpp v62, v170, v158 row_shl:8 row_mask:0xf bank_mask:0xf bound_ctrl:0
	v_fmac_f32_dpp v63, v171, v159 row_shl:8 row_mask:0xf bank_mask:0xf bound_ctrl:0
	ds_read_b128 v[152:155], v9 offset:2240
	ds_read_b128 v[156:159], v9 offset:2496
	s_waitcnt lgkmcnt(2)
	v_mov_b32_e32 v168, v64
	v_mov_b32_e32 v169, v65
	v_mov_b32_e32 v170, v66
	v_mov_b32_e32 v171, v67
	v_fmac_f32_dpp v64, v64, v144 row_shl:8 row_mask:0xf bank_mask:0xf bound_ctrl:0
	v_fmac_f32_dpp v65, v65, v145 row_shl:8 row_mask:0xf bank_mask:0xf bound_ctrl:0
	v_fmac_f32_dpp v66, v66, v146 row_shl:8 row_mask:0xf bank_mask:0xf bound_ctrl:0
	v_fmac_f32_dpp v67, v67, v147 row_shl:8 row_mask:0xf bank_mask:0xf bound_ctrl:0
	v_fmac_f32_dpp v64, v68, -v148 row_shl:8 row_mask:0xf bank_mask:0xf bound_ctrl:0
	v_fmac_f32_dpp v65, v69, -v149 row_shl:8 row_mask:0xf bank_mask:0xf bound_ctrl:0
	v_fmac_f32_dpp v66, v70, -v150 row_shl:8 row_mask:0xf bank_mask:0xf bound_ctrl:0
	v_fmac_f32_dpp v67, v71, -v151 row_shl:8 row_mask:0xf bank_mask:0xf bound_ctrl:0
	v_fmac_f32_dpp v68, v68, v144 row_shl:8 row_mask:0xf bank_mask:0xf bound_ctrl:0
	v_fmac_f32_dpp v69, v69, v145 row_shl:8 row_mask:0xf bank_mask:0xf bound_ctrl:0
	v_fmac_f32_dpp v70, v70, v146 row_shl:8 row_mask:0xf bank_mask:0xf bound_ctrl:0
	v_fmac_f32_dpp v71, v71, v147 row_shl:8 row_mask:0xf bank_mask:0xf bound_ctrl:0
	v_fmac_f32_dpp v68, v168, v148 row_shl:8 row_mask:0xf bank_mask:0xf bound_ctrl:0
	v_fmac_f32_dpp v69, v169, v149 row_shl:8 row_mask:0xf bank_mask:0xf bound_ctrl:0
	v_fmac_f32_dpp v70, v170, v150 row_shl:8 row_mask:0xf bank_mask:0xf bound_ctrl:0
	v_fmac_f32_dpp v71, v171, v151 row_shl:8 row_mask:0xf bank_mask:0xf bound_ctrl:0
	s_waitcnt lgkmcnt(0)
	v_mov_b32_e32 v168, v72
	v_mov_b32_e32 v169, v73
	v_mov_b32_e32 v170, v74
	v_mov_b32_e32 v171, v75
	v_fmac_f32_dpp v72, v72, v152 row_shl:8 row_mask:0xf bank_mask:0xf bound_ctrl:0
	v_fmac_f32_dpp v73, v73, v153 row_shl:8 row_mask:0xf bank_mask:0xf bound_ctrl:0
	v_fmac_f32_dpp v74, v74, v154 row_shl:8 row_mask:0xf bank_mask:0xf bound_ctrl:0
	v_fmac_f32_dpp v75, v75, v155 row_shl:8 row_mask:0xf bank_mask:0xf bound_ctrl:0
	v_fmac_f32_dpp v72, v76, -v156 row_shl:8 row_mask:0xf bank_mask:0xf bound_ctrl:0
	v_fmac_f32_dpp v73, v77, -v157 row_shl:8 row_mask:0xf bank_mask:0xf bound_ctrl:0
	v_fmac_f32_dpp v74, v78, -v158 row_shl:8 row_mask:0xf bank_mask:0xf bound_ctrl:0
	v_fmac_f32_dpp v75, v79, -v159 row_shl:8 row_mask:0xf bank_mask:0xf bound_ctrl:0
	v_fmac_f32_dpp v76, v76, v152 row_shl:8 row_mask:0xf bank_mask:0xf bound_ctrl:0
	v_fmac_f32_dpp v77, v77, v153 row_shl:8 row_mask:0xf bank_mask:0xf bound_ctrl:0
	v_fmac_f32_dpp v78, v78, v154 row_shl:8 row_mask:0xf bank_mask:0xf bound_ctrl:0
	v_fmac_f32_dpp v79, v79, v155 row_shl:8 row_mask:0xf bank_mask:0xf bound_ctrl:0
	v_fmac_f32_dpp v76, v168, v156 row_shl:8 row_mask:0xf bank_mask:0xf bound_ctrl:0
	v_fmac_f32_dpp v77, v169, v157 row_shl:8 row_mask:0xf bank_mask:0xf bound_ctrl:0
	v_fmac_f32_dpp v78, v170, v158 row_shl:8 row_mask:0xf bank_mask:0xf bound_ctrl:0
	v_fmac_f32_dpp v79, v171, v159 row_shl:8 row_mask:0xf bank_mask:0xf bound_ctrl:0
	s_nop 1
	s_mov_b64 exec, s[52:53]
	global_store_dword v10, v44, s[36:37] offset:0
	global_store_dword v10, v52, s[36:37] offset:4
	global_store_dword v10, v45, s[36:37] offset:8
	global_store_dword v10, v53, s[36:37] offset:12
	global_store_dword v10, v46, s[36:37] offset:16
	global_store_dword v10, v54, s[36:37] offset:20
	global_store_dword v10, v47, s[36:37] offset:24
	global_store_dword v10, v55, s[36:37] offset:28
	global_store_dword v10, v56, s[36:37] offset:128
	global_store_dword v10, v60, s[36:37] offset:132
	global_store_dword v10, v57, s[36:37] offset:136
	global_store_dword v10, v61, s[36:37] offset:140
	global_store_dword v10, v58, s[36:37] offset:144
	global_store_dword v10, v62, s[36:37] offset:148
	global_store_dword v10, v59, s[36:37] offset:152
	global_store_dword v10, v63, s[36:37] offset:156
	global_store_dword v10, v64, s[36:37] offset:256
	global_store_dword v10, v68, s[36:37] offset:260
	global_store_dword v10, v65, s[36:37] offset:264
	global_store_dword v10, v69, s[36:37] offset:268
	global_store_dword v10, v66, s[36:37] offset:272
	global_store_dword v10, v70, s[36:37] offset:276
	global_store_dword v10, v67, s[36:37] offset:280
	global_store_dword v10, v71, s[36:37] offset:284
	global_store_dword v10, v72, s[36:37] offset:384
	global_store_dword v10, v76, s[36:37] offset:388
	global_store_dword v10, v73, s[36:37] offset:392
	global_store_dword v10, v77, s[36:37] offset:396
	global_store_dword v10, v74, s[36:37] offset:400
	global_store_dword v10, v78, s[36:37] offset:404
	global_store_dword v10, v75, s[36:37] offset:408
	global_store_dword v10, v79, s[36:37] offset:412
	s_mov_b64 exec, -1
	s_branch .LBB0_618
